# v40: static priority: per-segment s_setprio flips deleted in all GEMM K-loops, one s_setprio 1 for waves 0-3 per unit, reset at grid barriers
# baseline (speedup 1.0000x reference)
; __device__ __forceinline__ unsigned xb_ld(unsigned* p)              { return __hip_atomic_load(p, __ATOMIC_RELAXED, __HIP_MEMORY_SCOPE_AGENT); }
; __device__ __forceinline__ unsigned xb_add(unsigned* p, unsigned v) { return __hip_atomic_fetch_add(p, v, __ATOMIC_RELAXED, __HIP_MEMORY_SCOPE_AGENT); }
; #define XB_SPIN(cond, bar) do { unsigned _sp = 0; while (cond) { __builtin_amdgcn_s_sleep(1); \
;     if ((++_sp & 255u) == 0u) { if (xb_ld(&(bar)[XB_TMO])) break; if (_sp > XB_SPIN_CAP) { atomicAdd(&(bar)[XB_TMO], 1u); break; } } } } while (0)
; __device__ __forceinline__ void xcd_barrier(const XcdBarrier& b) {
;     asm volatile("s_waitcnt vmcnt(0)" ::: "memory");
;     __syncthreads();
;     if (threadIdx.x == 0) {
;         unsigned* bar = b.bar;
;         __builtin_amdgcn_s_waitcnt(0);
;         unsigned nloc = b.st[0], nx = b.st[1];
;         if (nloc == 0u) { xcd_barrier_complete(bar, b.x, nloc, nx); b.st[0] = nloc; b.st[1] = nx; }
;         const unsigned old = xb_add(&bar[XB_XSUB(b.x)], 1u);
;         const unsigned gen = old / nloc;
;         if (old + 1u == (gen + 1u) * nloc) {
;             __builtin_amdgcn_fence(__ATOMIC_RELEASE, "agent");
;             asm volatile("s_waitcnt vmcnt(0)" ::: "memory");
;             const unsigned og = xb_add(&bar[XB_TOP], 1u);
;             const unsigned tg = og / nx;
;             if (og + 1u == (tg + 1u) * nx) xb_add(&bar[XB_TOPGEN], 1u);
;             else XB_SPIN(xb_ld(&bar[XB_TOPGEN]) == tg, bar);
;             __builtin_amdgcn_fence(__ATOMIC_ACQUIRE, "agent");
;             xb_add(&bar[XB_XGEN(b.x)], 1u);
;             asm volatile("s_waitcnt vmcnt(0)" ::: "memory");
;         } else {
;             XB_SPIN(xb_ld(&bar[XB_XGEN(b.x)]) == gen, bar);
;             __builtin_amdgcn_fence(__ATOMIC_ACQUIRE, "agent");
;             asm volatile("s_waitcnt vmcnt(0)" ::: "memory");
;         }
;     }
;     __syncthreads();
; }
.LBB0_262:
	s_cmp_gt_i32 s95, 1
	s_cselect_b64 s[0:1], -1, 0
	s_and_b64 s[4:5], s[4:5], s[0:1]
	s_andn2_b64 vcc, exec, s[4:5]
	s_cbranch_vccnz .LBB0_312
	s_setprio 0
	s_waitcnt vmcnt(0) lgkmcnt(0)
	s_barrier
	v_readfirstlane_b32 s98, v0
	s_cmp_lg_u32 s98, 0
	s_cbranch_scc1 .Lxb0_end
	s_mov_b64 s[100:101], exec
	v_readlane_b32 s98, v253, 0
	s_cmp_lg_u32 s98, 0
	s_cbranch_scc1 .Lxb0_have
	s_mov_b64 exec, 0xffff
	v_mbcnt_lo_u32_b32 v254, -1, 0
	v_lshlrev_b32_e32 v254, 8, v254
	s_mov_b32 s99, 0
	v_writelane_b32 v253, s99, 3
	s_branch .Lxb0_cgot

; #define PG8_STAGE(bufoff, gbase, voff) do { _Pragma("unroll") for (int _i = 0; _i < 2; ++_i) \
;         __builtin_amdgcn_global_load_lds((const unsigned*)((const char*)(gbase) + (voff)[_i]), (LAS unsigned*)(lds + (bufoff) + ldsw + _i * 8192), 16, 0, 0); } while (0)
; #define PG8_LDA(dst, b, h) do { _Pragma("unroll") for (int m = 0; m < 4; ++m) _Pragma("unroll") for (int k = 0; k < 2; ++k) dst[m][k] = *(const LAS bf16x8*)(lds + PG8_SA(b, h) + aoff + m * 2048 + k * 1024); } while (0)
; #define PG8_LDB(dst, b, h) do { _Pragma("unroll") for (int n = 0; n < 2; ++n) _Pragma("unroll") for (int k = 0; k < 2; ++k) dst[n][k] = *(const LAS bf16x8*)(lds + PG8_SB(b, h) + boff + n * 2048 + k * 1024); } while (0)
; #define PG8_SCHED __builtin_amdgcn_sched_barrier(0)
; template <class Epi>
; __device__ __forceinline__ void gemm_phase(LAS unsigned char* lds, const Gemm g, const Sched& S, const Epi& E) {
;     ...
;         const bool has_next = S.next(ui + 1, nxt);
;         const char* nA = has_next ? (const char*)g.A + (size_t)nxt.pm * tstepA + (size_t)nxt.part * g.koff * 2 : cA; const char* nB = has_next ? (const char*)g.Bt + (size_t)nxt.pn * tstepB + (size_t)nxt.part * g.koff * 2 : cB;
;         for (int t = 0; t < nt; t += 2) {
;             const bool last = (t == nt - 2);
;             const char* a1 = cA + (size_t)(t + 1) * kstep;
;             const char* a2 = last ? nA : cA + (size_t)(t + 2) * kstep; const char* b2 = last ? nB : cB + (size_t)(t + 2) * kstep;
;             const char* a3 = a2 + kstep; const char* b3 = b2 + kstep;
;             PG8_LDB(B0, 0, 0); PG8_LDB(B1, 0, 1); PG8_SCHED; PG8_LDA(At, 0, 0); PG8_STAGE(PG8_SA(1, 1), a1 + hstepA, voffA);
.LBB0_583:
	s_ashr_i32 s21, s20, 31
	s_lshl_b64 s[22:23], s[20:21], 19
	s_add_u32 s22, s88, s22
	s_addc_u32 s23, s89, s23
	s_and_b64 s[28:29], s[0:1], exec
	s_cselect_b32 s21, s23, s35
	s_cselect_b32 s82, s22, s34
	s_ashr_i32 s19, s18, 31
	s_lshl_b64 s[28:29], s[18:19], 19
	s_add_u32 s28, s50, s28
	s_addc_u32 s29, s51, s29
	s_and_b64 s[40:41], s[0:1], exec
	s_cselect_b32 s19, s29, s39
	s_cselect_b32 s83, s28, s38
	s_add_u32 s34, s34, 0x40080
	s_addc_u32 s35, s35, 0
	s_add_u32 s84, s38, 0x100
	s_addc_u32 s85, s39, 0
	s_mov_b32 s86, -2
	v_readfirstlane_b32 s100, v0
	s_lshr_b32 s100, s100, 8
	s_cmp_eq_u32 s100, 0
	s_cbranch_scc0 .Lprio_0
	s_setprio 1
.Lprio_0:
.LBB0_584:
	ds_read_b128 v[156:159], v153
	ds_read_b128 v[160:163], v153 offset:1024
	ds_read_b128 v[164:167], v153 offset:2048
	ds_read_b128 v[168:171], v153 offset:3072
	ds_read_b128 v[172:175], v154
	ds_read_b128 v[176:179], v154 offset:1024
	ds_read_b128 v[180:183], v154 offset:2048
	ds_read_b128 v[184:187], v154 offset:3072
	s_add_u32 s38, s34, 0xfffc0080
	s_addc_u32 s39, s35, -1
	s_cmp_eq_u32 s86, 12
	s_cselect_b32 s41, s21, s39
	s_cselect_b32 s40, s82, s38
	s_cselect_b32 s39, s19, s85
	s_cselect_b32 s38, s83, s84
	v_lshl_add_u64 v[196:197], s[34:35], 0, v[138:139]
	s_add_i32 m0, s25, 0xc000
	ds_read_b128 v[188:191], v155
	ds_read_b128 v[192:195], v155 offset:1024
	ds_read_b128 v[200:203], v155 offset:2048
	ds_read_b128 v[204:207], v155 offset:3072
	ds_read_b128 v[208:211], v155 offset:4096
	ds_read_b128 v[212:215], v155 offset:5120
	ds_read_b128 v[216:219], v155 offset:6144
	ds_read_b128 v[220:223], v155 offset:7168
	s_cmp_lg_u32 s98, 0
	s_cbranch_scc1 .Lpi_p1_s
	global_load_lds_dwordx4 v[196:197], off
	v_lshl_add_u64 v[196:197], s[34:35], 0, v[140:141]
	s_add_i32 m0, s25, 0xe000
	s_nop 0
	global_load_lds_dwordx4 v[196:197], off

; #define PG8_STAGE(bufoff, gbase, voff) do { _Pragma("unroll") for (int _i = 0; _i < 2; ++_i) \
;         __builtin_amdgcn_global_load_lds((const unsigned*)((const char*)(gbase) + (voff)[_i]), (LAS unsigned*)(lds + (bufoff) + ldsw + _i * 8192), 16, 0, 0); } while (0)
; #define PG8_LDA(dst, b, h) do { _Pragma("unroll") for (int m = 0; m < 4; ++m) _Pragma("unroll") for (int k = 0; k < 2; ++k) dst[m][k] = *(const LAS bf16x8*)(lds + PG8_SA(b, h) + aoff + m * 2048 + k * 1024); } while (0)
; #define PG8_LDB(dst, b, h) do { _Pragma("unroll") for (int n = 0; n < 2; ++n) _Pragma("unroll") for (int k = 0; k < 2; ++k) dst[n][k] = *(const LAS bf16x8*)(lds + PG8_SB(b, h) + boff + n * 2048 + k * 1024); } while (0)
; #define PG8_MMA(ai, bj, At, Bt) do { __builtin_amdgcn_s_setprio(1); _Pragma("unroll") for (int m = 0; m < 4; ++m) _Pragma("unroll") for (int n = 0; n < 2; ++n) _Pragma("unroll") for (int k = 0; k < 2; ++k) \
;         acc[ai][bj][m][n] = __builtin_amdgcn_mfma_f32_16x16x32_bf16(Bt[n][k], At[m][k], acc[ai][bj][m][n], 0, 0, 0); __builtin_amdgcn_s_setprio(0); } while (0)
; #define PG8_WAIT_V(n) asm volatile("s_waitcnt vmcnt(" #n ")" ::: "memory")
; #define PG8_WAIT_L(n) asm volatile("s_waitcnt lgkmcnt(" #n ")" ::: "memory")
; #define PG8_BAR __builtin_amdgcn_s_barrier()
; #define PG8_SCHED __builtin_amdgcn_sched_barrier(0)
; template <class Epi>
; __device__ __forceinline__ void gemm_phase(LAS unsigned char* lds, const Gemm g, const Sched& S, const Epi& E) {
;     ...
;             PG8_LDB(B0, 0, 0); PG8_LDB(B1, 0, 1); PG8_SCHED; PG8_LDA(At, 0, 0); PG8_STAGE(PG8_SA(1, 1), a1 + hstepA, voffA);
;             PG8_WAIT_V(8); PG8_WAIT_L(0); PG8_BAR; PG8_MMA(0, 0, At, B0); PG8_MMA(0, 1, At, B1); PG8_BAR; PG8_SCHED;
;             PG8_LDA(At, 0, 1); PG8_STAGE(PG8_SB(0, 0), b2, voffB); PG8_STAGE(PG8_SB(0, 1), b2 + hstepB, voffB); PG8_STAGE(PG8_SA(0, 0), a2, voffA);
.Lrx_p1_0_j:
	s_waitcnt lgkmcnt(0)
	s_cmp_eq_u32 s86, -2
	s_cbranch_scc1 .Lcz_p1_0
	s_barrier
	s_waitcnt lgkmcnt(0)
	v_mfma_f32_16x16x32_bf16 v[126:129], v[156:159], v[188:191], v[126:129]
	v_mfma_f32_16x16x32_bf16 v[122:125], v[164:167], v[188:191], v[122:125]
	v_mfma_f32_16x16x32_bf16 v[110:113], v[156:159], v[200:203], v[110:113]
	v_mfma_f32_16x16x32_bf16 v[106:109], v[164:167], v[200:203], v[106:109]
	v_mfma_f32_16x16x32_bf16 v[94:97], v[156:159], v[208:211], v[94:97]
	v_mfma_f32_16x16x32_bf16 v[90:93], v[164:167], v[208:211], v[90:93]
	v_mfma_f32_16x16x32_bf16 v[78:81], v[156:159], v[216:219], v[78:81]
	v_mfma_f32_16x16x32_bf16 v[74:77], v[164:167], v[216:219], v[74:77]
	v_mfma_f32_16x16x32_bf16 v[126:129], v[160:163], v[192:195], v[126:129]
	v_mfma_f32_16x16x32_bf16 v[122:125], v[168:171], v[192:195], v[122:125]
	v_mfma_f32_16x16x32_bf16 v[110:113], v[160:163], v[204:207], v[110:113]
	v_mfma_f32_16x16x32_bf16 v[106:109], v[168:171], v[204:207], v[106:109]
	v_mfma_f32_16x16x32_bf16 v[94:97], v[160:163], v[212:215], v[94:97]
	v_mfma_f32_16x16x32_bf16 v[90:93], v[168:171], v[212:215], v[90:93]
	v_mfma_f32_16x16x32_bf16 v[78:81], v[160:163], v[220:223], v[78:81]
	v_mfma_f32_16x16x32_bf16 v[74:77], v[168:171], v[220:223], v[74:77]
	v_mfma_f32_16x16x32_bf16 v[118:121], v[172:175], v[188:191], v[118:121]
	v_mfma_f32_16x16x32_bf16 v[114:117], v[180:183], v[188:191], v[114:117]
	v_mfma_f32_16x16x32_bf16 v[102:105], v[172:175], v[200:203], v[102:105]
	v_mfma_f32_16x16x32_bf16 v[98:101], v[180:183], v[200:203], v[98:101]
	v_mfma_f32_16x16x32_bf16 v[86:89], v[172:175], v[208:211], v[86:89]
	v_mfma_f32_16x16x32_bf16 v[82:85], v[180:183], v[208:211], v[82:85]
	v_mfma_f32_16x16x32_bf16 v[70:73], v[172:175], v[216:219], v[70:73]
	v_mfma_f32_16x16x32_bf16 v[66:69], v[180:183], v[216:219], v[66:69]
	v_mfma_f32_16x16x32_bf16 v[118:121], v[176:179], v[192:195], v[118:121]
	v_mfma_f32_16x16x32_bf16 v[114:117], v[184:187], v[192:195], v[114:117]
	v_mfma_f32_16x16x32_bf16 v[102:105], v[176:179], v[204:207], v[102:105]
	v_mfma_f32_16x16x32_bf16 v[98:101], v[184:187], v[204:207], v[98:101]
	v_mfma_f32_16x16x32_bf16 v[86:89], v[176:179], v[212:215], v[86:89]
	v_mfma_f32_16x16x32_bf16 v[82:85], v[184:187], v[212:215], v[82:85]
	v_mfma_f32_16x16x32_bf16 v[70:73], v[176:179], v[220:223], v[70:73]
	v_mfma_f32_16x16x32_bf16 v[66:69], v[184:187], v[220:223], v[66:69]
.Lcz_p1_0_j:
	s_barrier
	s_add_i32 s87, s72, s24
	v_lshl_add_u64 v[196:197], s[38:39], 0, v[132:133]
	s_mov_b32 m0, s87
	ds_read_b128 v[188:191], v155 offset:16384
	ds_read_b128 v[192:195], v155 offset:17408
	ds_read_b128 v[200:203], v155 offset:18432
	ds_read_b128 v[204:207], v155 offset:19456
	ds_read_b128 v[208:211], v155 offset:20480
	ds_read_b128 v[212:215], v155 offset:21504
	ds_read_b128 v[216:219], v155 offset:22528
	ds_read_b128 v[220:223], v155 offset:23552
	global_load_lds_dwordx4 v[196:197], off
	s_add_i32 m0, s87, 0x2000
	s_add_u32 s88, s38, 0x40000
	v_lshl_add_u64 v[224:225], s[38:39], 0, v[136:137]
	s_addc_u32 s89, s39, 0
	s_add_i32 s87, s73, s24
	global_load_lds_dwordx4 v[224:225], off
	v_lshl_add_u64 v[226:227], s[88:89], 0, v[132:133]
	s_mov_b32 m0, s87
	v_lshl_add_u64 v[228:229], s[40:41], 0, v[134:135]
	global_load_lds_dwordx4 v[226:227], off
	v_lshl_add_u64 v[226:227], s[88:89], 0, v[136:137]
	s_add_i32 m0, s87, 0x2000
	s_nop 0
	global_load_lds_dwordx4 v[226:227], off
	v_lshl_add_u64 v[226:227], s[40:41], 0, v[130:131]
	s_mov_b32 m0, s25
	s_nop 0
	global_load_lds_dwordx4 v[226:227], off
	s_mov_b32 m0, s31
	s_nop 0
	global_load_lds_dwordx4 v[228:229], off
	s_cmp_eq_u32 s98, 0
	s_cbranch_scc1 .Lrx_p1_1_n
	s_sub_u32 s98, s98, 1
	s_waitcnt vmcnt(16)
	s_branch .Lrx_p1_1_j

; #define PG8_STAGE(bufoff, gbase, voff) do { _Pragma("unroll") for (int _i = 0; _i < 2; ++_i) \
;         __builtin_amdgcn_global_load_lds((const unsigned*)((const char*)(gbase) + (voff)[_i]), (LAS unsigned*)(lds + (bufoff) + ldsw + _i * 8192), 16, 0, 0); } while (0)
; #define PG8_LDA(dst, b, h) do { _Pragma("unroll") for (int m = 0; m < 4; ++m) _Pragma("unroll") for (int k = 0; k < 2; ++k) dst[m][k] = *(const LAS bf16x8*)(lds + PG8_SA(b, h) + aoff + m * 2048 + k * 1024); } while (0)
; #define PG8_LDB(dst, b, h) do { _Pragma("unroll") for (int n = 0; n < 2; ++n) _Pragma("unroll") for (int k = 0; k < 2; ++k) dst[n][k] = *(const LAS bf16x8*)(lds + PG8_SB(b, h) + boff + n * 2048 + k * 1024); } while (0)
; #define PG8_MMA(ai, bj, At, Bt) do { __builtin_amdgcn_s_setprio(1); _Pragma("unroll") for (int m = 0; m < 4; ++m) _Pragma("unroll") for (int n = 0; n < 2; ++n) _Pragma("unroll") for (int k = 0; k < 2; ++k) \
;         acc[ai][bj][m][n] = __builtin_amdgcn_mfma_f32_16x16x32_bf16(Bt[n][k], At[m][k], acc[ai][bj][m][n], 0, 0, 0); __builtin_amdgcn_s_setprio(0); } while (0)
; #define PG8_WAIT_V(n) asm volatile("s_waitcnt vmcnt(" #n ")" ::: "memory")
; #define PG8_WAIT_L(n) asm volatile("s_waitcnt lgkmcnt(" #n ")" ::: "memory")
; #define PG8_BAR __builtin_amdgcn_s_barrier()
; #define PG8_SCHED __builtin_amdgcn_sched_barrier(0)
; template <class Epi>
; __device__ __forceinline__ void gemm_phase(LAS unsigned char* lds, const Gemm g, const Sched& S, const Epi& E) {
;     ...
;             PG8_LDA(At, 0, 1); PG8_STAGE(PG8_SB(0, 0), b2, voffB); PG8_STAGE(PG8_SB(0, 1), b2 + hstepB, voffB); PG8_STAGE(PG8_SA(0, 0), a2, voffA);
;             PG8_WAIT_V(8); PG8_WAIT_L(0); PG8_BAR; PG8_MMA(1, 0, At, B0); PG8_MMA(1, 1, At, B1); PG8_BAR; PG8_SCHED;
;             PG8_LDB(B0, 1, 0); PG8_LDB(B1, 1, 1); PG8_SCHED; PG8_LDA(At, 1, 0); PG8_STAGE(PG8_SA(0, 1), a2 + hstepA, voffA);
.Lrx_p1_1_j:
	s_waitcnt lgkmcnt(0)
	s_cmp_eq_u32 s86, -2
	s_cbranch_scc1 .Lcz_p1_1
	s_barrier
	s_waitcnt lgkmcnt(0)
	v_mfma_f32_16x16x32_bf16 v[62:65], v[156:159], v[188:191], v[62:65]
	v_mfma_f32_16x16x32_bf16 v[58:61], v[164:167], v[188:191], v[58:61]
	v_mfma_f32_16x16x32_bf16 v[46:49], v[156:159], v[200:203], v[46:49]
	v_mfma_f32_16x16x32_bf16 v[42:45], v[164:167], v[200:203], v[42:45]
	v_mfma_f32_16x16x32_bf16 v[30:33], v[156:159], v[208:211], v[30:33]
	v_mfma_f32_16x16x32_bf16 v[26:29], v[164:167], v[208:211], v[26:29]
	v_mfma_f32_16x16x32_bf16 v[14:17], v[156:159], v[216:219], v[14:17]
	v_mfma_f32_16x16x32_bf16 v[10:13], v[164:167], v[216:219], v[10:13]
	v_mfma_f32_16x16x32_bf16 v[62:65], v[160:163], v[192:195], v[62:65]
	v_mfma_f32_16x16x32_bf16 v[58:61], v[168:171], v[192:195], v[58:61]
	v_mfma_f32_16x16x32_bf16 v[46:49], v[160:163], v[204:207], v[46:49]
	v_mfma_f32_16x16x32_bf16 v[42:45], v[168:171], v[204:207], v[42:45]
	v_mfma_f32_16x16x32_bf16 v[30:33], v[160:163], v[212:215], v[30:33]
	v_mfma_f32_16x16x32_bf16 v[26:29], v[168:171], v[212:215], v[26:29]
	v_mfma_f32_16x16x32_bf16 v[14:17], v[160:163], v[220:223], v[14:17]
	v_mfma_f32_16x16x32_bf16 v[10:13], v[168:171], v[220:223], v[10:13]
	v_mfma_f32_16x16x32_bf16 v[54:57], v[172:175], v[188:191], v[54:57]
	v_mfma_f32_16x16x32_bf16 v[50:53], v[180:183], v[188:191], v[50:53]
	v_mfma_f32_16x16x32_bf16 v[38:41], v[172:175], v[200:203], v[38:41]
	v_mfma_f32_16x16x32_bf16 v[34:37], v[180:183], v[200:203], v[34:37]
	v_mfma_f32_16x16x32_bf16 v[22:25], v[172:175], v[208:211], v[22:25]
	v_mfma_f32_16x16x32_bf16 v[18:21], v[180:183], v[208:211], v[18:21]
	v_mfma_f32_16x16x32_bf16 v[6:9], v[172:175], v[216:219], v[6:9]
	v_mfma_f32_16x16x32_bf16 v[2:5], v[180:183], v[216:219], v[2:5]
	v_mfma_f32_16x16x32_bf16 v[54:57], v[176:179], v[192:195], v[54:57]
	v_mfma_f32_16x16x32_bf16 v[50:53], v[184:187], v[192:195], v[50:53]
	v_mfma_f32_16x16x32_bf16 v[38:41], v[176:179], v[204:207], v[38:41]
	v_mfma_f32_16x16x32_bf16 v[34:37], v[184:187], v[204:207], v[34:37]
	v_mfma_f32_16x16x32_bf16 v[22:25], v[176:179], v[212:215], v[22:25]
	v_mfma_f32_16x16x32_bf16 v[18:21], v[184:187], v[212:215], v[18:21]
	v_mfma_f32_16x16x32_bf16 v[6:9], v[176:179], v[220:223], v[6:9]
	v_mfma_f32_16x16x32_bf16 v[2:5], v[184:187], v[220:223], v[2:5]
.Lcz_p1_1_j:
	s_barrier
	s_add_i32 s87, 0, 0x18000
	s_add_i32 s88, 0, 0x1c000
	v_add_u32_e32 v168, s87, v147
	v_add_u32_e32 v184, s88, v147
	ds_read_b128 v[156:159], v168
	ds_read_b128 v[160:163], v168 offset:1024
	ds_read_b128 v[164:167], v168 offset:2048
	ds_read_b128 v[168:171], v168 offset:3072
	ds_read_b128 v[172:175], v184
	ds_read_b128 v[176:179], v184 offset:1024
	ds_read_b128 v[180:183], v184 offset:2048
	ds_read_b128 v[184:187], v184 offset:3072
	s_add_u32 s40, s40, 0x40000
	s_addc_u32 s41, s41, 0
	s_mov_b32 m0, s52
	v_lshl_add_u64 v[230:231], s[40:41], 0, v[130:131]
	ds_read_b128 v[188:191], v155 offset:32768
	ds_read_b128 v[192:195], v155 offset:33792
	ds_read_b128 v[200:203], v155 offset:34816
	ds_read_b128 v[204:207], v155 offset:35840
	ds_read_b128 v[208:211], v155 offset:36864
	ds_read_b128 v[212:215], v155 offset:37888
	ds_read_b128 v[216:219], v155 offset:38912
	ds_read_b128 v[220:223], v155 offset:39936
	global_load_lds_dwordx4 v[230:231], off
	v_lshl_add_u64 v[230:231], s[40:41], 0, v[134:135]
	s_mov_b32 m0, s53
	s_nop 0
	global_load_lds_dwordx4 v[230:231], off
	s_cmp_eq_u32 s98, 0
	s_cbranch_scc1 .Lrx_p1_2_n
	s_sub_u32 s98, s98, 1
	s_waitcnt vmcnt(10)
	s_branch .Lrx_p1_2_j

; #define PG8_STAGE(bufoff, gbase, voff) do { _Pragma("unroll") for (int _i = 0; _i < 2; ++_i) \
;         __builtin_amdgcn_global_load_lds((const unsigned*)((const char*)(gbase) + (voff)[_i]), (LAS unsigned*)(lds + (bufoff) + ldsw + _i * 8192), 16, 0, 0); } while (0)
; #define PG8_LDA(dst, b, h) do { _Pragma("unroll") for (int m = 0; m < 4; ++m) _Pragma("unroll") for (int k = 0; k < 2; ++k) dst[m][k] = *(const LAS bf16x8*)(lds + PG8_SA(b, h) + aoff + m * 2048 + k * 1024); } while (0)
; #define PG8_LDB(dst, b, h) do { _Pragma("unroll") for (int n = 0; n < 2; ++n) _Pragma("unroll") for (int k = 0; k < 2; ++k) dst[n][k] = *(const LAS bf16x8*)(lds + PG8_SB(b, h) + boff + n * 2048 + k * 1024); } while (0)
; #define PG8_MMA(ai, bj, At, Bt) do { __builtin_amdgcn_s_setprio(1); _Pragma("unroll") for (int m = 0; m < 4; ++m) _Pragma("unroll") for (int n = 0; n < 2; ++n) _Pragma("unroll") for (int k = 0; k < 2; ++k) \
;         acc[ai][bj][m][n] = __builtin_amdgcn_mfma_f32_16x16x32_bf16(Bt[n][k], At[m][k], acc[ai][bj][m][n], 0, 0, 0); __builtin_amdgcn_s_setprio(0); } while (0)
; #define PG8_WAIT_V(n) asm volatile("s_waitcnt vmcnt(" #n ")" ::: "memory")
; #define PG8_WAIT_L(n) asm volatile("s_waitcnt lgkmcnt(" #n ")" ::: "memory")
; #define PG8_BAR __builtin_amdgcn_s_barrier()
; #define PG8_SCHED __builtin_amdgcn_sched_barrier(0)
; template <class Epi>
; __device__ __forceinline__ void gemm_phase(LAS unsigned char* lds, const Gemm g, const Sched& S, const Epi& E) {
;     ...
;             PG8_LDB(B0, 1, 0); PG8_LDB(B1, 1, 1); PG8_SCHED; PG8_LDA(At, 1, 0); PG8_STAGE(PG8_SA(0, 1), a2 + hstepA, voffA);
;             PG8_WAIT_V(8); PG8_WAIT_L(0); PG8_BAR; PG8_MMA(0, 0, At, B0); PG8_MMA(0, 1, At, B1); PG8_BAR; PG8_SCHED;
;             PG8_LDA(At, 1, 1); PG8_STAGE(PG8_SB(1, 0), b3, voffB); PG8_STAGE(PG8_SB(1, 1), b3 + hstepB, voffB); PG8_STAGE(PG8_SA(1, 0), a3, voffA);
;             PG8_WAIT_V(8); PG8_WAIT_L(0); PG8_BAR; PG8_MMA(1, 0, At, B0); PG8_MMA(1, 1, At, B1); PG8_BAR; PG8_SCHED;
;         }
.Lrx_p1_2_j:
	s_waitcnt lgkmcnt(0)
	s_barrier
	s_waitcnt lgkmcnt(0)
	v_mfma_f32_16x16x32_bf16 v[126:129], v[156:159], v[188:191], v[126:129]
	v_mfma_f32_16x16x32_bf16 v[122:125], v[164:167], v[188:191], v[122:125]
	v_mfma_f32_16x16x32_bf16 v[110:113], v[156:159], v[200:203], v[110:113]
	v_mfma_f32_16x16x32_bf16 v[106:109], v[164:167], v[200:203], v[106:109]
	v_mfma_f32_16x16x32_bf16 v[94:97], v[156:159], v[208:211], v[94:97]
	v_mfma_f32_16x16x32_bf16 v[90:93], v[164:167], v[208:211], v[90:93]
	v_mfma_f32_16x16x32_bf16 v[78:81], v[156:159], v[216:219], v[78:81]
	v_mfma_f32_16x16x32_bf16 v[74:77], v[164:167], v[216:219], v[74:77]
	v_mfma_f32_16x16x32_bf16 v[126:129], v[160:163], v[192:195], v[126:129]
	v_mfma_f32_16x16x32_bf16 v[122:125], v[168:171], v[192:195], v[122:125]
	v_mfma_f32_16x16x32_bf16 v[110:113], v[160:163], v[204:207], v[110:113]
	v_mfma_f32_16x16x32_bf16 v[106:109], v[168:171], v[204:207], v[106:109]
	v_mfma_f32_16x16x32_bf16 v[94:97], v[160:163], v[212:215], v[94:97]
	v_mfma_f32_16x16x32_bf16 v[90:93], v[168:171], v[212:215], v[90:93]
	v_mfma_f32_16x16x32_bf16 v[78:81], v[160:163], v[220:223], v[78:81]
	v_mfma_f32_16x16x32_bf16 v[74:77], v[168:171], v[220:223], v[74:77]
	v_mfma_f32_16x16x32_bf16 v[118:121], v[172:175], v[188:191], v[118:121]
	v_mfma_f32_16x16x32_bf16 v[114:117], v[180:183], v[188:191], v[114:117]
	v_mfma_f32_16x16x32_bf16 v[102:105], v[172:175], v[200:203], v[102:105]
	v_mfma_f32_16x16x32_bf16 v[98:101], v[180:183], v[200:203], v[98:101]
	v_mfma_f32_16x16x32_bf16 v[86:89], v[172:175], v[208:211], v[86:89]
	v_mfma_f32_16x16x32_bf16 v[82:85], v[180:183], v[208:211], v[82:85]
	v_mfma_f32_16x16x32_bf16 v[70:73], v[172:175], v[216:219], v[70:73]
	v_mfma_f32_16x16x32_bf16 v[66:69], v[180:183], v[216:219], v[66:69]
	v_mfma_f32_16x16x32_bf16 v[118:121], v[176:179], v[192:195], v[118:121]
	v_mfma_f32_16x16x32_bf16 v[114:117], v[184:187], v[192:195], v[114:117]
	v_mfma_f32_16x16x32_bf16 v[102:105], v[176:179], v[204:207], v[102:105]
	v_mfma_f32_16x16x32_bf16 v[98:101], v[184:187], v[204:207], v[98:101]
	v_mfma_f32_16x16x32_bf16 v[86:89], v[176:179], v[212:215], v[86:89]
	v_mfma_f32_16x16x32_bf16 v[82:85], v[184:187], v[212:215], v[82:85]
	v_mfma_f32_16x16x32_bf16 v[70:73], v[176:179], v[220:223], v[70:73]
	v_mfma_f32_16x16x32_bf16 v[66:69], v[184:187], v[220:223], v[66:69]
	s_barrier
	s_add_i32 s40, s87, s24
	v_lshl_add_u64 v[196:197], v[196:197], 0, s[6:7]
	s_mov_b32 m0, s40
	ds_read_b128 v[188:191], v155 offset:49152
	ds_read_b128 v[192:195], v155 offset:50176
	ds_read_b128 v[200:203], v155 offset:51200
	ds_read_b128 v[204:207], v155 offset:52224
	ds_read_b128 v[208:211], v155 offset:53248
	ds_read_b128 v[212:215], v155 offset:54272
	ds_read_b128 v[216:219], v155 offset:55296
	ds_read_b128 v[220:223], v155 offset:56320
	global_load_lds_dwordx4 v[196:197], off
	s_add_i32 m0, s40, 0x2000
	s_add_u32 s38, s38, 0x40080
	v_lshl_add_u64 v[196:197], v[224:225], 0, s[6:7]
	s_addc_u32 s39, s39, 0
	s_add_i32 s40, s88, s24
	global_load_lds_dwordx4 v[196:197], off
	v_lshl_add_u64 v[196:197], s[38:39], 0, v[132:133]
	s_mov_b32 m0, s40
	s_nop 0
	global_load_lds_dwordx4 v[196:197], off
	v_lshl_add_u64 v[196:197], s[38:39], 0, v[136:137]
	s_add_i32 m0, s40, 0x2000
	s_nop 0
	global_load_lds_dwordx4 v[196:197], off
	v_lshl_add_u64 v[196:197], v[226:227], 0, s[6:7]
	s_mov_b32 m0, s54
	s_nop 0
	global_load_lds_dwordx4 v[196:197], off
	v_lshl_add_u64 v[196:197], v[228:229], 0, s[6:7]
	s_mov_b32 m0, s55
	s_nop 0
	global_load_lds_dwordx4 v[196:197], off
	s_waitcnt vmcnt(8)
	s_waitcnt lgkmcnt(0)
	s_barrier
	s_waitcnt lgkmcnt(0)
	v_mfma_f32_16x16x32_bf16 v[62:65], v[156:159], v[188:191], v[62:65]
	v_mfma_f32_16x16x32_bf16 v[58:61], v[164:167], v[188:191], v[58:61]
	v_mfma_f32_16x16x32_bf16 v[46:49], v[156:159], v[200:203], v[46:49]
	v_mfma_f32_16x16x32_bf16 v[42:45], v[164:167], v[200:203], v[42:45]
	v_mfma_f32_16x16x32_bf16 v[30:33], v[156:159], v[208:211], v[30:33]
	v_mfma_f32_16x16x32_bf16 v[26:29], v[164:167], v[208:211], v[26:29]
	v_mfma_f32_16x16x32_bf16 v[14:17], v[156:159], v[216:219], v[14:17]
	v_mfma_f32_16x16x32_bf16 v[10:13], v[164:167], v[216:219], v[10:13]
	v_mfma_f32_16x16x32_bf16 v[62:65], v[160:163], v[192:195], v[62:65]
	v_mfma_f32_16x16x32_bf16 v[58:61], v[168:171], v[192:195], v[58:61]
	v_mfma_f32_16x16x32_bf16 v[46:49], v[160:163], v[204:207], v[46:49]
	v_mfma_f32_16x16x32_bf16 v[42:45], v[168:171], v[204:207], v[42:45]
	v_mfma_f32_16x16x32_bf16 v[30:33], v[160:163], v[212:215], v[30:33]
	v_mfma_f32_16x16x32_bf16 v[26:29], v[168:171], v[212:215], v[26:29]
	v_mfma_f32_16x16x32_bf16 v[14:17], v[160:163], v[220:223], v[14:17]
	v_mfma_f32_16x16x32_bf16 v[10:13], v[168:171], v[220:223], v[10:13]
	v_mfma_f32_16x16x32_bf16 v[54:57], v[172:175], v[188:191], v[54:57]
	v_mfma_f32_16x16x32_bf16 v[50:53], v[180:183], v[188:191], v[50:53]
	v_mfma_f32_16x16x32_bf16 v[38:41], v[172:175], v[200:203], v[38:41]
	v_mfma_f32_16x16x32_bf16 v[34:37], v[180:183], v[200:203], v[34:37]
	v_mfma_f32_16x16x32_bf16 v[22:25], v[172:175], v[208:211], v[22:25]
	v_mfma_f32_16x16x32_bf16 v[18:21], v[180:183], v[208:211], v[18:21]
	v_mfma_f32_16x16x32_bf16 v[6:9], v[172:175], v[216:219], v[6:9]
	v_mfma_f32_16x16x32_bf16 v[2:5], v[180:183], v[216:219], v[2:5]
	v_mfma_f32_16x16x32_bf16 v[54:57], v[176:179], v[192:195], v[54:57]
	v_mfma_f32_16x16x32_bf16 v[50:53], v[184:187], v[192:195], v[50:53]
	v_mfma_f32_16x16x32_bf16 v[38:41], v[176:179], v[204:207], v[38:41]
	v_mfma_f32_16x16x32_bf16 v[34:37], v[184:187], v[204:207], v[34:37]
	v_mfma_f32_16x16x32_bf16 v[22:25], v[176:179], v[212:215], v[22:25]
	v_mfma_f32_16x16x32_bf16 v[18:21], v[184:187], v[212:215], v[18:21]
	v_mfma_f32_16x16x32_bf16 v[6:9], v[176:179], v[220:223], v[6:9]
	v_mfma_f32_16x16x32_bf16 v[2:5], v[184:187], v[220:223], v[2:5]
	s_barrier
	s_add_i32 s86, s86, 2
	s_add_u32 s34, s34, 0x100
	s_addc_u32 s35, s35, 0
	s_add_u32 s84, s84, 0x100
	s_addc_u32 s85, s85, 0
	s_cmp_gt_u32 s86, 13
	s_cbranch_scc0 .LBB0_584
	s_and_b64 vcc, exec, s[8:9]
	s_cbranch_vccz .LBB0_587
	s_barrier

; #define PG8_STAGE(bufoff, gbase, voff) do { _Pragma("unroll") for (int _i = 0; _i < 2; ++_i) \
;         __builtin_amdgcn_global_load_lds((const unsigned*)((const char*)(gbase) + (voff)[_i]), (LAS unsigned*)(lds + (bufoff) + ldsw + _i * 8192), 16, 0, 0); } while (0)
; #define PG8_LDA(dst, b, h) do { _Pragma("unroll") for (int m = 0; m < 4; ++m) _Pragma("unroll") for (int k = 0; k < 2; ++k) dst[m][k] = *(const LAS bf16x8*)(lds + PG8_SA(b, h) + aoff + m * 2048 + k * 1024); } while (0)
; #define PG8_MMA(ai, bj, At, Bt) do { __builtin_amdgcn_s_setprio(1); _Pragma("unroll") for (int m = 0; m < 4; ++m) _Pragma("unroll") for (int n = 0; n < 2; ++n) _Pragma("unroll") for (int k = 0; k < 2; ++k) \
;         acc[ai][bj][m][n] = __builtin_amdgcn_mfma_f32_16x16x32_bf16(Bt[n][k], At[m][k], acc[ai][bj][m][n], 0, 0, 0); __builtin_amdgcn_s_setprio(0); } while (0)
; #define PG8_WAIT_V(n) asm volatile("s_waitcnt vmcnt(" #n ")" ::: "memory")
; #define PG8_WAIT_L(n) asm volatile("s_waitcnt lgkmcnt(" #n ")" ::: "memory")
; #define PG8_BAR __builtin_amdgcn_s_barrier()
; #define PG8_SCHED __builtin_amdgcn_sched_barrier(0)
; template <class Epi>
; __device__ __forceinline__ void gemm_phase(LAS unsigned char* lds, const Gemm g, const Sched& S, const Epi& E) {
;     ...
;                 for (int n = 0; n < 2; ++n) acc[a][b][m][n] = (f32x4){0.f, 0.f, 0.f, 0.f};
;     ...
;             PG8_WAIT_V(8); PG8_WAIT_L(0); PG8_BAR; PG8_MMA(0, 0, At, B0); PG8_MMA(0, 1, At, B1); PG8_BAR; PG8_SCHED;
;             PG8_LDA(At, 0, 1); PG8_STAGE(PG8_SB(0, 0), b2, voffB); PG8_STAGE(PG8_SB(0, 1), b2 + hstepB, voffB); PG8_STAGE(PG8_SA(0, 0), a2, voffA);
;             PG8_WAIT_V(8); PG8_WAIT_L(0); PG8_BAR; PG8_MMA(1, 0, At, B0); PG8_MMA(1, 1, At, B1); PG8_BAR; PG8_SCHED;
.Lcz_p1_0:
	s_barrier
	s_waitcnt lgkmcnt(0)
	v_mfma_f32_16x16x32_bf16 v[126:129], v[156:159], v[188:191], 0
	v_mfma_f32_16x16x32_bf16 v[122:125], v[164:167], v[188:191], 0
	v_mfma_f32_16x16x32_bf16 v[110:113], v[156:159], v[200:203], 0
	v_mfma_f32_16x16x32_bf16 v[106:109], v[164:167], v[200:203], 0
	v_mfma_f32_16x16x32_bf16 v[94:97], v[156:159], v[208:211], 0
	v_mfma_f32_16x16x32_bf16 v[90:93], v[164:167], v[208:211], 0
	v_mfma_f32_16x16x32_bf16 v[78:81], v[156:159], v[216:219], 0
	v_mfma_f32_16x16x32_bf16 v[74:77], v[164:167], v[216:219], 0
	v_mfma_f32_16x16x32_bf16 v[126:129], v[160:163], v[192:195], v[126:129]
	v_mfma_f32_16x16x32_bf16 v[122:125], v[168:171], v[192:195], v[122:125]
	v_mfma_f32_16x16x32_bf16 v[110:113], v[160:163], v[204:207], v[110:113]
	v_mfma_f32_16x16x32_bf16 v[106:109], v[168:171], v[204:207], v[106:109]
	v_mfma_f32_16x16x32_bf16 v[94:97], v[160:163], v[212:215], v[94:97]
	v_mfma_f32_16x16x32_bf16 v[90:93], v[168:171], v[212:215], v[90:93]
	v_mfma_f32_16x16x32_bf16 v[78:81], v[160:163], v[220:223], v[78:81]
	v_mfma_f32_16x16x32_bf16 v[74:77], v[168:171], v[220:223], v[74:77]
	v_mfma_f32_16x16x32_bf16 v[118:121], v[172:175], v[188:191], 0
	v_mfma_f32_16x16x32_bf16 v[114:117], v[180:183], v[188:191], 0
	v_mfma_f32_16x16x32_bf16 v[102:105], v[172:175], v[200:203], 0
	v_mfma_f32_16x16x32_bf16 v[98:101], v[180:183], v[200:203], 0
	v_mfma_f32_16x16x32_bf16 v[86:89], v[172:175], v[208:211], 0
	v_mfma_f32_16x16x32_bf16 v[82:85], v[180:183], v[208:211], 0
	v_mfma_f32_16x16x32_bf16 v[70:73], v[172:175], v[216:219], 0
	v_mfma_f32_16x16x32_bf16 v[66:69], v[180:183], v[216:219], 0
	v_mfma_f32_16x16x32_bf16 v[118:121], v[176:179], v[192:195], v[118:121]
	v_mfma_f32_16x16x32_bf16 v[114:117], v[184:187], v[192:195], v[114:117]
	v_mfma_f32_16x16x32_bf16 v[102:105], v[176:179], v[204:207], v[102:105]
	v_mfma_f32_16x16x32_bf16 v[98:101], v[184:187], v[204:207], v[98:101]
	v_mfma_f32_16x16x32_bf16 v[86:89], v[176:179], v[212:215], v[86:89]
	v_mfma_f32_16x16x32_bf16 v[82:85], v[184:187], v[212:215], v[82:85]
	v_mfma_f32_16x16x32_bf16 v[70:73], v[176:179], v[220:223], v[70:73]
	v_mfma_f32_16x16x32_bf16 v[66:69], v[184:187], v[220:223], v[66:69]
	s_branch .Lcz_p1_0_j
.Lcz_p1_1:
	s_barrier
	s_waitcnt lgkmcnt(0)
	v_mfma_f32_16x16x32_bf16 v[62:65], v[156:159], v[188:191], 0
	v_mfma_f32_16x16x32_bf16 v[58:61], v[164:167], v[188:191], 0
	v_mfma_f32_16x16x32_bf16 v[46:49], v[156:159], v[200:203], 0
	v_mfma_f32_16x16x32_bf16 v[42:45], v[164:167], v[200:203], 0
	v_mfma_f32_16x16x32_bf16 v[30:33], v[156:159], v[208:211], 0
	v_mfma_f32_16x16x32_bf16 v[26:29], v[164:167], v[208:211], 0
	v_mfma_f32_16x16x32_bf16 v[14:17], v[156:159], v[216:219], 0
	v_mfma_f32_16x16x32_bf16 v[10:13], v[164:167], v[216:219], 0
	v_mfma_f32_16x16x32_bf16 v[62:65], v[160:163], v[192:195], v[62:65]
	v_mfma_f32_16x16x32_bf16 v[58:61], v[168:171], v[192:195], v[58:61]
	v_mfma_f32_16x16x32_bf16 v[46:49], v[160:163], v[204:207], v[46:49]
	v_mfma_f32_16x16x32_bf16 v[42:45], v[168:171], v[204:207], v[42:45]
	v_mfma_f32_16x16x32_bf16 v[30:33], v[160:163], v[212:215], v[30:33]
	v_mfma_f32_16x16x32_bf16 v[26:29], v[168:171], v[212:215], v[26:29]
	v_mfma_f32_16x16x32_bf16 v[14:17], v[160:163], v[220:223], v[14:17]
	v_mfma_f32_16x16x32_bf16 v[10:13], v[168:171], v[220:223], v[10:13]
	v_mfma_f32_16x16x32_bf16 v[54:57], v[172:175], v[188:191], 0
	v_mfma_f32_16x16x32_bf16 v[50:53], v[180:183], v[188:191], 0
	v_mfma_f32_16x16x32_bf16 v[38:41], v[172:175], v[200:203], 0
	v_mfma_f32_16x16x32_bf16 v[34:37], v[180:183], v[200:203], 0
	v_mfma_f32_16x16x32_bf16 v[22:25], v[172:175], v[208:211], 0
	v_mfma_f32_16x16x32_bf16 v[18:21], v[180:183], v[208:211], 0
	v_mfma_f32_16x16x32_bf16 v[6:9], v[172:175], v[216:219], 0
	v_mfma_f32_16x16x32_bf16 v[2:5], v[180:183], v[216:219], 0
	v_mfma_f32_16x16x32_bf16 v[54:57], v[176:179], v[192:195], v[54:57]
	v_mfma_f32_16x16x32_bf16 v[50:53], v[184:187], v[192:195], v[50:53]
	v_mfma_f32_16x16x32_bf16 v[38:41], v[176:179], v[204:207], v[38:41]
	v_mfma_f32_16x16x32_bf16 v[34:37], v[184:187], v[204:207], v[34:37]
	v_mfma_f32_16x16x32_bf16 v[22:25], v[176:179], v[212:215], v[22:25]
	v_mfma_f32_16x16x32_bf16 v[18:21], v[184:187], v[212:215], v[18:21]
	v_mfma_f32_16x16x32_bf16 v[6:9], v[176:179], v[220:223], v[6:9]
	v_mfma_f32_16x16x32_bf16 v[2:5], v[184:187], v[220:223], v[2:5]
	s_branch .Lcz_p1_1_j

; __device__ __forceinline__ unsigned xb_ld(unsigned* p)              { return __hip_atomic_load(p, __ATOMIC_RELAXED, __HIP_MEMORY_SCOPE_AGENT); }
; __device__ __forceinline__ unsigned xb_add(unsigned* p, unsigned v) { return __hip_atomic_fetch_add(p, v, __ATOMIC_RELAXED, __HIP_MEMORY_SCOPE_AGENT); }
; #define XB_SPIN(cond, bar) do { unsigned _sp = 0; while (cond) { __builtin_amdgcn_s_sleep(1); \
;     if ((++_sp & 255u) == 0u) { if (xb_ld(&(bar)[XB_TMO])) break; if (_sp > XB_SPIN_CAP) { atomicAdd(&(bar)[XB_TMO], 1u); break; } } } } while (0)
; __device__ __forceinline__ void xcd_barrier(const XcdBarrier& b) {
;     asm volatile("s_waitcnt vmcnt(0)" ::: "memory");
;     __syncthreads();
;     if (threadIdx.x == 0) {
;         unsigned* bar = b.bar;
;         __builtin_amdgcn_s_waitcnt(0);
;         unsigned nloc = b.st[0], nx = b.st[1];
;         if (nloc == 0u) { xcd_barrier_complete(bar, b.x, nloc, nx); b.st[0] = nloc; b.st[1] = nx; }
;         const unsigned old = xb_add(&bar[XB_XSUB(b.x)], 1u);
;         const unsigned gen = old / nloc;
;         if (old + 1u == (gen + 1u) * nloc) {
;             __builtin_amdgcn_fence(__ATOMIC_RELEASE, "agent");
;             asm volatile("s_waitcnt vmcnt(0)" ::: "memory");
;             const unsigned og = xb_add(&bar[XB_TOP], 1u);
;             const unsigned tg = og / nx;
;             if (og + 1u == (tg + 1u) * nx) xb_add(&bar[XB_TOPGEN], 1u);
;             else XB_SPIN(xb_ld(&bar[XB_TOPGEN]) == tg, bar);
;             __builtin_amdgcn_fence(__ATOMIC_ACQUIRE, "agent");
;             xb_add(&bar[XB_XGEN(b.x)], 1u);
;             asm volatile("s_waitcnt vmcnt(0)" ::: "memory");
;         } else {
;             XB_SPIN(xb_ld(&bar[XB_XGEN(b.x)]) == gen, bar);
;             __builtin_amdgcn_fence(__ATOMIC_ACQUIRE, "agent");
;             asm volatile("s_waitcnt vmcnt(0)" ::: "memory");
;         }
;     }
;     __syncthreads();
; }
.LBB0_591:
	s_cmp_gt_i32 s95, 2
	s_cselect_b64 s[0:1], -1, 0
	s_and_b64 s[4:5], s[10:11], s[0:1]
	s_andn2_b64 vcc, exec, s[4:5]
	s_cbranch_vccnz .LBB0_641
	s_setprio 0
	s_waitcnt vmcnt(0) lgkmcnt(0)
	s_barrier
	v_readfirstlane_b32 s98, v0
	s_cmp_lg_u32 s98, 0
	s_cbranch_scc1 .Lxb1_end
	s_mov_b64 s[100:101], exec
	v_readlane_b32 s98, v253, 0
	s_cmp_lg_u32 s98, 0
	s_cbranch_scc1 .Lxb1_have
	s_mov_b64 exec, 0xffff
	v_mbcnt_lo_u32_b32 v254, -1, 0
	v_lshlrev_b32_e32 v254, 8, v254
	s_mov_b32 s99, 0
	v_writelane_b32 v253, s99, 3

; #define PG8_STAGE(bufoff, gbase, voff) do { _Pragma("unroll") for (int _i = 0; _i < 2; ++_i) \
;         __builtin_amdgcn_global_load_lds((const unsigned*)((const char*)(gbase) + (voff)[_i]), (LAS unsigned*)(lds + (bufoff) + ldsw + _i * 8192), 16, 0, 0); } while (0)
; #define PG8_LDA(dst, b, h) do { _Pragma("unroll") for (int m = 0; m < 4; ++m) _Pragma("unroll") for (int k = 0; k < 2; ++k) dst[m][k] = *(const LAS bf16x8*)(lds + PG8_SA(b, h) + aoff + m * 2048 + k * 1024); } while (0)
; #define PG8_LDB(dst, b, h) do { _Pragma("unroll") for (int n = 0; n < 2; ++n) _Pragma("unroll") for (int k = 0; k < 2; ++k) dst[n][k] = *(const LAS bf16x8*)(lds + PG8_SB(b, h) + boff + n * 2048 + k * 1024); } while (0)
; #define PG8_MMA(ai, bj, At, Bt) do { __builtin_amdgcn_s_setprio(1); _Pragma("unroll") for (int m = 0; m < 4; ++m) _Pragma("unroll") for (int n = 0; n < 2; ++n) _Pragma("unroll") for (int k = 0; k < 2; ++k) \
;         acc[ai][bj][m][n] = __builtin_amdgcn_mfma_f32_16x16x32_bf16(Bt[n][k], At[m][k], acc[ai][bj][m][n], 0, 0, 0); __builtin_amdgcn_s_setprio(0); } while (0)
; #define PG8_WAIT_V(n) asm volatile("s_waitcnt vmcnt(" #n ")" ::: "memory")
; #define PG8_WAIT_L(n) asm volatile("s_waitcnt lgkmcnt(" #n ")" ::: "memory")
; #define PG8_BAR __builtin_amdgcn_s_barrier()
; #define PG8_SCHED __builtin_amdgcn_sched_barrier(0)
; template <class Epi>
; __device__ __forceinline__ void gemm_phase(LAS unsigned char* lds, const Gemm g, const Sched& S, const Epi& E) {
;     ...
;         for (int t = 0; t < nt; t += 2) {
;             const bool last = (t == nt - 2);
;             const char* a1 = cA + (size_t)(t + 1) * kstep;
;             const char* a2 = last ? nA : cA + (size_t)(t + 2) * kstep; const char* b2 = last ? nB : cB + (size_t)(t + 2) * kstep;
;             const char* a3 = a2 + kstep; const char* b3 = b2 + kstep;
;             PG8_LDB(B0, 0, 0); PG8_LDB(B1, 0, 1); PG8_SCHED; PG8_LDA(At, 0, 0); PG8_STAGE(PG8_SA(1, 1), a1 + hstepA, voffA);
;             PG8_WAIT_V(8); PG8_WAIT_L(0); PG8_BAR; PG8_MMA(0, 0, At, B0); PG8_MMA(0, 1, At, B1); PG8_BAR; PG8_SCHED;
;             PG8_LDA(At, 0, 1); PG8_STAGE(PG8_SB(0, 0), b2, voffB); PG8_STAGE(PG8_SB(0, 1), b2 + hstepB, voffB); PG8_STAGE(PG8_SA(0, 0), a2, voffA);
;             PG8_WAIT_V(8); PG8_WAIT_L(0); PG8_BAR; PG8_MMA(1, 0, At, B0); PG8_MMA(1, 1, At, B1); PG8_BAR; PG8_SCHED;
.LBB0_677:
	s_add_u32 s38, s38, 0xb0080
	s_addc_u32 s39, s39, 0
	s_add_u32 s85, s40, 0x100
	s_addc_u32 s86, s41, 0
	s_mov_b32 s87, -2
	s_waitcnt lgkmcnt(0)
	s_waitcnt lgkmcnt(0)
	v_readfirstlane_b32 s100, v0
	s_lshr_b32 s100, s100, 8
	s_cmp_eq_u32 s100, 0
	s_cbranch_scc0 .Lprio_1
	s_setprio 1
.Lprio_1:
.LBB0_678:
	ds_read_b128 v[118:121], v214
	ds_read_b128 v[126:129], v214 offset:1024
	ds_read_b128 v[138:141], v214 offset:2048
	ds_read_b128 v[142:145], v214 offset:3072
	ds_read_b128 v[146:149], v215
	ds_read_b128 v[150:153], v215 offset:1024
	ds_read_b128 v[154:157], v215 offset:2048
	ds_read_b128 v[158:161], v215 offset:3072
	s_add_u32 s40, s38, 0xfff50080
	s_addc_u32 s41, s39, -1
	s_cmp_eq_u32 s87, 40
	s_cselect_b32 s53, s9, s41
	s_cselect_b32 s52, s8, s40
	s_cselect_b32 s41, s35, s86
	s_cselect_b32 s40, s34, s85
	v_lshl_add_u64 v[222:223], s[38:39], 0, v[196:197]
	s_add_i32 m0, s24, 0xc000
	ds_read_b128 v[162:165], v216
	ds_read_b128 v[166:169], v216 offset:1024
	ds_read_b128 v[170:173], v216 offset:2048
	ds_read_b128 v[174:177], v216 offset:3072
	ds_read_b128 v[178:181], v216 offset:4096
	ds_read_b128 v[182:185], v216 offset:5120
	ds_read_b128 v[206:209], v216 offset:6144
	ds_read_b128 v[218:221], v216 offset:7168
	global_load_lds_dwordx4 v[222:223], off
	v_lshl_add_u64 v[222:223], s[38:39], 0, v[200:201]
	s_add_i32 m0, s24, 0xe000
	s_nop 0
	global_load_lds_dwordx4 v[222:223], off
	s_waitcnt vmcnt(8)
	s_waitcnt lgkmcnt(0)
	s_cmp_eq_u32 s87, -2
	s_cbranch_scc1 .Lcz_p2_0
	s_barrier
	s_waitcnt lgkmcnt(0)
	v_mfma_f32_16x16x32_bf16 v[134:137], v[118:121], v[162:165], v[134:137]
	v_mfma_f32_16x16x32_bf16 v[130:133], v[138:141], v[162:165], v[130:133]
	v_mfma_f32_16x16x32_bf16 v[110:113], v[118:121], v[170:173], v[110:113]
	v_mfma_f32_16x16x32_bf16 v[106:109], v[138:141], v[170:173], v[106:109]
	v_mfma_f32_16x16x32_bf16 v[94:97], v[118:121], v[178:181], v[94:97]
	v_mfma_f32_16x16x32_bf16 v[90:93], v[138:141], v[178:181], v[90:93]
	v_mfma_f32_16x16x32_bf16 v[78:81], v[118:121], v[206:209], v[78:81]
	v_mfma_f32_16x16x32_bf16 v[74:77], v[138:141], v[206:209], v[74:77]
	v_mfma_f32_16x16x32_bf16 v[134:137], v[126:129], v[166:169], v[134:137]
	v_mfma_f32_16x16x32_bf16 v[130:133], v[142:145], v[166:169], v[130:133]
	v_mfma_f32_16x16x32_bf16 v[110:113], v[126:129], v[174:177], v[110:113]
	v_mfma_f32_16x16x32_bf16 v[106:109], v[142:145], v[174:177], v[106:109]
	v_mfma_f32_16x16x32_bf16 v[94:97], v[126:129], v[182:185], v[94:97]
	v_mfma_f32_16x16x32_bf16 v[90:93], v[142:145], v[182:185], v[90:93]
	v_mfma_f32_16x16x32_bf16 v[78:81], v[126:129], v[218:221], v[78:81]
	v_mfma_f32_16x16x32_bf16 v[74:77], v[142:145], v[218:221], v[74:77]
	v_mfma_f32_16x16x32_bf16 v[122:125], v[146:149], v[162:165], v[122:125]
	v_mfma_f32_16x16x32_bf16 v[114:117], v[154:157], v[162:165], v[114:117]
	v_mfma_f32_16x16x32_bf16 v[102:105], v[146:149], v[170:173], v[102:105]
	v_mfma_f32_16x16x32_bf16 v[98:101], v[154:157], v[170:173], v[98:101]
	v_mfma_f32_16x16x32_bf16 v[86:89], v[146:149], v[178:181], v[86:89]
	v_mfma_f32_16x16x32_bf16 v[82:85], v[154:157], v[178:181], v[82:85]
	v_mfma_f32_16x16x32_bf16 v[70:73], v[146:149], v[206:209], v[70:73]
	v_mfma_f32_16x16x32_bf16 v[66:69], v[154:157], v[206:209], v[66:69]
	v_mfma_f32_16x16x32_bf16 v[122:125], v[150:153], v[166:169], v[122:125]
	v_mfma_f32_16x16x32_bf16 v[114:117], v[158:161], v[166:169], v[114:117]
	v_mfma_f32_16x16x32_bf16 v[102:105], v[150:153], v[174:177], v[102:105]
	v_mfma_f32_16x16x32_bf16 v[98:101], v[158:161], v[174:177], v[98:101]
	v_mfma_f32_16x16x32_bf16 v[86:89], v[150:153], v[182:185], v[86:89]
	v_mfma_f32_16x16x32_bf16 v[82:85], v[158:161], v[182:185], v[82:85]
	v_mfma_f32_16x16x32_bf16 v[70:73], v[150:153], v[218:221], v[70:73]
	v_mfma_f32_16x16x32_bf16 v[66:69], v[158:161], v[218:221], v[66:69]
.Lcz_p2_0_j:
	s_barrier
	s_add_i32 s88, s77, s3
	v_lshl_add_u64 v[222:223], s[40:41], 0, v[188:189]
	s_mov_b32 m0, s88
	ds_read_b128 v[162:165], v216 offset:16384
	ds_read_b128 v[166:169], v216 offset:17408
	ds_read_b128 v[170:173], v216 offset:18432
	ds_read_b128 v[174:177], v216 offset:19456
	ds_read_b128 v[178:181], v216 offset:20480
	ds_read_b128 v[182:185], v216 offset:21504
	ds_read_b128 v[206:209], v216 offset:22528
	ds_read_b128 v[218:221], v216 offset:23552
	global_load_lds_dwordx4 v[222:223], off
	s_add_i32 m0, s88, 0x2000
	s_add_u32 s88, s40, 0xb0000
	v_lshl_add_u64 v[224:225], s[40:41], 0, v[192:193]
	s_addc_u32 s89, s41, 0
	s_add_i32 s90, s78, s3
	global_load_lds_dwordx4 v[224:225], off
	v_lshl_add_u64 v[226:227], s[88:89], 0, v[188:189]
	s_mov_b32 m0, s90
	v_lshl_add_u64 v[228:229], s[52:53], 0, v[190:191]
	global_load_lds_dwordx4 v[226:227], off
	v_lshl_add_u64 v[226:227], s[88:89], 0, v[192:193]
	s_add_i32 m0, s90, 0x2000
	s_nop 0
	global_load_lds_dwordx4 v[226:227], off
	v_lshl_add_u64 v[226:227], s[52:53], 0, v[186:187]
	s_mov_b32 m0, s24
	s_nop 0
	global_load_lds_dwordx4 v[226:227], off
	s_mov_b32 m0, s25
	s_nop 0
	global_load_lds_dwordx4 v[228:229], off
	s_waitcnt vmcnt(8)
	s_waitcnt lgkmcnt(0)
	s_cmp_eq_u32 s87, -2
	s_cbranch_scc1 .Lcz_p2_1
	s_barrier
; #define PG8_STAGE(bufoff, gbase, voff) do { _Pragma("unroll") for (int _i = 0; _i < 2; ++_i) \
;         __builtin_amdgcn_global_load_lds((const unsigned*)((const char*)(gbase) + (voff)[_i]), (LAS unsigned*)(lds + (bufoff) + ldsw + _i * 8192), 16, 0, 0); } while (0)
; #define PG8_LDA(dst, b, h) do { _Pragma("unroll") for (int m = 0; m < 4; ++m) _Pragma("unroll") for (int k = 0; k < 2; ++k) dst[m][k] = *(const LAS bf16x8*)(lds + PG8_SA(b, h) + aoff + m * 2048 + k * 1024); } while (0)
; #define PG8_LDB(dst, b, h) do { _Pragma("unroll") for (int n = 0; n < 2; ++n) _Pragma("unroll") for (int k = 0; k < 2; ++k) dst[n][k] = *(const LAS bf16x8*)(lds + PG8_SB(b, h) + boff + n * 2048 + k * 1024); } while (0)
; #define PG8_MMA(ai, bj, At, Bt) do { __builtin_amdgcn_s_setprio(1); _Pragma("unroll") for (int m = 0; m < 4; ++m) _Pragma("unroll") for (int n = 0; n < 2; ++n) _Pragma("unroll") for (int k = 0; k < 2; ++k) \
;         acc[ai][bj][m][n] = __builtin_amdgcn_mfma_f32_16x16x32_bf16(Bt[n][k], At[m][k], acc[ai][bj][m][n], 0, 0, 0); __builtin_amdgcn_s_setprio(0); } while (0)
; #define PG8_WAIT_V(n) asm volatile("s_waitcnt vmcnt(" #n ")" ::: "memory")
; #define PG8_WAIT_L(n) asm volatile("s_waitcnt lgkmcnt(" #n ")" ::: "memory")
; #define PG8_BAR __builtin_amdgcn_s_barrier()
; #define PG8_SCHED __builtin_amdgcn_sched_barrier(0)
; template <class Epi>
; __device__ __forceinline__ void gemm_phase(LAS unsigned char* lds, const Gemm g, const Sched& S, const Epi& E) {
;     ...
;             PG8_WAIT_V(8); PG8_WAIT_L(0); PG8_BAR; PG8_MMA(1, 0, At, B0); PG8_MMA(1, 1, At, B1); PG8_BAR; PG8_SCHED;
;             PG8_LDB(B0, 1, 0); PG8_LDB(B1, 1, 1); PG8_SCHED; PG8_LDA(At, 1, 0); PG8_STAGE(PG8_SA(0, 1), a2 + hstepA, voffA);
;             PG8_WAIT_V(8); PG8_WAIT_L(0); PG8_BAR; PG8_MMA(0, 0, At, B0); PG8_MMA(0, 1, At, B1); PG8_BAR; PG8_SCHED;
	s_waitcnt lgkmcnt(0)
	v_mfma_f32_16x16x32_bf16 v[62:65], v[118:121], v[162:165], v[62:65]
	v_mfma_f32_16x16x32_bf16 v[58:61], v[138:141], v[162:165], v[58:61]
	v_mfma_f32_16x16x32_bf16 v[46:49], v[118:121], v[170:173], v[46:49]
	v_mfma_f32_16x16x32_bf16 v[42:45], v[138:141], v[170:173], v[42:45]
	v_mfma_f32_16x16x32_bf16 v[30:33], v[118:121], v[178:181], v[30:33]
	v_mfma_f32_16x16x32_bf16 v[26:29], v[138:141], v[178:181], v[26:29]
	v_mfma_f32_16x16x32_bf16 v[14:17], v[118:121], v[206:209], v[14:17]
	v_mfma_f32_16x16x32_bf16 v[10:13], v[138:141], v[206:209], v[10:13]
	v_mfma_f32_16x16x32_bf16 v[62:65], v[126:129], v[166:169], v[62:65]
	v_mfma_f32_16x16x32_bf16 v[58:61], v[142:145], v[166:169], v[58:61]
	v_mfma_f32_16x16x32_bf16 v[46:49], v[126:129], v[174:177], v[46:49]
	v_mfma_f32_16x16x32_bf16 v[42:45], v[142:145], v[174:177], v[42:45]
	v_mfma_f32_16x16x32_bf16 v[30:33], v[126:129], v[182:185], v[30:33]
	v_mfma_f32_16x16x32_bf16 v[26:29], v[142:145], v[182:185], v[26:29]
	v_mfma_f32_16x16x32_bf16 v[14:17], v[126:129], v[218:221], v[14:17]
	v_mfma_f32_16x16x32_bf16 v[10:13], v[142:145], v[218:221], v[10:13]
	v_mfma_f32_16x16x32_bf16 v[54:57], v[146:149], v[162:165], v[54:57]
	v_mfma_f32_16x16x32_bf16 v[50:53], v[154:157], v[162:165], v[50:53]
	v_mfma_f32_16x16x32_bf16 v[38:41], v[146:149], v[170:173], v[38:41]
	v_mfma_f32_16x16x32_bf16 v[34:37], v[154:157], v[170:173], v[34:37]
	v_mfma_f32_16x16x32_bf16 v[22:25], v[146:149], v[178:181], v[22:25]
	v_mfma_f32_16x16x32_bf16 v[18:21], v[154:157], v[178:181], v[18:21]
	v_mfma_f32_16x16x32_bf16 v[6:9], v[146:149], v[206:209], v[6:9]
	v_mfma_f32_16x16x32_bf16 v[2:5], v[154:157], v[206:209], v[2:5]
	v_mfma_f32_16x16x32_bf16 v[54:57], v[150:153], v[166:169], v[54:57]
	v_mfma_f32_16x16x32_bf16 v[50:53], v[158:161], v[166:169], v[50:53]
	v_mfma_f32_16x16x32_bf16 v[38:41], v[150:153], v[174:177], v[38:41]
	v_mfma_f32_16x16x32_bf16 v[34:37], v[158:161], v[174:177], v[34:37]
	v_mfma_f32_16x16x32_bf16 v[22:25], v[150:153], v[182:185], v[22:25]
	v_mfma_f32_16x16x32_bf16 v[18:21], v[158:161], v[182:185], v[18:21]
	v_mfma_f32_16x16x32_bf16 v[6:9], v[150:153], v[218:221], v[6:9]
	v_mfma_f32_16x16x32_bf16 v[2:5], v[158:161], v[218:221], v[2:5]
.Lcz_p2_1_j:
	s_barrier
	s_add_i32 s88, 0, 0x18000
	s_add_i32 s89, 0, 0x1c000
	v_add_u32_e32 v142, s88, v213
	v_add_u32_e32 v158, s89, v213
	ds_read_b128 v[118:121], v142
	ds_read_b128 v[126:129], v142 offset:1024
	ds_read_b128 v[138:141], v142 offset:2048
	ds_read_b128 v[142:145], v142 offset:3072
	ds_read_b128 v[146:149], v158
	ds_read_b128 v[150:153], v158 offset:1024
	ds_read_b128 v[154:157], v158 offset:2048
	ds_read_b128 v[158:161], v158 offset:3072
	s_add_u32 s52, s52, 0xb0000
	s_addc_u32 s53, s53, 0
	s_mov_b32 m0, s33
	v_lshl_add_u64 v[230:231], s[52:53], 0, v[186:187]
	ds_read_b128 v[162:165], v216 offset:32768
	ds_read_b128 v[166:169], v216 offset:33792
	ds_read_b128 v[170:173], v216 offset:34816
	ds_read_b128 v[174:177], v216 offset:35840
	ds_read_b128 v[178:181], v216 offset:36864
	ds_read_b128 v[182:185], v216 offset:37888
	ds_read_b128 v[206:209], v216 offset:38912
	ds_read_b128 v[218:221], v216 offset:39936
	global_load_lds_dwordx4 v[230:231], off
	v_lshl_add_u64 v[230:231], s[52:53], 0, v[190:191]
	s_mov_b32 m0, s54
	s_nop 0
	global_load_lds_dwordx4 v[230:231], off
	s_waitcnt vmcnt(8)
	s_waitcnt lgkmcnt(0)
	s_barrier
	s_waitcnt lgkmcnt(0)
	v_mfma_f32_16x16x32_bf16 v[134:137], v[118:121], v[162:165], v[134:137]
	v_mfma_f32_16x16x32_bf16 v[130:133], v[138:141], v[162:165], v[130:133]
	v_mfma_f32_16x16x32_bf16 v[110:113], v[118:121], v[170:173], v[110:113]
	v_mfma_f32_16x16x32_bf16 v[106:109], v[138:141], v[170:173], v[106:109]
	v_mfma_f32_16x16x32_bf16 v[94:97], v[118:121], v[178:181], v[94:97]
	v_mfma_f32_16x16x32_bf16 v[90:93], v[138:141], v[178:181], v[90:93]
	v_mfma_f32_16x16x32_bf16 v[78:81], v[118:121], v[206:209], v[78:81]
	v_mfma_f32_16x16x32_bf16 v[74:77], v[138:141], v[206:209], v[74:77]
	v_mfma_f32_16x16x32_bf16 v[134:137], v[126:129], v[166:169], v[134:137]
	v_mfma_f32_16x16x32_bf16 v[130:133], v[142:145], v[166:169], v[130:133]
	v_mfma_f32_16x16x32_bf16 v[110:113], v[126:129], v[174:177], v[110:113]
	v_mfma_f32_16x16x32_bf16 v[106:109], v[142:145], v[174:177], v[106:109]
	v_mfma_f32_16x16x32_bf16 v[94:97], v[126:129], v[182:185], v[94:97]
	v_mfma_f32_16x16x32_bf16 v[90:93], v[142:145], v[182:185], v[90:93]
	v_mfma_f32_16x16x32_bf16 v[78:81], v[126:129], v[218:221], v[78:81]
	v_mfma_f32_16x16x32_bf16 v[74:77], v[142:145], v[218:221], v[74:77]
	v_mfma_f32_16x16x32_bf16 v[122:125], v[146:149], v[162:165], v[122:125]
	v_mfma_f32_16x16x32_bf16 v[114:117], v[154:157], v[162:165], v[114:117]
	v_mfma_f32_16x16x32_bf16 v[102:105], v[146:149], v[170:173], v[102:105]
	v_mfma_f32_16x16x32_bf16 v[98:101], v[154:157], v[170:173], v[98:101]
	v_mfma_f32_16x16x32_bf16 v[86:89], v[146:149], v[178:181], v[86:89]
	v_mfma_f32_16x16x32_bf16 v[82:85], v[154:157], v[178:181], v[82:85]
	v_mfma_f32_16x16x32_bf16 v[70:73], v[146:149], v[206:209], v[70:73]
	v_mfma_f32_16x16x32_bf16 v[66:69], v[154:157], v[206:209], v[66:69]
	v_mfma_f32_16x16x32_bf16 v[122:125], v[150:153], v[166:169], v[122:125]
	v_mfma_f32_16x16x32_bf16 v[114:117], v[158:161], v[166:169], v[114:117]
	v_mfma_f32_16x16x32_bf16 v[102:105], v[150:153], v[174:177], v[102:105]
	v_mfma_f32_16x16x32_bf16 v[98:101], v[158:161], v[174:177], v[98:101]
	v_mfma_f32_16x16x32_bf16 v[86:89], v[150:153], v[182:185], v[86:89]
	v_mfma_f32_16x16x32_bf16 v[82:85], v[158:161], v[182:185], v[82:85]
	v_mfma_f32_16x16x32_bf16 v[70:73], v[150:153], v[218:221], v[70:73]
	v_mfma_f32_16x16x32_bf16 v[66:69], v[158:161], v[218:221], v[66:69]
	s_barrier
; #define PG8_STAGE(bufoff, gbase, voff) do { _Pragma("unroll") for (int _i = 0; _i < 2; ++_i) \
;         __builtin_amdgcn_global_load_lds((const unsigned*)((const char*)(gbase) + (voff)[_i]), (LAS unsigned*)(lds + (bufoff) + ldsw + _i * 8192), 16, 0, 0); } while (0)
; #define PG8_LDA(dst, b, h) do { _Pragma("unroll") for (int m = 0; m < 4; ++m) _Pragma("unroll") for (int k = 0; k < 2; ++k) dst[m][k] = *(const LAS bf16x8*)(lds + PG8_SA(b, h) + aoff + m * 2048 + k * 1024); } while (0)
; #define PG8_MMA(ai, bj, At, Bt) do { __builtin_amdgcn_s_setprio(1); _Pragma("unroll") for (int m = 0; m < 4; ++m) _Pragma("unroll") for (int n = 0; n < 2; ++n) _Pragma("unroll") for (int k = 0; k < 2; ++k) \
;         acc[ai][bj][m][n] = __builtin_amdgcn_mfma_f32_16x16x32_bf16(Bt[n][k], At[m][k], acc[ai][bj][m][n], 0, 0, 0); __builtin_amdgcn_s_setprio(0); } while (0)
; #define PG8_WAIT_V(n) asm volatile("s_waitcnt vmcnt(" #n ")" ::: "memory")
; #define PG8_WAIT_L(n) asm volatile("s_waitcnt lgkmcnt(" #n ")" ::: "memory")
; #define PG8_BAR __builtin_amdgcn_s_barrier()
; #define PG8_SCHED __builtin_amdgcn_sched_barrier(0)
; template <class Epi>
; __device__ __forceinline__ void gemm_phase(LAS unsigned char* lds, const Gemm g, const Sched& S, const Epi& E) {
;     ...
;             PG8_LDA(At, 1, 1); PG8_STAGE(PG8_SB(1, 0), b3, voffB); PG8_STAGE(PG8_SB(1, 1), b3 + hstepB, voffB); PG8_STAGE(PG8_SA(1, 0), a3, voffA);
;             PG8_WAIT_V(8); PG8_WAIT_L(0); PG8_BAR; PG8_MMA(1, 0, At, B0); PG8_MMA(1, 1, At, B1); PG8_BAR; PG8_SCHED;
;         }
	s_add_i32 s52, s88, s3
	v_lshl_add_u64 v[222:223], v[222:223], 0, s[28:29]
	s_mov_b32 m0, s52
	ds_read_b128 v[162:165], v216 offset:49152
	ds_read_b128 v[166:169], v216 offset:50176
	ds_read_b128 v[170:173], v216 offset:51200
	ds_read_b128 v[174:177], v216 offset:52224
	ds_read_b128 v[178:181], v216 offset:53248
	ds_read_b128 v[182:185], v216 offset:54272
	ds_read_b128 v[206:209], v216 offset:55296
	ds_read_b128 v[218:221], v216 offset:56320
	global_load_lds_dwordx4 v[222:223], off
	s_add_i32 m0, s52, 0x2000
	s_add_u32 s40, s40, 0xb0080
	v_lshl_add_u64 v[222:223], v[224:225], 0, s[28:29]
	s_addc_u32 s41, s41, 0
	s_add_i32 s52, s89, s3
	global_load_lds_dwordx4 v[222:223], off
	v_lshl_add_u64 v[222:223], s[40:41], 0, v[188:189]
	s_mov_b32 m0, s52
	s_nop 0
	global_load_lds_dwordx4 v[222:223], off
	v_lshl_add_u64 v[222:223], s[40:41], 0, v[192:193]
	s_add_i32 m0, s52, 0x2000
	s_nop 0
	global_load_lds_dwordx4 v[222:223], off
	v_lshl_add_u64 v[222:223], v[226:227], 0, s[28:29]
	s_mov_b32 m0, s72
	s_nop 0
	global_load_lds_dwordx4 v[222:223], off
	v_lshl_add_u64 v[222:223], v[228:229], 0, s[28:29]
	s_mov_b32 m0, s73
	s_nop 0
	global_load_lds_dwordx4 v[222:223], off
	s_waitcnt vmcnt(8)
	s_waitcnt lgkmcnt(0)
	s_barrier
	s_waitcnt lgkmcnt(0)
	v_mfma_f32_16x16x32_bf16 v[62:65], v[118:121], v[162:165], v[62:65]
	v_mfma_f32_16x16x32_bf16 v[58:61], v[138:141], v[162:165], v[58:61]
	v_mfma_f32_16x16x32_bf16 v[46:49], v[118:121], v[170:173], v[46:49]
	v_mfma_f32_16x16x32_bf16 v[42:45], v[138:141], v[170:173], v[42:45]
	v_mfma_f32_16x16x32_bf16 v[30:33], v[118:121], v[178:181], v[30:33]
	v_mfma_f32_16x16x32_bf16 v[26:29], v[138:141], v[178:181], v[26:29]
	v_mfma_f32_16x16x32_bf16 v[14:17], v[118:121], v[206:209], v[14:17]
	v_mfma_f32_16x16x32_bf16 v[10:13], v[138:141], v[206:209], v[10:13]
	v_mfma_f32_16x16x32_bf16 v[62:65], v[126:129], v[166:169], v[62:65]
	v_mfma_f32_16x16x32_bf16 v[58:61], v[142:145], v[166:169], v[58:61]
	v_mfma_f32_16x16x32_bf16 v[46:49], v[126:129], v[174:177], v[46:49]
	v_mfma_f32_16x16x32_bf16 v[42:45], v[142:145], v[174:177], v[42:45]
	v_mfma_f32_16x16x32_bf16 v[30:33], v[126:129], v[182:185], v[30:33]
	v_mfma_f32_16x16x32_bf16 v[26:29], v[142:145], v[182:185], v[26:29]
	v_mfma_f32_16x16x32_bf16 v[14:17], v[126:129], v[218:221], v[14:17]
	v_mfma_f32_16x16x32_bf16 v[10:13], v[142:145], v[218:221], v[10:13]
	v_mfma_f32_16x16x32_bf16 v[54:57], v[146:149], v[162:165], v[54:57]
	v_mfma_f32_16x16x32_bf16 v[50:53], v[154:157], v[162:165], v[50:53]
	v_mfma_f32_16x16x32_bf16 v[38:41], v[146:149], v[170:173], v[38:41]
	v_mfma_f32_16x16x32_bf16 v[34:37], v[154:157], v[170:173], v[34:37]
	v_mfma_f32_16x16x32_bf16 v[22:25], v[146:149], v[178:181], v[22:25]
	v_mfma_f32_16x16x32_bf16 v[18:21], v[154:157], v[178:181], v[18:21]
	v_mfma_f32_16x16x32_bf16 v[6:9], v[146:149], v[206:209], v[6:9]
	v_mfma_f32_16x16x32_bf16 v[2:5], v[154:157], v[206:209], v[2:5]
	v_mfma_f32_16x16x32_bf16 v[54:57], v[150:153], v[166:169], v[54:57]
	v_mfma_f32_16x16x32_bf16 v[50:53], v[158:161], v[166:169], v[50:53]
	v_mfma_f32_16x16x32_bf16 v[38:41], v[150:153], v[174:177], v[38:41]
	v_mfma_f32_16x16x32_bf16 v[34:37], v[158:161], v[174:177], v[34:37]
	v_mfma_f32_16x16x32_bf16 v[22:25], v[150:153], v[182:185], v[22:25]
	v_mfma_f32_16x16x32_bf16 v[18:21], v[158:161], v[182:185], v[18:21]
	v_mfma_f32_16x16x32_bf16 v[6:9], v[150:153], v[218:221], v[6:9]
	v_mfma_f32_16x16x32_bf16 v[2:5], v[158:161], v[218:221], v[2:5]
	s_barrier
	s_add_i32 s87, s87, 2
	s_add_u32 s38, s38, 0x100
	s_addc_u32 s39, s39, 0
	s_add_u32 s85, s85, 0x100
	s_addc_u32 s86, s86, 0
	s_cmp_gt_u32 s87, 41
	s_cbranch_scc0 .LBB0_678
	s_and_b64 vcc, exec, s[30:31]
	s_cbranch_vccz .LBB0_681
	s_barrier

; #define PG8_STAGE(bufoff, gbase, voff) do { _Pragma("unroll") for (int _i = 0; _i < 2; ++_i) \
;         __builtin_amdgcn_global_load_lds((const unsigned*)((const char*)(gbase) + (voff)[_i]), (LAS unsigned*)(lds + (bufoff) + ldsw + _i * 8192), 16, 0, 0); } while (0)
; #define PG8_LDA(dst, b, h) do { _Pragma("unroll") for (int m = 0; m < 4; ++m) _Pragma("unroll") for (int k = 0; k < 2; ++k) dst[m][k] = *(const LAS bf16x8*)(lds + PG8_SA(b, h) + aoff + m * 2048 + k * 1024); } while (0)
; #define PG8_MMA(ai, bj, At, Bt) do { __builtin_amdgcn_s_setprio(1); _Pragma("unroll") for (int m = 0; m < 4; ++m) _Pragma("unroll") for (int n = 0; n < 2; ++n) _Pragma("unroll") for (int k = 0; k < 2; ++k) \
;         acc[ai][bj][m][n] = __builtin_amdgcn_mfma_f32_16x16x32_bf16(Bt[n][k], At[m][k], acc[ai][bj][m][n], 0, 0, 0); __builtin_amdgcn_s_setprio(0); } while (0)
; #define PG8_WAIT_V(n) asm volatile("s_waitcnt vmcnt(" #n ")" ::: "memory")
; #define PG8_WAIT_L(n) asm volatile("s_waitcnt lgkmcnt(" #n ")" ::: "memory")
; #define PG8_BAR __builtin_amdgcn_s_barrier()
; #define PG8_SCHED __builtin_amdgcn_sched_barrier(0)
; template <class Epi>
; __device__ __forceinline__ void gemm_phase(LAS unsigned char* lds, const Gemm g, const Sched& S, const Epi& E) {
;     ...
;                 for (int n = 0; n < 2; ++n) acc[a][b][m][n] = (f32x4){0.f, 0.f, 0.f, 0.f};
;     ...
;             PG8_WAIT_V(8); PG8_WAIT_L(0); PG8_BAR; PG8_MMA(0, 0, At, B0); PG8_MMA(0, 1, At, B1); PG8_BAR; PG8_SCHED;
;             PG8_LDA(At, 0, 1); PG8_STAGE(PG8_SB(0, 0), b2, voffB); PG8_STAGE(PG8_SB(0, 1), b2 + hstepB, voffB); PG8_STAGE(PG8_SA(0, 0), a2, voffA);
;             PG8_WAIT_V(8); PG8_WAIT_L(0); PG8_BAR; PG8_MMA(1, 0, At, B0); PG8_MMA(1, 1, At, B1); PG8_BAR; PG8_SCHED;
.Lcz_p2_0:
	s_barrier
	s_waitcnt lgkmcnt(0)
	v_mfma_f32_16x16x32_bf16 v[134:137], v[118:121], v[162:165], 0
	v_mfma_f32_16x16x32_bf16 v[130:133], v[138:141], v[162:165], 0
	v_mfma_f32_16x16x32_bf16 v[110:113], v[118:121], v[170:173], 0
	v_mfma_f32_16x16x32_bf16 v[106:109], v[138:141], v[170:173], 0
	v_mfma_f32_16x16x32_bf16 v[94:97], v[118:121], v[178:181], 0
	v_mfma_f32_16x16x32_bf16 v[90:93], v[138:141], v[178:181], 0
	v_mfma_f32_16x16x32_bf16 v[78:81], v[118:121], v[206:209], 0
	v_mfma_f32_16x16x32_bf16 v[74:77], v[138:141], v[206:209], 0
	v_mfma_f32_16x16x32_bf16 v[134:137], v[126:129], v[166:169], v[134:137]
	v_mfma_f32_16x16x32_bf16 v[130:133], v[142:145], v[166:169], v[130:133]
	v_mfma_f32_16x16x32_bf16 v[110:113], v[126:129], v[174:177], v[110:113]
	v_mfma_f32_16x16x32_bf16 v[106:109], v[142:145], v[174:177], v[106:109]
	v_mfma_f32_16x16x32_bf16 v[94:97], v[126:129], v[182:185], v[94:97]
	v_mfma_f32_16x16x32_bf16 v[90:93], v[142:145], v[182:185], v[90:93]
	v_mfma_f32_16x16x32_bf16 v[78:81], v[126:129], v[218:221], v[78:81]
	v_mfma_f32_16x16x32_bf16 v[74:77], v[142:145], v[218:221], v[74:77]
	v_mfma_f32_16x16x32_bf16 v[122:125], v[146:149], v[162:165], 0
	v_mfma_f32_16x16x32_bf16 v[114:117], v[154:157], v[162:165], 0
	v_mfma_f32_16x16x32_bf16 v[102:105], v[146:149], v[170:173], 0
	v_mfma_f32_16x16x32_bf16 v[98:101], v[154:157], v[170:173], 0
	v_mfma_f32_16x16x32_bf16 v[86:89], v[146:149], v[178:181], 0
	v_mfma_f32_16x16x32_bf16 v[82:85], v[154:157], v[178:181], 0
	v_mfma_f32_16x16x32_bf16 v[70:73], v[146:149], v[206:209], 0
	v_mfma_f32_16x16x32_bf16 v[66:69], v[154:157], v[206:209], 0
	v_mfma_f32_16x16x32_bf16 v[122:125], v[150:153], v[166:169], v[122:125]
	v_mfma_f32_16x16x32_bf16 v[114:117], v[158:161], v[166:169], v[114:117]
	v_mfma_f32_16x16x32_bf16 v[102:105], v[150:153], v[174:177], v[102:105]
	v_mfma_f32_16x16x32_bf16 v[98:101], v[158:161], v[174:177], v[98:101]
	v_mfma_f32_16x16x32_bf16 v[86:89], v[150:153], v[182:185], v[86:89]
	v_mfma_f32_16x16x32_bf16 v[82:85], v[158:161], v[182:185], v[82:85]
	v_mfma_f32_16x16x32_bf16 v[70:73], v[150:153], v[218:221], v[70:73]
	v_mfma_f32_16x16x32_bf16 v[66:69], v[158:161], v[218:221], v[66:69]
	s_branch .Lcz_p2_0_j
.Lcz_p2_1:
	s_barrier
	s_waitcnt lgkmcnt(0)
	v_mfma_f32_16x16x32_bf16 v[62:65], v[118:121], v[162:165], 0
	v_mfma_f32_16x16x32_bf16 v[58:61], v[138:141], v[162:165], 0
	v_mfma_f32_16x16x32_bf16 v[46:49], v[118:121], v[170:173], 0
	v_mfma_f32_16x16x32_bf16 v[42:45], v[138:141], v[170:173], 0
	v_mfma_f32_16x16x32_bf16 v[30:33], v[118:121], v[178:181], 0
	v_mfma_f32_16x16x32_bf16 v[26:29], v[138:141], v[178:181], 0
	v_mfma_f32_16x16x32_bf16 v[14:17], v[118:121], v[206:209], 0
	v_mfma_f32_16x16x32_bf16 v[10:13], v[138:141], v[206:209], 0
	v_mfma_f32_16x16x32_bf16 v[62:65], v[126:129], v[166:169], v[62:65]
	v_mfma_f32_16x16x32_bf16 v[58:61], v[142:145], v[166:169], v[58:61]
	v_mfma_f32_16x16x32_bf16 v[46:49], v[126:129], v[174:177], v[46:49]
	v_mfma_f32_16x16x32_bf16 v[42:45], v[142:145], v[174:177], v[42:45]
	v_mfma_f32_16x16x32_bf16 v[30:33], v[126:129], v[182:185], v[30:33]
	v_mfma_f32_16x16x32_bf16 v[26:29], v[142:145], v[182:185], v[26:29]
	v_mfma_f32_16x16x32_bf16 v[14:17], v[126:129], v[218:221], v[14:17]
	v_mfma_f32_16x16x32_bf16 v[10:13], v[142:145], v[218:221], v[10:13]
	v_mfma_f32_16x16x32_bf16 v[54:57], v[146:149], v[162:165], 0
	v_mfma_f32_16x16x32_bf16 v[50:53], v[154:157], v[162:165], 0
	v_mfma_f32_16x16x32_bf16 v[38:41], v[146:149], v[170:173], 0
	v_mfma_f32_16x16x32_bf16 v[34:37], v[154:157], v[170:173], 0
	v_mfma_f32_16x16x32_bf16 v[22:25], v[146:149], v[178:181], 0
	v_mfma_f32_16x16x32_bf16 v[18:21], v[154:157], v[178:181], 0
	v_mfma_f32_16x16x32_bf16 v[6:9], v[146:149], v[206:209], 0
	v_mfma_f32_16x16x32_bf16 v[2:5], v[154:157], v[206:209], 0
	v_mfma_f32_16x16x32_bf16 v[54:57], v[150:153], v[166:169], v[54:57]
	v_mfma_f32_16x16x32_bf16 v[50:53], v[158:161], v[166:169], v[50:53]
	v_mfma_f32_16x16x32_bf16 v[38:41], v[150:153], v[174:177], v[38:41]
	v_mfma_f32_16x16x32_bf16 v[34:37], v[158:161], v[174:177], v[34:37]
	v_mfma_f32_16x16x32_bf16 v[22:25], v[150:153], v[182:185], v[22:25]
	v_mfma_f32_16x16x32_bf16 v[18:21], v[158:161], v[182:185], v[18:21]
	v_mfma_f32_16x16x32_bf16 v[6:9], v[150:153], v[218:221], v[6:9]
	v_mfma_f32_16x16x32_bf16 v[2:5], v[158:161], v[218:221], v[2:5]
	s_branch .Lcz_p2_1_j

; __device__ __forceinline__ unsigned xb_ld(unsigned* p)              { return __hip_atomic_load(p, __ATOMIC_RELAXED, __HIP_MEMORY_SCOPE_AGENT); }
; __device__ __forceinline__ unsigned xb_add(unsigned* p, unsigned v) { return __hip_atomic_fetch_add(p, v, __ATOMIC_RELAXED, __HIP_MEMORY_SCOPE_AGENT); }
; #define XB_SPIN(cond, bar) do { unsigned _sp = 0; while (cond) { __builtin_amdgcn_s_sleep(1); \
;     if ((++_sp & 255u) == 0u) { if (xb_ld(&(bar)[XB_TMO])) break; if (_sp > XB_SPIN_CAP) { atomicAdd(&(bar)[XB_TMO], 1u); break; } } } } while (0)
; __device__ __forceinline__ void xcd_barrier(const XcdBarrier& b) {
;     asm volatile("s_waitcnt vmcnt(0)" ::: "memory");
;     __syncthreads();
;     if (threadIdx.x == 0) {
;         unsigned* bar = b.bar;
;         __builtin_amdgcn_s_waitcnt(0);
;         unsigned nloc = b.st[0], nx = b.st[1];
;         if (nloc == 0u) { xcd_barrier_complete(bar, b.x, nloc, nx); b.st[0] = nloc; b.st[1] = nx; }
;         const unsigned old = xb_add(&bar[XB_XSUB(b.x)], 1u);
;         const unsigned gen = old / nloc;
;         if (old + 1u == (gen + 1u) * nloc) {
;             __builtin_amdgcn_fence(__ATOMIC_RELEASE, "agent");
;             asm volatile("s_waitcnt vmcnt(0)" ::: "memory");
;             const unsigned og = xb_add(&bar[XB_TOP], 1u);
;             const unsigned tg = og / nx;
;             if (og + 1u == (tg + 1u) * nx) xb_add(&bar[XB_TOPGEN], 1u);
;             else XB_SPIN(xb_ld(&bar[XB_TOPGEN]) == tg, bar);
;             __builtin_amdgcn_fence(__ATOMIC_ACQUIRE, "agent");
;             xb_add(&bar[XB_XGEN(b.x)], 1u);
;             asm volatile("s_waitcnt vmcnt(0)" ::: "memory");
;         } else {
;             XB_SPIN(xb_ld(&bar[XB_XGEN(b.x)]) == gen, bar);
;             __builtin_amdgcn_fence(__ATOMIC_ACQUIRE, "agent");
;             asm volatile("s_waitcnt vmcnt(0)" ::: "memory");
;         }
;     }
;     __syncthreads();
; }
.LBB0_710:
	s_cmp_gt_i32 s95, 3
	s_cselect_b64 s[0:1], -1, 0
	s_and_b64 s[4:5], s[10:11], s[0:1]
	s_andn2_b64 vcc, exec, s[4:5]
	s_cbranch_vccnz .LBB0_760
	s_setprio 0
	s_waitcnt vmcnt(0) lgkmcnt(0)
	s_barrier
	v_readfirstlane_b32 s98, v0
	s_cmp_lg_u32 s98, 0
	s_cbranch_scc1 .Lxb2_end
	s_mov_b64 s[100:101], exec
	v_readlane_b32 s98, v253, 0
	s_cmp_lg_u32 s98, 0
	s_cbranch_scc1 .Lxb2_have
	s_mov_b64 exec, 0xffff
	v_mbcnt_lo_u32_b32 v254, -1, 0
	v_lshlrev_b32_e32 v254, 8, v254
	s_mov_b32 s99, 0
	v_writelane_b32 v253, s99, 3

; #define PG8_STAGE(bufoff, gbase, voff) do { _Pragma("unroll") for (int _i = 0; _i < 2; ++_i) \
;         __builtin_amdgcn_global_load_lds((const unsigned*)((const char*)(gbase) + (voff)[_i]), (LAS unsigned*)(lds + (bufoff) + ldsw + _i * 8192), 16, 0, 0); } while (0)
; #define PG8_LDA(dst, b, h) do { _Pragma("unroll") for (int m = 0; m < 4; ++m) _Pragma("unroll") for (int k = 0; k < 2; ++k) dst[m][k] = *(const LAS bf16x8*)(lds + PG8_SA(b, h) + aoff + m * 2048 + k * 1024); } while (0)
; #define PG8_LDB(dst, b, h) do { _Pragma("unroll") for (int n = 0; n < 2; ++n) _Pragma("unroll") for (int k = 0; k < 2; ++k) dst[n][k] = *(const LAS bf16x8*)(lds + PG8_SB(b, h) + boff + n * 2048 + k * 1024); } while (0)
; #define PG8_SCHED __builtin_amdgcn_sched_barrier(0)
; template <class Epi>
; __device__ __forceinline__ void gemm_phase(LAS unsigned char* lds, const Gemm g, const Sched& S, const Epi& E) {
;     ...
;         const bool has_next = S.next(ui + 1, nxt);
;         const char* nA = has_next ? (const char*)g.A + (size_t)nxt.pm * tstepA + (size_t)nxt.part * g.koff * 2 : cA; const char* nB = has_next ? (const char*)g.Bt + (size_t)nxt.pn * tstepB + (size_t)nxt.part * g.koff * 2 : cB;
;         for (int t = 0; t < nt; t += 2) {
;             const bool last = (t == nt - 2);
;             const char* a1 = cA + (size_t)(t + 1) * kstep;
;             const char* a2 = last ? nA : cA + (size_t)(t + 2) * kstep; const char* b2 = last ? nB : cB + (size_t)(t + 2) * kstep;
;             const char* a3 = a2 + kstep; const char* b3 = b2 + kstep;
;             PG8_LDB(B0, 0, 0); PG8_LDB(B1, 0, 1); PG8_SCHED; PG8_LDA(At, 0, 0); PG8_STAGE(PG8_SA(1, 1), a1 + hstepA, voffA);
.LBB0_821:
	s_ashr_i32 s55, s54, 31
	s_lshl_b64 s[20:21], s[54:55], 19
	s_add_u32 s42, s88, s20
	s_addc_u32 s43, s89, s21
	s_and_b64 s[20:21], s[0:1], exec
	s_cselect_b32 s25, s43, s5
	s_cselect_b32 s55, s42, s4
	s_ashr_i32 s77, s76, 31
	s_lshl_b64 s[20:21], s[76:77], 19
	v_readlane_b32 s44, v252, 3
	v_readlane_b32 s45, v252, 4
	s_add_u32 s44, s44, s20
	s_addc_u32 s45, s45, s21
	s_and_b64 s[20:21], s[0:1], exec
	s_cselect_b32 s72, s45, s7
	s_cselect_b32 s73, s44, s6
	s_add_u32 s4, s4, 0x40080
	s_addc_u32 s5, s5, 0
	s_add_u32 s74, s6, 0x100
	s_addc_u32 s75, s7, 0
	s_mov_b32 s77, -2
	v_readfirstlane_b32 s100, v0
	s_lshr_b32 s100, s100, 8
	s_cmp_eq_u32 s100, 0
	s_cbranch_scc0 .Lprio_2
	s_setprio 1
.Lprio_2:
.LBB0_822:
	ds_read_b128 v[130:133], v210
	ds_read_b128 v[134:137], v210 offset:1024
	ds_read_b128 v[138:141], v210 offset:2048
	ds_read_b128 v[142:145], v210 offset:3072
	ds_read_b128 v[146:149], v211
	ds_read_b128 v[150:153], v211 offset:1024
	ds_read_b128 v[180:183], v211 offset:2048
	ds_read_b128 v[184:187], v211 offset:3072
	s_add_u32 s6, s4, 0xfffc0080
	s_addc_u32 s7, s5, -1
	s_cmp_eq_u32 s77, 12
	s_cselect_b32 s21, s25, s7
	s_cselect_b32 s20, s55, s6
	s_cselect_b32 s7, s72, s75
	s_cselect_b32 s6, s73, s74
	v_lshl_add_u64 v[240:241], s[4:5], 0, v[172:173]
	s_add_i32 m0, s11, 0xc000
	ds_read_b128 v[188:191], v212
	ds_read_b128 v[192:195], v212 offset:1024
	ds_read_b128 v[216:219], v212 offset:2048
	ds_read_b128 v[220:223], v212 offset:3072
	ds_read_b128 v[224:227], v212 offset:4096
	ds_read_b128 v[228:231], v212 offset:5120
	ds_read_b128 v[232:235], v212 offset:6144
	ds_read_b128 v[236:239], v212 offset:7168
	s_cmp_eq_u32 s98, 3
	s_cbranch_scc1 .Lpi_p3_s
	global_load_lds_dwordx4 v[240:241], off
	v_lshl_add_u64 v[240:241], s[4:5], 0, v[174:175]
	s_add_i32 m0, s11, 0xe000
	s_nop 0
	global_load_lds_dwordx4 v[240:241], off

; #define PG8_STAGE(bufoff, gbase, voff) do { _Pragma("unroll") for (int _i = 0; _i < 2; ++_i) \
;         __builtin_amdgcn_global_load_lds((const unsigned*)((const char*)(gbase) + (voff)[_i]), (LAS unsigned*)(lds + (bufoff) + ldsw + _i * 8192), 16, 0, 0); } while (0)
; #define PG8_LDA(dst, b, h) do { _Pragma("unroll") for (int m = 0; m < 4; ++m) _Pragma("unroll") for (int k = 0; k < 2; ++k) dst[m][k] = *(const LAS bf16x8*)(lds + PG8_SA(b, h) + aoff + m * 2048 + k * 1024); } while (0)
; #define PG8_LDB(dst, b, h) do { _Pragma("unroll") for (int n = 0; n < 2; ++n) _Pragma("unroll") for (int k = 0; k < 2; ++k) dst[n][k] = *(const LAS bf16x8*)(lds + PG8_SB(b, h) + boff + n * 2048 + k * 1024); } while (0)
; #define PG8_MMA(ai, bj, At, Bt) do { __builtin_amdgcn_s_setprio(1); _Pragma("unroll") for (int m = 0; m < 4; ++m) _Pragma("unroll") for (int n = 0; n < 2; ++n) _Pragma("unroll") for (int k = 0; k < 2; ++k) \
;         acc[ai][bj][m][n] = __builtin_amdgcn_mfma_f32_16x16x32_bf16(Bt[n][k], At[m][k], acc[ai][bj][m][n], 0, 0, 0); __builtin_amdgcn_s_setprio(0); } while (0)
; #define PG8_WAIT_V(n) asm volatile("s_waitcnt vmcnt(" #n ")" ::: "memory")
; #define PG8_WAIT_L(n) asm volatile("s_waitcnt lgkmcnt(" #n ")" ::: "memory")
; #define PG8_BAR __builtin_amdgcn_s_barrier()
; #define PG8_SCHED __builtin_amdgcn_sched_barrier(0)
; template <class Epi>
; __device__ __forceinline__ void gemm_phase(LAS unsigned char* lds, const Gemm g, const Sched& S, const Epi& E) {
;     ...
;             PG8_LDB(B0, 0, 0); PG8_LDB(B1, 0, 1); PG8_SCHED; PG8_LDA(At, 0, 0); PG8_STAGE(PG8_SA(1, 1), a1 + hstepA, voffA);
;             PG8_WAIT_V(8); PG8_WAIT_L(0); PG8_BAR; PG8_MMA(0, 0, At, B0); PG8_MMA(0, 1, At, B1); PG8_BAR; PG8_SCHED;
;             PG8_LDA(At, 0, 1); PG8_STAGE(PG8_SB(0, 0), b2, voffB); PG8_STAGE(PG8_SB(0, 1), b2 + hstepB, voffB); PG8_STAGE(PG8_SA(0, 0), a2, voffA);
.Lrx_p3_0_j:
	s_waitcnt lgkmcnt(0)
	s_cmp_eq_u32 s77, -2
	s_cbranch_scc1 .Lcz_p3_0
	s_barrier
	s_waitcnt lgkmcnt(0)
	v_mfma_f32_16x16x32_bf16 v[126:129], v[130:133], v[188:191], v[126:129]
	v_mfma_f32_16x16x32_bf16 v[122:125], v[138:141], v[188:191], v[122:125]
	v_mfma_f32_16x16x32_bf16 v[110:113], v[130:133], v[216:219], v[110:113]
	v_mfma_f32_16x16x32_bf16 v[106:109], v[138:141], v[216:219], v[106:109]
	v_mfma_f32_16x16x32_bf16 v[94:97], v[130:133], v[224:227], v[94:97]
	v_mfma_f32_16x16x32_bf16 v[90:93], v[138:141], v[224:227], v[90:93]
	v_mfma_f32_16x16x32_bf16 v[78:81], v[130:133], v[232:235], v[78:81]
	v_mfma_f32_16x16x32_bf16 v[74:77], v[138:141], v[232:235], v[74:77]
	v_mfma_f32_16x16x32_bf16 v[126:129], v[134:137], v[192:195], v[126:129]
	v_mfma_f32_16x16x32_bf16 v[122:125], v[142:145], v[192:195], v[122:125]
	v_mfma_f32_16x16x32_bf16 v[110:113], v[134:137], v[220:223], v[110:113]
	v_mfma_f32_16x16x32_bf16 v[106:109], v[142:145], v[220:223], v[106:109]
	v_mfma_f32_16x16x32_bf16 v[94:97], v[134:137], v[228:231], v[94:97]
	v_mfma_f32_16x16x32_bf16 v[90:93], v[142:145], v[228:231], v[90:93]
	v_mfma_f32_16x16x32_bf16 v[78:81], v[134:137], v[236:239], v[78:81]
	v_mfma_f32_16x16x32_bf16 v[74:77], v[142:145], v[236:239], v[74:77]
	v_mfma_f32_16x16x32_bf16 v[118:121], v[146:149], v[188:191], v[118:121]
	v_mfma_f32_16x16x32_bf16 v[114:117], v[180:183], v[188:191], v[114:117]
	v_mfma_f32_16x16x32_bf16 v[102:105], v[146:149], v[216:219], v[102:105]
	v_mfma_f32_16x16x32_bf16 v[98:101], v[180:183], v[216:219], v[98:101]
	v_mfma_f32_16x16x32_bf16 v[86:89], v[146:149], v[224:227], v[86:89]
	v_mfma_f32_16x16x32_bf16 v[82:85], v[180:183], v[224:227], v[82:85]
	v_mfma_f32_16x16x32_bf16 v[70:73], v[146:149], v[232:235], v[70:73]
	v_mfma_f32_16x16x32_bf16 v[66:69], v[180:183], v[232:235], v[66:69]
	v_mfma_f32_16x16x32_bf16 v[118:121], v[150:153], v[192:195], v[118:121]
	v_mfma_f32_16x16x32_bf16 v[114:117], v[184:187], v[192:195], v[114:117]
	v_mfma_f32_16x16x32_bf16 v[102:105], v[150:153], v[220:223], v[102:105]
	v_mfma_f32_16x16x32_bf16 v[98:101], v[184:187], v[220:223], v[98:101]
	v_mfma_f32_16x16x32_bf16 v[86:89], v[150:153], v[228:231], v[86:89]
	v_mfma_f32_16x16x32_bf16 v[82:85], v[184:187], v[228:231], v[82:85]
	v_mfma_f32_16x16x32_bf16 v[70:73], v[150:153], v[236:239], v[70:73]
	v_mfma_f32_16x16x32_bf16 v[66:69], v[184:187], v[236:239], v[66:69]
.Lcz_p3_0_j:
	s_barrier
	s_add_i32 s82, s19, s78
	v_lshl_add_u64 v[240:241], s[6:7], 0, v[156:157]
	s_mov_b32 m0, s82
	ds_read_b128 v[188:191], v212 offset:16384
	ds_read_b128 v[192:195], v212 offset:17408
	ds_read_b128 v[216:219], v212 offset:18432
	ds_read_b128 v[220:223], v212 offset:19456
	ds_read_b128 v[224:227], v212 offset:20480
	ds_read_b128 v[228:231], v212 offset:21504
	ds_read_b128 v[232:235], v212 offset:22528
	ds_read_b128 v[236:239], v212 offset:23552
	global_load_lds_dwordx4 v[240:241], off
	s_add_i32 m0, s82, 0x2000
	s_add_u32 s82, s6, 0x40000
	v_lshl_add_u64 v[242:243], s[6:7], 0, v[160:161]
	s_addc_u32 s83, s7, 0
	s_add_i32 s86, s22, s78
	global_load_lds_dwordx4 v[242:243], off
	v_lshl_add_u64 v[244:245], s[82:83], 0, v[156:157]
	s_mov_b32 m0, s86
	v_lshl_add_u64 v[246:247], s[20:21], 0, v[158:159]
	global_load_lds_dwordx4 v[244:245], off
	v_lshl_add_u64 v[244:245], s[82:83], 0, v[160:161]
	s_add_i32 m0, s86, 0x2000
	s_nop 0
	global_load_lds_dwordx4 v[244:245], off
	v_lshl_add_u64 v[244:245], s[20:21], 0, v[154:155]
	s_mov_b32 m0, s11
	s_nop 0
	global_load_lds_dwordx4 v[244:245], off
	s_mov_b32 m0, s31
	s_nop 0
	global_load_lds_dwordx4 v[246:247], off
	s_cmp_eq_u32 s98, 0
	s_cbranch_scc1 .Lrx_p3_1_n
	s_sub_u32 s98, s98, 1
	s_waitcnt vmcnt(24)
	s_branch .Lrx_p3_1_j

; #define PG8_STAGE(bufoff, gbase, voff) do { _Pragma("unroll") for (int _i = 0; _i < 2; ++_i) \
;         __builtin_amdgcn_global_load_lds((const unsigned*)((const char*)(gbase) + (voff)[_i]), (LAS unsigned*)(lds + (bufoff) + ldsw + _i * 8192), 16, 0, 0); } while (0)
; #define PG8_LDA(dst, b, h) do { _Pragma("unroll") for (int m = 0; m < 4; ++m) _Pragma("unroll") for (int k = 0; k < 2; ++k) dst[m][k] = *(const LAS bf16x8*)(lds + PG8_SA(b, h) + aoff + m * 2048 + k * 1024); } while (0)
; #define PG8_LDB(dst, b, h) do { _Pragma("unroll") for (int n = 0; n < 2; ++n) _Pragma("unroll") for (int k = 0; k < 2; ++k) dst[n][k] = *(const LAS bf16x8*)(lds + PG8_SB(b, h) + boff + n * 2048 + k * 1024); } while (0)
; #define PG8_MMA(ai, bj, At, Bt) do { __builtin_amdgcn_s_setprio(1); _Pragma("unroll") for (int m = 0; m < 4; ++m) _Pragma("unroll") for (int n = 0; n < 2; ++n) _Pragma("unroll") for (int k = 0; k < 2; ++k) \
;         acc[ai][bj][m][n] = __builtin_amdgcn_mfma_f32_16x16x32_bf16(Bt[n][k], At[m][k], acc[ai][bj][m][n], 0, 0, 0); __builtin_amdgcn_s_setprio(0); } while (0)
; #define PG8_WAIT_V(n) asm volatile("s_waitcnt vmcnt(" #n ")" ::: "memory")
; #define PG8_WAIT_L(n) asm volatile("s_waitcnt lgkmcnt(" #n ")" ::: "memory")
; #define PG8_BAR __builtin_amdgcn_s_barrier()
; #define PG8_SCHED __builtin_amdgcn_sched_barrier(0)
; template <class Epi>
; __device__ __forceinline__ void gemm_phase(LAS unsigned char* lds, const Gemm g, const Sched& S, const Epi& E) {
;     ...
;             PG8_LDA(At, 0, 1); PG8_STAGE(PG8_SB(0, 0), b2, voffB); PG8_STAGE(PG8_SB(0, 1), b2 + hstepB, voffB); PG8_STAGE(PG8_SA(0, 0), a2, voffA);
;             PG8_WAIT_V(8); PG8_WAIT_L(0); PG8_BAR; PG8_MMA(1, 0, At, B0); PG8_MMA(1, 1, At, B1); PG8_BAR; PG8_SCHED;
;             PG8_LDB(B0, 1, 0); PG8_LDB(B1, 1, 1); PG8_SCHED; PG8_LDA(At, 1, 0); PG8_STAGE(PG8_SA(0, 1), a2 + hstepA, voffA);
.Lrx_p3_1_j:
	s_waitcnt lgkmcnt(0)
	s_cmp_eq_u32 s77, -2
	s_cbranch_scc1 .Lcz_p3_1
	s_barrier
	s_waitcnt lgkmcnt(0)
	v_mfma_f32_16x16x32_bf16 v[62:65], v[130:133], v[188:191], v[62:65]
	v_mfma_f32_16x16x32_bf16 v[58:61], v[138:141], v[188:191], v[58:61]
	v_mfma_f32_16x16x32_bf16 v[46:49], v[130:133], v[216:219], v[46:49]
	v_mfma_f32_16x16x32_bf16 v[42:45], v[138:141], v[216:219], v[42:45]
	v_mfma_f32_16x16x32_bf16 v[30:33], v[130:133], v[224:227], v[30:33]
	v_mfma_f32_16x16x32_bf16 v[26:29], v[138:141], v[224:227], v[26:29]
	v_mfma_f32_16x16x32_bf16 v[14:17], v[130:133], v[232:235], v[14:17]
	v_mfma_f32_16x16x32_bf16 v[10:13], v[138:141], v[232:235], v[10:13]
	v_mfma_f32_16x16x32_bf16 v[62:65], v[134:137], v[192:195], v[62:65]
	v_mfma_f32_16x16x32_bf16 v[58:61], v[142:145], v[192:195], v[58:61]
	v_mfma_f32_16x16x32_bf16 v[46:49], v[134:137], v[220:223], v[46:49]
	v_mfma_f32_16x16x32_bf16 v[42:45], v[142:145], v[220:223], v[42:45]
	v_mfma_f32_16x16x32_bf16 v[30:33], v[134:137], v[228:231], v[30:33]
	v_mfma_f32_16x16x32_bf16 v[26:29], v[142:145], v[228:231], v[26:29]
	v_mfma_f32_16x16x32_bf16 v[14:17], v[134:137], v[236:239], v[14:17]
	v_mfma_f32_16x16x32_bf16 v[10:13], v[142:145], v[236:239], v[10:13]
	v_mfma_f32_16x16x32_bf16 v[54:57], v[146:149], v[188:191], v[54:57]
	v_mfma_f32_16x16x32_bf16 v[50:53], v[180:183], v[188:191], v[50:53]
	v_mfma_f32_16x16x32_bf16 v[38:41], v[146:149], v[216:219], v[38:41]
	v_mfma_f32_16x16x32_bf16 v[34:37], v[180:183], v[216:219], v[34:37]
	v_mfma_f32_16x16x32_bf16 v[22:25], v[146:149], v[224:227], v[22:25]
	v_mfma_f32_16x16x32_bf16 v[18:21], v[180:183], v[224:227], v[18:21]
	v_mfma_f32_16x16x32_bf16 v[6:9], v[146:149], v[232:235], v[6:9]
	v_mfma_f32_16x16x32_bf16 v[2:5], v[180:183], v[232:235], v[2:5]
	v_mfma_f32_16x16x32_bf16 v[54:57], v[150:153], v[192:195], v[54:57]
	v_mfma_f32_16x16x32_bf16 v[50:53], v[184:187], v[192:195], v[50:53]
	v_mfma_f32_16x16x32_bf16 v[38:41], v[150:153], v[220:223], v[38:41]
	v_mfma_f32_16x16x32_bf16 v[34:37], v[184:187], v[220:223], v[34:37]
	v_mfma_f32_16x16x32_bf16 v[22:25], v[150:153], v[228:231], v[22:25]
	v_mfma_f32_16x16x32_bf16 v[18:21], v[184:187], v[228:231], v[18:21]
	v_mfma_f32_16x16x32_bf16 v[6:9], v[150:153], v[236:239], v[6:9]
	v_mfma_f32_16x16x32_bf16 v[2:5], v[184:187], v[236:239], v[2:5]
.Lcz_p3_1_j:
	s_barrier
	s_add_i32 s82, 0, 0x18000
	s_add_i32 s83, 0, 0x1c000
	v_add_u32_e32 v142, s82, v196
	v_add_u32_e32 v162, s83, v196
	ds_read_b128 v[130:133], v142
	ds_read_b128 v[134:137], v142 offset:1024
	ds_read_b128 v[138:141], v142 offset:2048
	ds_read_b128 v[142:145], v142 offset:3072
	ds_read_b128 v[146:149], v162
	ds_read_b128 v[150:153], v162 offset:1024
	ds_read_b128 v[180:183], v162 offset:2048
	ds_read_b128 v[184:187], v162 offset:3072
	s_add_u32 s20, s20, 0x40000
	s_addc_u32 s21, s21, 0
	s_mov_b32 m0, s79
	v_lshl_add_u64 v[248:249], s[20:21], 0, v[154:155]
	ds_read_b128 v[188:191], v212 offset:32768
	ds_read_b128 v[192:195], v212 offset:33792
	ds_read_b128 v[216:219], v212 offset:34816
	ds_read_b128 v[220:223], v212 offset:35840
	ds_read_b128 v[224:227], v212 offset:36864
	ds_read_b128 v[228:231], v212 offset:37888
	ds_read_b128 v[232:235], v212 offset:38912
	ds_read_b128 v[236:239], v212 offset:39936
	global_load_lds_dwordx4 v[248:249], off
	v_lshl_add_u64 v[248:249], s[20:21], 0, v[158:159]
	s_mov_b32 m0, s18
	s_nop 0
	global_load_lds_dwordx4 v[248:249], off
	s_cmp_eq_u32 s98, 0
	s_cbranch_scc1 .Lrx_p3_2_n
	s_sub_u32 s98, s98, 1
	s_waitcnt vmcnt(24)
	s_branch .Lrx_p3_2_j

; #define PG8_STAGE(bufoff, gbase, voff) do { _Pragma("unroll") for (int _i = 0; _i < 2; ++_i) \
;         __builtin_amdgcn_global_load_lds((const unsigned*)((const char*)(gbase) + (voff)[_i]), (LAS unsigned*)(lds + (bufoff) + ldsw + _i * 8192), 16, 0, 0); } while (0)
; #define PG8_LDA(dst, b, h) do { _Pragma("unroll") for (int m = 0; m < 4; ++m) _Pragma("unroll") for (int k = 0; k < 2; ++k) dst[m][k] = *(const LAS bf16x8*)(lds + PG8_SA(b, h) + aoff + m * 2048 + k * 1024); } while (0)
; #define PG8_LDB(dst, b, h) do { _Pragma("unroll") for (int n = 0; n < 2; ++n) _Pragma("unroll") for (int k = 0; k < 2; ++k) dst[n][k] = *(const LAS bf16x8*)(lds + PG8_SB(b, h) + boff + n * 2048 + k * 1024); } while (0)
; #define PG8_MMA(ai, bj, At, Bt) do { __builtin_amdgcn_s_setprio(1); _Pragma("unroll") for (int m = 0; m < 4; ++m) _Pragma("unroll") for (int n = 0; n < 2; ++n) _Pragma("unroll") for (int k = 0; k < 2; ++k) \
;         acc[ai][bj][m][n] = __builtin_amdgcn_mfma_f32_16x16x32_bf16(Bt[n][k], At[m][k], acc[ai][bj][m][n], 0, 0, 0); __builtin_amdgcn_s_setprio(0); } while (0)
; #define PG8_WAIT_V(n) asm volatile("s_waitcnt vmcnt(" #n ")" ::: "memory")
; #define PG8_WAIT_L(n) asm volatile("s_waitcnt lgkmcnt(" #n ")" ::: "memory")
; #define PG8_BAR __builtin_amdgcn_s_barrier()
; #define PG8_SCHED __builtin_amdgcn_sched_barrier(0)
; template <class Epi>
; __device__ __forceinline__ void gemm_phase(LAS unsigned char* lds, const Gemm g, const Sched& S, const Epi& E) {
;     ...
;             PG8_LDB(B0, 1, 0); PG8_LDB(B1, 1, 1); PG8_SCHED; PG8_LDA(At, 1, 0); PG8_STAGE(PG8_SA(0, 1), a2 + hstepA, voffA);
;             PG8_WAIT_V(8); PG8_WAIT_L(0); PG8_BAR; PG8_MMA(0, 0, At, B0); PG8_MMA(0, 1, At, B1); PG8_BAR; PG8_SCHED;
;             PG8_LDA(At, 1, 1); PG8_STAGE(PG8_SB(1, 0), b3, voffB); PG8_STAGE(PG8_SB(1, 1), b3 + hstepB, voffB); PG8_STAGE(PG8_SA(1, 0), a3, voffA);
;             PG8_WAIT_V(8); PG8_WAIT_L(0); PG8_BAR; PG8_MMA(1, 0, At, B0); PG8_MMA(1, 1, At, B1); PG8_BAR; PG8_SCHED;
;         }
.Lrx_p3_2_j:
	s_waitcnt lgkmcnt(0)
	s_barrier
	s_waitcnt lgkmcnt(0)
	v_mfma_f32_16x16x32_bf16 v[126:129], v[130:133], v[188:191], v[126:129]
	v_mfma_f32_16x16x32_bf16 v[122:125], v[138:141], v[188:191], v[122:125]
	v_mfma_f32_16x16x32_bf16 v[110:113], v[130:133], v[216:219], v[110:113]
	v_mfma_f32_16x16x32_bf16 v[106:109], v[138:141], v[216:219], v[106:109]
	v_mfma_f32_16x16x32_bf16 v[94:97], v[130:133], v[224:227], v[94:97]
	v_mfma_f32_16x16x32_bf16 v[90:93], v[138:141], v[224:227], v[90:93]
	v_mfma_f32_16x16x32_bf16 v[78:81], v[130:133], v[232:235], v[78:81]
	v_mfma_f32_16x16x32_bf16 v[74:77], v[138:141], v[232:235], v[74:77]
	v_mfma_f32_16x16x32_bf16 v[126:129], v[134:137], v[192:195], v[126:129]
	v_mfma_f32_16x16x32_bf16 v[122:125], v[142:145], v[192:195], v[122:125]
	v_mfma_f32_16x16x32_bf16 v[110:113], v[134:137], v[220:223], v[110:113]
	v_mfma_f32_16x16x32_bf16 v[106:109], v[142:145], v[220:223], v[106:109]
	v_mfma_f32_16x16x32_bf16 v[94:97], v[134:137], v[228:231], v[94:97]
	v_mfma_f32_16x16x32_bf16 v[90:93], v[142:145], v[228:231], v[90:93]
	v_mfma_f32_16x16x32_bf16 v[78:81], v[134:137], v[236:239], v[78:81]
	v_mfma_f32_16x16x32_bf16 v[74:77], v[142:145], v[236:239], v[74:77]
	v_mfma_f32_16x16x32_bf16 v[118:121], v[146:149], v[188:191], v[118:121]
	v_mfma_f32_16x16x32_bf16 v[114:117], v[180:183], v[188:191], v[114:117]
	v_mfma_f32_16x16x32_bf16 v[102:105], v[146:149], v[216:219], v[102:105]
	v_mfma_f32_16x16x32_bf16 v[98:101], v[180:183], v[216:219], v[98:101]
	v_mfma_f32_16x16x32_bf16 v[86:89], v[146:149], v[224:227], v[86:89]
	v_mfma_f32_16x16x32_bf16 v[82:85], v[180:183], v[224:227], v[82:85]
	v_mfma_f32_16x16x32_bf16 v[70:73], v[146:149], v[232:235], v[70:73]
	v_mfma_f32_16x16x32_bf16 v[66:69], v[180:183], v[232:235], v[66:69]
	v_mfma_f32_16x16x32_bf16 v[118:121], v[150:153], v[192:195], v[118:121]
	v_mfma_f32_16x16x32_bf16 v[114:117], v[184:187], v[192:195], v[114:117]
	v_mfma_f32_16x16x32_bf16 v[102:105], v[150:153], v[220:223], v[102:105]
	v_mfma_f32_16x16x32_bf16 v[98:101], v[184:187], v[220:223], v[98:101]
	v_mfma_f32_16x16x32_bf16 v[86:89], v[150:153], v[228:231], v[86:89]
	v_mfma_f32_16x16x32_bf16 v[82:85], v[184:187], v[228:231], v[82:85]
	v_mfma_f32_16x16x32_bf16 v[70:73], v[150:153], v[236:239], v[70:73]
	v_mfma_f32_16x16x32_bf16 v[66:69], v[184:187], v[236:239], v[66:69]
	s_barrier
	s_add_i32 s20, s82, s78
	v_lshl_add_u64 v[240:241], v[240:241], 0, s[26:27]
	s_mov_b32 m0, s20
	ds_read_b128 v[188:191], v212 offset:49152
	ds_read_b128 v[192:195], v212 offset:50176
	ds_read_b128 v[216:219], v212 offset:51200
	ds_read_b128 v[220:223], v212 offset:52224
	ds_read_b128 v[224:227], v212 offset:53248
	ds_read_b128 v[228:231], v212 offset:54272
	ds_read_b128 v[232:235], v212 offset:55296
	ds_read_b128 v[236:239], v212 offset:56320
	global_load_lds_dwordx4 v[240:241], off
	s_add_i32 m0, s20, 0x2000
	s_add_u32 s6, s6, 0x40080
	v_lshl_add_u64 v[240:241], v[242:243], 0, s[26:27]
	s_addc_u32 s7, s7, 0
	s_add_i32 s20, s83, s78
	global_load_lds_dwordx4 v[240:241], off
	v_lshl_add_u64 v[240:241], s[6:7], 0, v[156:157]
	s_mov_b32 m0, s20
	s_nop 0
	global_load_lds_dwordx4 v[240:241], off
	v_lshl_add_u64 v[240:241], s[6:7], 0, v[160:161]
	s_add_i32 m0, s20, 0x2000
	s_nop 0
	global_load_lds_dwordx4 v[240:241], off
	v_lshl_add_u64 v[240:241], v[244:245], 0, s[26:27]
	s_mov_b32 m0, s84
	s_nop 0
	global_load_lds_dwordx4 v[240:241], off
	v_lshl_add_u64 v[240:241], v[246:247], 0, s[26:27]
	s_mov_b32 m0, s85
	s_nop 0
	global_load_lds_dwordx4 v[240:241], off
	s_waitcnt vmcnt(8)
	s_waitcnt lgkmcnt(0)
	s_barrier
	s_waitcnt lgkmcnt(0)
	v_mfma_f32_16x16x32_bf16 v[62:65], v[130:133], v[188:191], v[62:65]
	v_mfma_f32_16x16x32_bf16 v[58:61], v[138:141], v[188:191], v[58:61]
	v_mfma_f32_16x16x32_bf16 v[46:49], v[130:133], v[216:219], v[46:49]
	v_mfma_f32_16x16x32_bf16 v[42:45], v[138:141], v[216:219], v[42:45]
	v_mfma_f32_16x16x32_bf16 v[30:33], v[130:133], v[224:227], v[30:33]
	v_mfma_f32_16x16x32_bf16 v[26:29], v[138:141], v[224:227], v[26:29]
	v_mfma_f32_16x16x32_bf16 v[14:17], v[130:133], v[232:235], v[14:17]
	v_mfma_f32_16x16x32_bf16 v[10:13], v[138:141], v[232:235], v[10:13]
	v_mfma_f32_16x16x32_bf16 v[62:65], v[134:137], v[192:195], v[62:65]
	v_mfma_f32_16x16x32_bf16 v[58:61], v[142:145], v[192:195], v[58:61]
	v_mfma_f32_16x16x32_bf16 v[46:49], v[134:137], v[220:223], v[46:49]
	v_mfma_f32_16x16x32_bf16 v[42:45], v[142:145], v[220:223], v[42:45]
	v_mfma_f32_16x16x32_bf16 v[30:33], v[134:137], v[228:231], v[30:33]
	v_mfma_f32_16x16x32_bf16 v[26:29], v[142:145], v[228:231], v[26:29]
	v_mfma_f32_16x16x32_bf16 v[14:17], v[134:137], v[236:239], v[14:17]
	v_mfma_f32_16x16x32_bf16 v[10:13], v[142:145], v[236:239], v[10:13]
	v_mfma_f32_16x16x32_bf16 v[54:57], v[146:149], v[188:191], v[54:57]
	v_mfma_f32_16x16x32_bf16 v[50:53], v[180:183], v[188:191], v[50:53]
	v_mfma_f32_16x16x32_bf16 v[38:41], v[146:149], v[216:219], v[38:41]
	v_mfma_f32_16x16x32_bf16 v[34:37], v[180:183], v[216:219], v[34:37]
	v_mfma_f32_16x16x32_bf16 v[22:25], v[146:149], v[224:227], v[22:25]
	v_mfma_f32_16x16x32_bf16 v[18:21], v[180:183], v[224:227], v[18:21]
	v_mfma_f32_16x16x32_bf16 v[6:9], v[146:149], v[232:235], v[6:9]
	v_mfma_f32_16x16x32_bf16 v[2:5], v[180:183], v[232:235], v[2:5]
	v_mfma_f32_16x16x32_bf16 v[54:57], v[150:153], v[192:195], v[54:57]
	v_mfma_f32_16x16x32_bf16 v[50:53], v[184:187], v[192:195], v[50:53]
	v_mfma_f32_16x16x32_bf16 v[38:41], v[150:153], v[220:223], v[38:41]
	v_mfma_f32_16x16x32_bf16 v[34:37], v[184:187], v[220:223], v[34:37]
	v_mfma_f32_16x16x32_bf16 v[22:25], v[150:153], v[228:231], v[22:25]
	v_mfma_f32_16x16x32_bf16 v[18:21], v[184:187], v[228:231], v[18:21]
	v_mfma_f32_16x16x32_bf16 v[6:9], v[150:153], v[236:239], v[6:9]
	v_mfma_f32_16x16x32_bf16 v[2:5], v[184:187], v[236:239], v[2:5]
	s_barrier
	s_add_i32 s77, s77, 2
	s_add_u32 s4, s4, 0x100
	s_addc_u32 s5, s5, 0
	s_add_u32 s74, s74, 0x100
	s_addc_u32 s75, s75, 0
	s_cmp_gt_u32 s77, 13
	s_cbranch_scc0 .LBB0_822
	s_and_b64 vcc, exec, s[28:29]
	s_cbranch_vccz .LBB0_825
	s_barrier

; #define PG8_STAGE(bufoff, gbase, voff) do { _Pragma("unroll") for (int _i = 0; _i < 2; ++_i) \
;         __builtin_amdgcn_global_load_lds((const unsigned*)((const char*)(gbase) + (voff)[_i]), (LAS unsigned*)(lds + (bufoff) + ldsw + _i * 8192), 16, 0, 0); } while (0)
; #define PG8_LDA(dst, b, h) do { _Pragma("unroll") for (int m = 0; m < 4; ++m) _Pragma("unroll") for (int k = 0; k < 2; ++k) dst[m][k] = *(const LAS bf16x8*)(lds + PG8_SA(b, h) + aoff + m * 2048 + k * 1024); } while (0)
; #define PG8_MMA(ai, bj, At, Bt) do { __builtin_amdgcn_s_setprio(1); _Pragma("unroll") for (int m = 0; m < 4; ++m) _Pragma("unroll") for (int n = 0; n < 2; ++n) _Pragma("unroll") for (int k = 0; k < 2; ++k) \
;         acc[ai][bj][m][n] = __builtin_amdgcn_mfma_f32_16x16x32_bf16(Bt[n][k], At[m][k], acc[ai][bj][m][n], 0, 0, 0); __builtin_amdgcn_s_setprio(0); } while (0)
; #define PG8_WAIT_V(n) asm volatile("s_waitcnt vmcnt(" #n ")" ::: "memory")
; #define PG8_WAIT_L(n) asm volatile("s_waitcnt lgkmcnt(" #n ")" ::: "memory")
; #define PG8_BAR __builtin_amdgcn_s_barrier()
; #define PG8_SCHED __builtin_amdgcn_sched_barrier(0)
; template <class Epi>
; __device__ __forceinline__ void gemm_phase(LAS unsigned char* lds, const Gemm g, const Sched& S, const Epi& E) {
;     ...
;                 for (int n = 0; n < 2; ++n) acc[a][b][m][n] = (f32x4){0.f, 0.f, 0.f, 0.f};
;     ...
;             PG8_WAIT_V(8); PG8_WAIT_L(0); PG8_BAR; PG8_MMA(0, 0, At, B0); PG8_MMA(0, 1, At, B1); PG8_BAR; PG8_SCHED;
;             PG8_LDA(At, 0, 1); PG8_STAGE(PG8_SB(0, 0), b2, voffB); PG8_STAGE(PG8_SB(0, 1), b2 + hstepB, voffB); PG8_STAGE(PG8_SA(0, 0), a2, voffA);
;             PG8_WAIT_V(8); PG8_WAIT_L(0); PG8_BAR; PG8_MMA(1, 0, At, B0); PG8_MMA(1, 1, At, B1); PG8_BAR; PG8_SCHED;
.Lcz_p3_0:
	s_barrier
	s_waitcnt lgkmcnt(0)
	v_mfma_f32_16x16x32_bf16 v[126:129], v[130:133], v[188:191], 0
	v_mfma_f32_16x16x32_bf16 v[122:125], v[138:141], v[188:191], 0
	v_mfma_f32_16x16x32_bf16 v[110:113], v[130:133], v[216:219], 0
	v_mfma_f32_16x16x32_bf16 v[106:109], v[138:141], v[216:219], 0
	v_mfma_f32_16x16x32_bf16 v[94:97], v[130:133], v[224:227], 0
	v_mfma_f32_16x16x32_bf16 v[90:93], v[138:141], v[224:227], 0
	v_mfma_f32_16x16x32_bf16 v[78:81], v[130:133], v[232:235], 0
	v_mfma_f32_16x16x32_bf16 v[74:77], v[138:141], v[232:235], 0
	v_mfma_f32_16x16x32_bf16 v[126:129], v[134:137], v[192:195], v[126:129]
	v_mfma_f32_16x16x32_bf16 v[122:125], v[142:145], v[192:195], v[122:125]
	v_mfma_f32_16x16x32_bf16 v[110:113], v[134:137], v[220:223], v[110:113]
	v_mfma_f32_16x16x32_bf16 v[106:109], v[142:145], v[220:223], v[106:109]
	v_mfma_f32_16x16x32_bf16 v[94:97], v[134:137], v[228:231], v[94:97]
	v_mfma_f32_16x16x32_bf16 v[90:93], v[142:145], v[228:231], v[90:93]
	v_mfma_f32_16x16x32_bf16 v[78:81], v[134:137], v[236:239], v[78:81]
	v_mfma_f32_16x16x32_bf16 v[74:77], v[142:145], v[236:239], v[74:77]
	v_mfma_f32_16x16x32_bf16 v[118:121], v[146:149], v[188:191], 0
	v_mfma_f32_16x16x32_bf16 v[114:117], v[180:183], v[188:191], 0
	v_mfma_f32_16x16x32_bf16 v[102:105], v[146:149], v[216:219], 0
	v_mfma_f32_16x16x32_bf16 v[98:101], v[180:183], v[216:219], 0
	v_mfma_f32_16x16x32_bf16 v[86:89], v[146:149], v[224:227], 0
	v_mfma_f32_16x16x32_bf16 v[82:85], v[180:183], v[224:227], 0
	v_mfma_f32_16x16x32_bf16 v[70:73], v[146:149], v[232:235], 0
	v_mfma_f32_16x16x32_bf16 v[66:69], v[180:183], v[232:235], 0
	v_mfma_f32_16x16x32_bf16 v[118:121], v[150:153], v[192:195], v[118:121]
	v_mfma_f32_16x16x32_bf16 v[114:117], v[184:187], v[192:195], v[114:117]
	v_mfma_f32_16x16x32_bf16 v[102:105], v[150:153], v[220:223], v[102:105]
	v_mfma_f32_16x16x32_bf16 v[98:101], v[184:187], v[220:223], v[98:101]
	v_mfma_f32_16x16x32_bf16 v[86:89], v[150:153], v[228:231], v[86:89]
	v_mfma_f32_16x16x32_bf16 v[82:85], v[184:187], v[228:231], v[82:85]
	v_mfma_f32_16x16x32_bf16 v[70:73], v[150:153], v[236:239], v[70:73]
	v_mfma_f32_16x16x32_bf16 v[66:69], v[184:187], v[236:239], v[66:69]
	s_branch .Lcz_p3_0_j
.Lcz_p3_1:
	s_barrier
	s_waitcnt lgkmcnt(0)
	v_mfma_f32_16x16x32_bf16 v[62:65], v[130:133], v[188:191], 0
	v_mfma_f32_16x16x32_bf16 v[58:61], v[138:141], v[188:191], 0
	v_mfma_f32_16x16x32_bf16 v[46:49], v[130:133], v[216:219], 0
	v_mfma_f32_16x16x32_bf16 v[42:45], v[138:141], v[216:219], 0
	v_mfma_f32_16x16x32_bf16 v[30:33], v[130:133], v[224:227], 0
	v_mfma_f32_16x16x32_bf16 v[26:29], v[138:141], v[224:227], 0
	v_mfma_f32_16x16x32_bf16 v[14:17], v[130:133], v[232:235], 0
	v_mfma_f32_16x16x32_bf16 v[10:13], v[138:141], v[232:235], 0
	v_mfma_f32_16x16x32_bf16 v[62:65], v[134:137], v[192:195], v[62:65]
	v_mfma_f32_16x16x32_bf16 v[58:61], v[142:145], v[192:195], v[58:61]
	v_mfma_f32_16x16x32_bf16 v[46:49], v[134:137], v[220:223], v[46:49]
	v_mfma_f32_16x16x32_bf16 v[42:45], v[142:145], v[220:223], v[42:45]
	v_mfma_f32_16x16x32_bf16 v[30:33], v[134:137], v[228:231], v[30:33]
	v_mfma_f32_16x16x32_bf16 v[26:29], v[142:145], v[228:231], v[26:29]
	v_mfma_f32_16x16x32_bf16 v[14:17], v[134:137], v[236:239], v[14:17]
	v_mfma_f32_16x16x32_bf16 v[10:13], v[142:145], v[236:239], v[10:13]
	v_mfma_f32_16x16x32_bf16 v[54:57], v[146:149], v[188:191], 0
	v_mfma_f32_16x16x32_bf16 v[50:53], v[180:183], v[188:191], 0
	v_mfma_f32_16x16x32_bf16 v[38:41], v[146:149], v[216:219], 0
	v_mfma_f32_16x16x32_bf16 v[34:37], v[180:183], v[216:219], 0
	v_mfma_f32_16x16x32_bf16 v[22:25], v[146:149], v[224:227], 0
	v_mfma_f32_16x16x32_bf16 v[18:21], v[180:183], v[224:227], 0
	v_mfma_f32_16x16x32_bf16 v[6:9], v[146:149], v[232:235], 0
	v_mfma_f32_16x16x32_bf16 v[2:5], v[180:183], v[232:235], 0
	v_mfma_f32_16x16x32_bf16 v[54:57], v[150:153], v[192:195], v[54:57]
	v_mfma_f32_16x16x32_bf16 v[50:53], v[184:187], v[192:195], v[50:53]
	v_mfma_f32_16x16x32_bf16 v[38:41], v[150:153], v[220:223], v[38:41]
	v_mfma_f32_16x16x32_bf16 v[34:37], v[184:187], v[220:223], v[34:37]
	v_mfma_f32_16x16x32_bf16 v[22:25], v[150:153], v[228:231], v[22:25]
	v_mfma_f32_16x16x32_bf16 v[18:21], v[184:187], v[228:231], v[18:21]
	v_mfma_f32_16x16x32_bf16 v[6:9], v[150:153], v[236:239], v[6:9]
	v_mfma_f32_16x16x32_bf16 v[2:5], v[184:187], v[236:239], v[2:5]
	s_branch .Lcz_p3_1_j

; __device__ __forceinline__ unsigned xb_ld(unsigned* p)              { return __hip_atomic_load(p, __ATOMIC_RELAXED, __HIP_MEMORY_SCOPE_AGENT); }
; __device__ __forceinline__ unsigned xb_add(unsigned* p, unsigned v) { return __hip_atomic_fetch_add(p, v, __ATOMIC_RELAXED, __HIP_MEMORY_SCOPE_AGENT); }
; #define XB_SPIN(cond, bar) do { unsigned _sp = 0; while (cond) { __builtin_amdgcn_s_sleep(1); \
;     if ((++_sp & 255u) == 0u) { if (xb_ld(&(bar)[XB_TMO])) break; if (_sp > XB_SPIN_CAP) { atomicAdd(&(bar)[XB_TMO], 1u); break; } } } } while (0)
; __device__ __forceinline__ void xcd_barrier(const XcdBarrier& b) {
;     asm volatile("s_waitcnt vmcnt(0)" ::: "memory");
;     __syncthreads();
;     if (threadIdx.x == 0) {
;         unsigned* bar = b.bar;
;         __builtin_amdgcn_s_waitcnt(0);
;         unsigned nloc = b.st[0], nx = b.st[1];
;         if (nloc == 0u) { xcd_barrier_complete(bar, b.x, nloc, nx); b.st[0] = nloc; b.st[1] = nx; }
;         const unsigned old = xb_add(&bar[XB_XSUB(b.x)], 1u);
;         const unsigned gen = old / nloc;
;         if (old + 1u == (gen + 1u) * nloc) {
;             __builtin_amdgcn_fence(__ATOMIC_RELEASE, "agent");
;             asm volatile("s_waitcnt vmcnt(0)" ::: "memory");
;             const unsigned og = xb_add(&bar[XB_TOP], 1u);
;             const unsigned tg = og / nx;
;             if (og + 1u == (tg + 1u) * nx) xb_add(&bar[XB_TOPGEN], 1u);
;             else XB_SPIN(xb_ld(&bar[XB_TOPGEN]) == tg, bar);
;             __builtin_amdgcn_fence(__ATOMIC_ACQUIRE, "agent");
;             xb_add(&bar[XB_XGEN(b.x)], 1u);
;             asm volatile("s_waitcnt vmcnt(0)" ::: "memory");
;         } else {
;             XB_SPIN(xb_ld(&bar[XB_XGEN(b.x)]) == gen, bar);
;             __builtin_amdgcn_fence(__ATOMIC_ACQUIRE, "agent");
;             asm volatile("s_waitcnt vmcnt(0)" ::: "memory");
;         }
;     }
;     __syncthreads();
; }
.LBB0_988:
	v_readlane_b32 s0, v252, 28
	v_readlane_b32 s1, v252, 29
	s_cmp_gt_i32 s1, 4
	s_cselect_b64 s[0:1], -1, 0
	s_and_b64 s[4:5], s[38:39], s[0:1]
	s_andn2_b64 vcc, exec, s[4:5]
	s_cbranch_vccnz .LBB0_1038
	s_setprio 0
	s_waitcnt vmcnt(0) lgkmcnt(0)
	s_barrier
	v_readfirstlane_b32 s98, v0
	s_cmp_lg_u32 s98, 0
	s_cbranch_scc1 .Lxb3_end
	s_mov_b64 s[100:101], exec
	v_readlane_b32 s98, v253, 0
	s_cmp_lg_u32 s98, 0
	s_cbranch_scc1 .Lxb3_have
	s_mov_b64 exec, 0xffff
	v_mbcnt_lo_u32_b32 v254, -1, 0
	v_lshlrev_b32_e32 v254, 8, v254
	s_mov_b32 s99, 0
	v_writelane_b32 v253, s99, 3

; __device__ __forceinline__ unsigned xb_ld(unsigned* p)              { return __hip_atomic_load(p, __ATOMIC_RELAXED, __HIP_MEMORY_SCOPE_AGENT); }
; __device__ __forceinline__ unsigned xb_add(unsigned* p, unsigned v) { return __hip_atomic_fetch_add(p, v, __ATOMIC_RELAXED, __HIP_MEMORY_SCOPE_AGENT); }
; #define XB_SPIN(cond, bar) do { unsigned _sp = 0; while (cond) { __builtin_amdgcn_s_sleep(1); \
;     if ((++_sp & 255u) == 0u) { if (xb_ld(&(bar)[XB_TMO])) break; if (_sp > XB_SPIN_CAP) { atomicAdd(&(bar)[XB_TMO], 1u); break; } } } } while (0)
; __device__ __forceinline__ void xcd_barrier(const XcdBarrier& b) {
;     asm volatile("s_waitcnt vmcnt(0)" ::: "memory");
;     __syncthreads();
;     if (threadIdx.x == 0) {
;         unsigned* bar = b.bar;
;         __builtin_amdgcn_s_waitcnt(0);
;         unsigned nloc = b.st[0], nx = b.st[1];
;         if (nloc == 0u) { xcd_barrier_complete(bar, b.x, nloc, nx); b.st[0] = nloc; b.st[1] = nx; }
;         const unsigned old = xb_add(&bar[XB_XSUB(b.x)], 1u);
;         const unsigned gen = old / nloc;
;         if (old + 1u == (gen + 1u) * nloc) {
;             __builtin_amdgcn_fence(__ATOMIC_RELEASE, "agent");
;             asm volatile("s_waitcnt vmcnt(0)" ::: "memory");
;             const unsigned og = xb_add(&bar[XB_TOP], 1u);
;             const unsigned tg = og / nx;
;             if (og + 1u == (tg + 1u) * nx) xb_add(&bar[XB_TOPGEN], 1u);
;             else XB_SPIN(xb_ld(&bar[XB_TOPGEN]) == tg, bar);
;             __builtin_amdgcn_fence(__ATOMIC_ACQUIRE, "agent");
;             xb_add(&bar[XB_XGEN(b.x)], 1u);
;             asm volatile("s_waitcnt vmcnt(0)" ::: "memory");
;         } else {
;             XB_SPIN(xb_ld(&bar[XB_XGEN(b.x)]) == gen, bar);
;             __builtin_amdgcn_fence(__ATOMIC_ACQUIRE, "agent");
;             asm volatile("s_waitcnt vmcnt(0)" ::: "memory");
;         }
;     }
;     __syncthreads();
; }
.LBB0_1195:
	v_readlane_b32 s0, v252, 28
	v_readlane_b32 s1, v252, 29
	s_cmp_gt_i32 s1, 5
	s_cselect_b64 s[0:1], -1, 0
	s_and_b64 s[4:5], s[20:21], s[0:1]
	s_andn2_b64 vcc, exec, s[4:5]
	s_cbranch_vccnz .LBB0_1245
	s_setprio 0
	s_waitcnt vmcnt(0) lgkmcnt(0)
	s_barrier
	v_readfirstlane_b32 s98, v0
	s_cmp_lg_u32 s98, 0
	s_cbranch_scc1 .Lxb4_end
	s_mov_b64 s[100:101], exec
	v_readlane_b32 s98, v253, 0
	s_cmp_lg_u32 s98, 0
	s_cbranch_scc1 .Lxb4_have
	s_mov_b64 exec, 0xffff
	v_mbcnt_lo_u32_b32 v254, -1, 0
	v_lshlrev_b32_e32 v254, 8, v254
	s_mov_b32 s99, 0
	v_writelane_b32 v253, s99, 3

; __device__ __forceinline__ unsigned xb_ld(unsigned* p)              { return __hip_atomic_load(p, __ATOMIC_RELAXED, __HIP_MEMORY_SCOPE_AGENT); }
; __device__ __forceinline__ unsigned xb_add(unsigned* p, unsigned v) { return __hip_atomic_fetch_add(p, v, __ATOMIC_RELAXED, __HIP_MEMORY_SCOPE_AGENT); }
; #define XB_SPIN(cond, bar) do { unsigned _sp = 0; while (cond) { __builtin_amdgcn_s_sleep(1); \
;     if ((++_sp & 255u) == 0u) { if (xb_ld(&(bar)[XB_TMO])) break; if (_sp > XB_SPIN_CAP) { atomicAdd(&(bar)[XB_TMO], 1u); break; } } } } while (0)
; __device__ __forceinline__ void xcd_barrier(const XcdBarrier& b) {
;     asm volatile("s_waitcnt vmcnt(0)" ::: "memory");
;     __syncthreads();
;     if (threadIdx.x == 0) {
;         unsigned* bar = b.bar;
;         __builtin_amdgcn_s_waitcnt(0);
;         unsigned nloc = b.st[0], nx = b.st[1];
;         if (nloc == 0u) { xcd_barrier_complete(bar, b.x, nloc, nx); b.st[0] = nloc; b.st[1] = nx; }
;         const unsigned old = xb_add(&bar[XB_XSUB(b.x)], 1u);
;         const unsigned gen = old / nloc;
;         if (old + 1u == (gen + 1u) * nloc) {
;             __builtin_amdgcn_fence(__ATOMIC_RELEASE, "agent");
;             asm volatile("s_waitcnt vmcnt(0)" ::: "memory");
;             const unsigned og = xb_add(&bar[XB_TOP], 1u);
;             const unsigned tg = og / nx;
;             if (og + 1u == (tg + 1u) * nx) xb_add(&bar[XB_TOPGEN], 1u);
;             else XB_SPIN(xb_ld(&bar[XB_TOPGEN]) == tg, bar);
;             __builtin_amdgcn_fence(__ATOMIC_ACQUIRE, "agent");
;             xb_add(&bar[XB_XGEN(b.x)], 1u);
;             asm volatile("s_waitcnt vmcnt(0)" ::: "memory");
;         } else {
;             XB_SPIN(xb_ld(&bar[XB_XGEN(b.x)]) == gen, bar);
;             __builtin_amdgcn_fence(__ATOMIC_ACQUIRE, "agent");
;             asm volatile("s_waitcnt vmcnt(0)" ::: "memory");
;         }
;     }
;     __syncthreads();
; }
.LBB0_1250:
	v_readlane_b32 s0, v252, 28
	v_readlane_b32 s1, v252, 29
	s_cmp_gt_i32 s1, 6
	s_cselect_b64 s[0:1], -1, 0
	s_and_b64 s[4:5], s[4:5], s[0:1]
	s_andn2_b64 vcc, exec, s[4:5]
	s_cbranch_vccnz .LBB0_1300
	s_setprio 0
	s_waitcnt vmcnt(0) lgkmcnt(0)
	s_barrier
	v_readfirstlane_b32 s98, v0
	s_cmp_lg_u32 s98, 0
	s_cbranch_scc1 .Lxb5_end
	s_mov_b64 s[100:101], exec
	v_readlane_b32 s98, v253, 0
	s_cmp_lg_u32 s98, 0
	s_cbranch_scc1 .Lxb5_have
	s_mov_b64 exec, 0xffff
	v_mbcnt_lo_u32_b32 v254, -1, 0
	v_lshlrev_b32_e32 v254, 8, v254
	s_mov_b32 s99, 0
	v_writelane_b32 v253, s99, 3

; __device__ __forceinline__ unsigned xb_ld(unsigned* p)              { return __hip_atomic_load(p, __ATOMIC_RELAXED, __HIP_MEMORY_SCOPE_AGENT); }
; __device__ __forceinline__ unsigned xb_add(unsigned* p, unsigned v) { return __hip_atomic_fetch_add(p, v, __ATOMIC_RELAXED, __HIP_MEMORY_SCOPE_AGENT); }
; #define XB_SPIN(cond, bar) do { unsigned _sp = 0; while (cond) { __builtin_amdgcn_s_sleep(1); \
;     if ((++_sp & 255u) == 0u) { if (xb_ld(&(bar)[XB_TMO])) break; if (_sp > XB_SPIN_CAP) { atomicAdd(&(bar)[XB_TMO], 1u); break; } } } } while (0)
; __device__ __forceinline__ void xcd_barrier(const XcdBarrier& b) {
;     asm volatile("s_waitcnt vmcnt(0)" ::: "memory");
;     __syncthreads();
;     if (threadIdx.x == 0) {
;         unsigned* bar = b.bar;
;         __builtin_amdgcn_s_waitcnt(0);
;         unsigned nloc = b.st[0], nx = b.st[1];
;         if (nloc == 0u) { xcd_barrier_complete(bar, b.x, nloc, nx); b.st[0] = nloc; b.st[1] = nx; }
;         const unsigned old = xb_add(&bar[XB_XSUB(b.x)], 1u);
;         const unsigned gen = old / nloc;
;         if (old + 1u == (gen + 1u) * nloc) {
;             __builtin_amdgcn_fence(__ATOMIC_RELEASE, "agent");
;             asm volatile("s_waitcnt vmcnt(0)" ::: "memory");
;             const unsigned og = xb_add(&bar[XB_TOP], 1u);
;             const unsigned tg = og / nx;
;             if (og + 1u == (tg + 1u) * nx) xb_add(&bar[XB_TOPGEN], 1u);
;             else XB_SPIN(xb_ld(&bar[XB_TOPGEN]) == tg, bar);
;             __builtin_amdgcn_fence(__ATOMIC_ACQUIRE, "agent");
;             xb_add(&bar[XB_XGEN(b.x)], 1u);
;             asm volatile("s_waitcnt vmcnt(0)" ::: "memory");
;         } else {
;             XB_SPIN(xb_ld(&bar[XB_XGEN(b.x)]) == gen, bar);
;             __builtin_amdgcn_fence(__ATOMIC_ACQUIRE, "agent");
;             asm volatile("s_waitcnt vmcnt(0)" ::: "memory");
;         }
;     }
;     __syncthreads();
; }
.LBB0_1332:
	v_readlane_b32 s84, v252, 28
	v_readlane_b32 s85, v252, 29
	s_cmp_gt_i32 s85, 7
	s_cselect_b64 s[0:1], -1, 0
	s_and_b64 s[4:5], s[4:5], s[0:1]
	s_andn2_b64 vcc, exec, s[4:5]
	s_cbranch_vccnz .LBB0_1382
	s_setprio 0
	s_waitcnt vmcnt(0) lgkmcnt(0)
	s_barrier
	v_readfirstlane_b32 s98, v0
	s_cmp_lg_u32 s98, 0
	s_cbranch_scc1 .Lxb6_end
	s_mov_b64 s[100:101], exec
	v_readlane_b32 s98, v253, 0
	s_cmp_lg_u32 s98, 0
	s_cbranch_scc1 .Lxb6_have
	s_mov_b64 exec, 0xffff
	v_mbcnt_lo_u32_b32 v254, -1, 0
	v_lshlrev_b32_e32 v254, 8, v254
	s_mov_b32 s99, 0
	v_writelane_b32 v253, s99, 3

; #define PG8_STAGE(bufoff, gbase, voff) do { _Pragma("unroll") for (int _i = 0; _i < 2; ++_i) \
;         __builtin_amdgcn_global_load_lds((const unsigned*)((const char*)(gbase) + (voff)[_i]), (LAS unsigned*)(lds + (bufoff) + ldsw + _i * 8192), 16, 0, 0); } while (0)
; #define PG8_LDA(dst, b, h) do { _Pragma("unroll") for (int m = 0; m < 4; ++m) _Pragma("unroll") for (int k = 0; k < 2; ++k) dst[m][k] = *(const LAS bf16x8*)(lds + PG8_SA(b, h) + aoff + m * 2048 + k * 1024); } while (0)
; #define PG8_LDB(dst, b, h) do { _Pragma("unroll") for (int n = 0; n < 2; ++n) _Pragma("unroll") for (int k = 0; k < 2; ++k) dst[n][k] = *(const LAS bf16x8*)(lds + PG8_SB(b, h) + boff + n * 2048 + k * 1024); } while (0)
; #define PG8_MMA(ai, bj, At, Bt) do { __builtin_amdgcn_s_setprio(1); _Pragma("unroll") for (int m = 0; m < 4; ++m) _Pragma("unroll") for (int n = 0; n < 2; ++n) _Pragma("unroll") for (int k = 0; k < 2; ++k) \
;         acc[ai][bj][m][n] = __builtin_amdgcn_mfma_f32_16x16x32_bf16(Bt[n][k], At[m][k], acc[ai][bj][m][n], 0, 0, 0); __builtin_amdgcn_s_setprio(0); } while (0)
; template <class Epi>
; __device__ __forceinline__ void gemm_phase(LAS unsigned char* lds, const Gemm g, const Sched& S, const Epi& E) {
;     ...
;     for (;;) {
;         const bool has_next = S.next(ui + 1, nxt);
;         const char* nA = has_next ? (const char*)g.A + (size_t)nxt.pm * tstepA + (size_t)nxt.part * g.koff * 2 : cA; const char* nB = has_next ? (const char*)g.Bt + (size_t)nxt.pn * tstepB + (size_t)nxt.part * g.koff * 2 : cB;
;         for (int t = 0; t < nt; t += 2) {
;             const bool last = (t == nt - 2);
;             const char* a1 = cA + (size_t)(t + 1) * kstep;
;             const char* a2 = last ? nA : cA + (size_t)(t + 2) * kstep; const char* b2 = last ? nB : cB + (size_t)(t + 2) * kstep;
;             const char* a3 = a2 + kstep; const char* b3 = b2 + kstep;
;             PG8_LDB(B0, 0, 0); PG8_LDB(B1, 0, 1); PG8_SCHED; PG8_LDA(At, 0, 0); PG8_STAGE(PG8_SA(1, 1), a1 + hstepA, voffA);
;             PG8_WAIT_V(8); PG8_WAIT_L(0); PG8_BAR; PG8_MMA(0, 0, At, B0); PG8_MMA(0, 1, At, B1); PG8_BAR; PG8_SCHED;
;             PG8_LDA(At, 0, 1); PG8_STAGE(PG8_SB(0, 0), b2, voffB); PG8_STAGE(PG8_SB(0, 1), b2 + hstepB, voffB); PG8_STAGE(PG8_SA(0, 0), a2, voffA);
;             PG8_WAIT_V(8); PG8_WAIT_L(0); PG8_BAR; PG8_MMA(1, 0, At, B0); PG8_MMA(1, 1, At, B1); PG8_BAR; PG8_SCHED;
.LBB0_1412:
	s_ashr_i32 s23, s22, 31
	s_lshl_b64 s[24:25], s[22:23], 20
	s_add_u32 s19, s92, s24
	s_addc_u32 s23, s93, s25
	s_ashr_i32 s21, s20, 31
	s_lshl_b64 s[26:27], s[20:21], 11
	s_add_u32 s24, s19, s26
	s_addc_u32 s25, s23, s27
	s_and_b64 s[36:37], s[4:5], exec
	s_cselect_b32 s21, s25, s31
	s_cselect_b32 s23, s24, s30
	s_ashr_i32 s19, s18, 31
	s_lshl_b64 s[36:37], s[18:19], 20
	v_readlane_b32 s60, v252, 5
	v_readlane_b32 s61, v252, 6
	s_add_u32 s19, s60, s36
	s_addc_u32 s29, s61, s37
	s_add_u32 s26, s19, s26
	s_addc_u32 s27, s29, s27
	s_and_b64 s[36:37], s[4:5], exec
	s_cselect_b32 s19, s27, s35
	s_cselect_b32 s29, s26, s34
	s_add_u32 s30, s30, 0x80080
	s_addc_u32 s31, s31, 0
	s_add_u32 s59, s34, 0x100
	s_addc_u32 s60, s35, 0
	s_mov_b32 s61, -2
	v_readfirstlane_b32 s100, v0
	s_lshr_b32 s100, s100, 8
	s_cmp_eq_u32 s100, 0
	s_cbranch_scc0 .Lprio_3
	s_setprio 1
.Lprio_3:
.LBB0_1413:
	v_add_u32_e32 v142, s52, v225
	v_add_u32_e32 v158, s53, v225
	ds_read_b128 v[130:133], v142
	ds_read_b128 v[134:137], v142 offset:1024
	ds_read_b128 v[138:141], v142 offset:2048
	ds_read_b128 v[142:145], v142 offset:3072
	ds_read_b128 v[146:149], v158
	ds_read_b128 v[150:153], v158 offset:1024
	ds_read_b128 v[154:157], v158 offset:2048
	ds_read_b128 v[158:161], v158 offset:3072
	s_add_u32 s34, s30, 0xfff80080
	s_addc_u32 s35, s31, -1
	s_cmp_eq_u32 s61, 12
	s_cselect_b32 s37, s21, s35
	s_cselect_b32 s36, s23, s34
	s_cselect_b32 s35, s19, s60
	s_cselect_b32 s34, s29, s59
	v_lshl_add_u64 v[194:195], s[30:31], 0, v[210:211]
	s_add_i32 m0, s33, 0xc000
	ds_read_b128 v[162:165], v229
	ds_read_b128 v[166:169], v229 offset:1024
	ds_read_b128 v[170:173], v229 offset:2048
	ds_read_b128 v[174:177], v229 offset:3072
	ds_read_b128 v[178:181], v229 offset:4096
	ds_read_b128 v[182:185], v229 offset:5120
	ds_read_b128 v[186:189], v229 offset:6144
	ds_read_b128 v[190:193], v229 offset:7168
	global_load_lds_dwordx4 v[194:195], off
	v_lshl_add_u64 v[194:195], s[30:31], 0, v[212:213]
	s_add_i32 m0, s33, 0xe000
	s_nop 0
	global_load_lds_dwordx4 v[194:195], off
	s_waitcnt vmcnt(8)
	s_waitcnt lgkmcnt(0)
	s_barrier
	s_waitcnt lgkmcnt(0)
	v_mfma_f32_16x16x32_bf16 v[126:129], v[130:133], v[162:165], v[126:129]
	v_mfma_f32_16x16x32_bf16 v[110:113], v[138:141], v[162:165], v[110:113]
	v_mfma_f32_16x16x32_bf16 v[122:125], v[130:133], v[170:173], v[122:125]
	v_mfma_f32_16x16x32_bf16 v[102:105], v[138:141], v[170:173], v[102:105]
	v_mfma_f32_16x16x32_bf16 v[118:121], v[130:133], v[178:181], v[118:121]
	v_mfma_f32_16x16x32_bf16 v[94:97], v[138:141], v[178:181], v[94:97]
	v_mfma_f32_16x16x32_bf16 v[114:117], v[130:133], v[186:189], v[114:117]
	v_mfma_f32_16x16x32_bf16 v[86:89], v[138:141], v[186:189], v[86:89]
	v_mfma_f32_16x16x32_bf16 v[126:129], v[134:137], v[166:169], v[126:129]
	v_mfma_f32_16x16x32_bf16 v[110:113], v[142:145], v[166:169], v[110:113]
	v_mfma_f32_16x16x32_bf16 v[122:125], v[134:137], v[174:177], v[122:125]
	v_mfma_f32_16x16x32_bf16 v[102:105], v[142:145], v[174:177], v[102:105]
	v_mfma_f32_16x16x32_bf16 v[118:121], v[134:137], v[182:185], v[118:121]
	v_mfma_f32_16x16x32_bf16 v[94:97], v[142:145], v[182:185], v[94:97]
	v_mfma_f32_16x16x32_bf16 v[114:117], v[134:137], v[190:193], v[114:117]
	v_mfma_f32_16x16x32_bf16 v[86:89], v[142:145], v[190:193], v[86:89]
	v_mfma_f32_16x16x32_bf16 v[106:109], v[146:149], v[162:165], v[106:109]
	v_mfma_f32_16x16x32_bf16 v[78:81], v[154:157], v[162:165], v[78:81]
	v_mfma_f32_16x16x32_bf16 v[98:101], v[146:149], v[170:173], v[98:101]
	v_mfma_f32_16x16x32_bf16 v[70:73], v[154:157], v[170:173], v[70:73]
	v_mfma_f32_16x16x32_bf16 v[90:93], v[146:149], v[178:181], v[90:93]
	v_mfma_f32_16x16x32_bf16 v[62:65], v[154:157], v[178:181], v[62:65]
	v_mfma_f32_16x16x32_bf16 v[82:85], v[146:149], v[186:189], v[82:85]
	v_mfma_f32_16x16x32_bf16 v[54:57], v[154:157], v[186:189], v[54:57]
	v_mfma_f32_16x16x32_bf16 v[106:109], v[150:153], v[166:169], v[106:109]
	v_mfma_f32_16x16x32_bf16 v[78:81], v[158:161], v[166:169], v[78:81]
	v_mfma_f32_16x16x32_bf16 v[98:101], v[150:153], v[174:177], v[98:101]
	v_mfma_f32_16x16x32_bf16 v[70:73], v[158:161], v[174:177], v[70:73]
	v_mfma_f32_16x16x32_bf16 v[90:93], v[150:153], v[182:185], v[90:93]
	v_mfma_f32_16x16x32_bf16 v[62:65], v[158:161], v[182:185], v[62:65]
	v_mfma_f32_16x16x32_bf16 v[82:85], v[150:153], v[190:193], v[82:85]
	v_mfma_f32_16x16x32_bf16 v[54:57], v[158:161], v[190:193], v[54:57]
	s_barrier
	s_add_i32 s62, s52, s3
	v_lshl_add_u64 v[194:195], s[34:35], 0, v[202:203]
	s_mov_b32 m0, s62
	ds_read_b128 v[162:165], v229 offset:16384
	ds_read_b128 v[166:169], v229 offset:17408
	ds_read_b128 v[170:173], v229 offset:18432
	ds_read_b128 v[174:177], v229 offset:19456
	ds_read_b128 v[178:181], v229 offset:20480
	ds_read_b128 v[182:185], v229 offset:21504
	ds_read_b128 v[186:189], v229 offset:22528
	ds_read_b128 v[190:193], v229 offset:23552
	global_load_lds_dwordx4 v[194:195], off
	s_add_i32 m0, s62, 0x2000
	s_add_u32 s62, s34, 0x80000
	v_lshl_add_u64 v[196:197], s[34:35], 0, v[206:207]
	s_addc_u32 s63, s35, 0
	s_add_i32 s64, s53, s3
	global_load_lds_dwordx4 v[196:197], off
	v_lshl_add_u64 v[218:219], s[62:63], 0, v[202:203]
	s_mov_b32 m0, s64
	v_lshl_add_u64 v[220:221], s[36:37], 0, v[204:205]
	global_load_lds_dwordx4 v[218:219], off
	v_lshl_add_u64 v[218:219], s[62:63], 0, v[206:207]
	s_add_i32 m0, s64, 0x2000
	s_nop 0
	global_load_lds_dwordx4 v[218:219], off
	v_lshl_add_u64 v[218:219], s[36:37], 0, v[200:201]
	s_mov_b32 m0, s33
	s_nop 0
	global_load_lds_dwordx4 v[218:219], off
	s_mov_b32 m0, s38
	s_nop 0
	global_load_lds_dwordx4 v[220:221], off
	s_waitcnt vmcnt(8)
	s_waitcnt lgkmcnt(0)
	s_barrier
; #define PG8_STAGE(bufoff, gbase, voff) do { _Pragma("unroll") for (int _i = 0; _i < 2; ++_i) \
;         __builtin_amdgcn_global_load_lds((const unsigned*)((const char*)(gbase) + (voff)[_i]), (LAS unsigned*)(lds + (bufoff) + ldsw + _i * 8192), 16, 0, 0); } while (0)
; #define PG8_LDA(dst, b, h) do { _Pragma("unroll") for (int m = 0; m < 4; ++m) _Pragma("unroll") for (int k = 0; k < 2; ++k) dst[m][k] = *(const LAS bf16x8*)(lds + PG8_SA(b, h) + aoff + m * 2048 + k * 1024); } while (0)
; #define PG8_LDB(dst, b, h) do { _Pragma("unroll") for (int n = 0; n < 2; ++n) _Pragma("unroll") for (int k = 0; k < 2; ++k) dst[n][k] = *(const LAS bf16x8*)(lds + PG8_SB(b, h) + boff + n * 2048 + k * 1024); } while (0)
; #define PG8_MMA(ai, bj, At, Bt) do { __builtin_amdgcn_s_setprio(1); _Pragma("unroll") for (int m = 0; m < 4; ++m) _Pragma("unroll") for (int n = 0; n < 2; ++n) _Pragma("unroll") for (int k = 0; k < 2; ++k) \
;         acc[ai][bj][m][n] = __builtin_amdgcn_mfma_f32_16x16x32_bf16(Bt[n][k], At[m][k], acc[ai][bj][m][n], 0, 0, 0); __builtin_amdgcn_s_setprio(0); } while (0)
; #define PG8_WAIT_V(n) asm volatile("s_waitcnt vmcnt(" #n ")" ::: "memory")
; #define PG8_WAIT_L(n) asm volatile("s_waitcnt lgkmcnt(" #n ")" ::: "memory")
; #define PG8_BAR __builtin_amdgcn_s_barrier()
; #define PG8_SCHED __builtin_amdgcn_sched_barrier(0)
; template <class Epi>
; __device__ __forceinline__ void gemm_phase(LAS unsigned char* lds, const Gemm g, const Sched& S, const Epi& E) {
;     ...
;             PG8_WAIT_V(8); PG8_WAIT_L(0); PG8_BAR; PG8_MMA(1, 0, At, B0); PG8_MMA(1, 1, At, B1); PG8_BAR; PG8_SCHED;
;             PG8_LDB(B0, 1, 0); PG8_LDB(B1, 1, 1); PG8_SCHED; PG8_LDA(At, 1, 0); PG8_STAGE(PG8_SA(0, 1), a2 + hstepA, voffA);
;             PG8_WAIT_V(8); PG8_WAIT_L(0); PG8_BAR; PG8_MMA(0, 0, At, B0); PG8_MMA(0, 1, At, B1); PG8_BAR; PG8_SCHED;
	s_waitcnt lgkmcnt(0)
	v_mfma_f32_16x16x32_bf16 v[74:77], v[130:133], v[162:165], v[74:77]
	v_mfma_f32_16x16x32_bf16 v[46:49], v[138:141], v[162:165], v[46:49]
	v_mfma_f32_16x16x32_bf16 v[66:69], v[130:133], v[170:173], v[66:69]
	v_mfma_f32_16x16x32_bf16 v[38:41], v[138:141], v[170:173], v[38:41]
	v_mfma_f32_16x16x32_bf16 v[58:61], v[130:133], v[178:181], v[58:61]
	v_mfma_f32_16x16x32_bf16 v[30:33], v[138:141], v[178:181], v[30:33]
	v_mfma_f32_16x16x32_bf16 v[50:53], v[130:133], v[186:189], v[50:53]
	v_mfma_f32_16x16x32_bf16 v[22:25], v[138:141], v[186:189], v[22:25]
	v_mfma_f32_16x16x32_bf16 v[74:77], v[134:137], v[166:169], v[74:77]
	v_mfma_f32_16x16x32_bf16 v[46:49], v[142:145], v[166:169], v[46:49]
	v_mfma_f32_16x16x32_bf16 v[66:69], v[134:137], v[174:177], v[66:69]
	v_mfma_f32_16x16x32_bf16 v[38:41], v[142:145], v[174:177], v[38:41]
	v_mfma_f32_16x16x32_bf16 v[58:61], v[134:137], v[182:185], v[58:61]
	v_mfma_f32_16x16x32_bf16 v[30:33], v[142:145], v[182:185], v[30:33]
	v_mfma_f32_16x16x32_bf16 v[50:53], v[134:137], v[190:193], v[50:53]
	v_mfma_f32_16x16x32_bf16 v[22:25], v[142:145], v[190:193], v[22:25]
	v_mfma_f32_16x16x32_bf16 v[42:45], v[146:149], v[162:165], v[42:45]
	v_mfma_f32_16x16x32_bf16 v[14:17], v[154:157], v[162:165], v[14:17]
	v_mfma_f32_16x16x32_bf16 v[34:37], v[146:149], v[170:173], v[34:37]
	v_mfma_f32_16x16x32_bf16 v[10:13], v[154:157], v[170:173], v[10:13]
	v_mfma_f32_16x16x32_bf16 v[26:29], v[146:149], v[178:181], v[26:29]
	v_mfma_f32_16x16x32_bf16 v[6:9], v[154:157], v[178:181], v[6:9]
	v_mfma_f32_16x16x32_bf16 v[18:21], v[146:149], v[186:189], v[18:21]
	v_mfma_f32_16x16x32_bf16 v[2:5], v[154:157], v[186:189], v[2:5]
	v_mfma_f32_16x16x32_bf16 v[42:45], v[150:153], v[166:169], v[42:45]
	v_mfma_f32_16x16x32_bf16 v[14:17], v[158:161], v[166:169], v[14:17]
	v_mfma_f32_16x16x32_bf16 v[34:37], v[150:153], v[174:177], v[34:37]
	v_mfma_f32_16x16x32_bf16 v[10:13], v[158:161], v[174:177], v[10:13]
	v_mfma_f32_16x16x32_bf16 v[26:29], v[150:153], v[182:185], v[26:29]
	v_mfma_f32_16x16x32_bf16 v[6:9], v[158:161], v[182:185], v[6:9]
	v_mfma_f32_16x16x32_bf16 v[18:21], v[150:153], v[190:193], v[18:21]
	v_mfma_f32_16x16x32_bf16 v[2:5], v[158:161], v[190:193], v[2:5]
	s_barrier
	s_add_i32 s62, 0, 0x18000
	s_add_i32 s63, 0, 0x1c000
	v_add_u32_e32 v142, s62, v225
	v_add_u32_e32 v158, s63, v225
	ds_read_b128 v[130:133], v142
	ds_read_b128 v[134:137], v142 offset:1024
	ds_read_b128 v[138:141], v142 offset:2048
	ds_read_b128 v[142:145], v142 offset:3072
	ds_read_b128 v[146:149], v158
	ds_read_b128 v[150:153], v158 offset:1024
	ds_read_b128 v[154:157], v158 offset:2048
	ds_read_b128 v[158:161], v158 offset:3072
	s_add_u32 s36, s36, 0x80000
	s_addc_u32 s37, s37, 0
	s_mov_b32 m0, s39
	v_lshl_add_u64 v[230:231], s[36:37], 0, v[200:201]
	ds_read_b128 v[162:165], v229 offset:32768
	ds_read_b128 v[166:169], v229 offset:33792
	ds_read_b128 v[170:173], v229 offset:34816
	ds_read_b128 v[174:177], v229 offset:35840
	ds_read_b128 v[178:181], v229 offset:36864
	ds_read_b128 v[182:185], v229 offset:37888
	ds_read_b128 v[186:189], v229 offset:38912
	ds_read_b128 v[190:193], v229 offset:39936
	global_load_lds_dwordx4 v[230:231], off
	v_lshl_add_u64 v[230:231], s[36:37], 0, v[204:205]
	s_mov_b32 m0, s42
	s_nop 0
	global_load_lds_dwordx4 v[230:231], off
	s_waitcnt vmcnt(8)
	s_waitcnt lgkmcnt(0)
	s_barrier
	s_waitcnt lgkmcnt(0)
	v_mfma_f32_16x16x32_bf16 v[126:129], v[130:133], v[162:165], v[126:129]
	v_mfma_f32_16x16x32_bf16 v[110:113], v[138:141], v[162:165], v[110:113]
	v_mfma_f32_16x16x32_bf16 v[122:125], v[130:133], v[170:173], v[122:125]
	v_mfma_f32_16x16x32_bf16 v[102:105], v[138:141], v[170:173], v[102:105]
	v_mfma_f32_16x16x32_bf16 v[118:121], v[130:133], v[178:181], v[118:121]
	v_mfma_f32_16x16x32_bf16 v[94:97], v[138:141], v[178:181], v[94:97]
	v_mfma_f32_16x16x32_bf16 v[114:117], v[130:133], v[186:189], v[114:117]
	v_mfma_f32_16x16x32_bf16 v[86:89], v[138:141], v[186:189], v[86:89]
	v_mfma_f32_16x16x32_bf16 v[126:129], v[134:137], v[166:169], v[126:129]
	v_mfma_f32_16x16x32_bf16 v[110:113], v[142:145], v[166:169], v[110:113]
	v_mfma_f32_16x16x32_bf16 v[122:125], v[134:137], v[174:177], v[122:125]
	v_mfma_f32_16x16x32_bf16 v[102:105], v[142:145], v[174:177], v[102:105]
	v_mfma_f32_16x16x32_bf16 v[118:121], v[134:137], v[182:185], v[118:121]
	v_mfma_f32_16x16x32_bf16 v[94:97], v[142:145], v[182:185], v[94:97]
	v_mfma_f32_16x16x32_bf16 v[114:117], v[134:137], v[190:193], v[114:117]
	v_mfma_f32_16x16x32_bf16 v[86:89], v[142:145], v[190:193], v[86:89]
	v_mfma_f32_16x16x32_bf16 v[106:109], v[146:149], v[162:165], v[106:109]
	v_mfma_f32_16x16x32_bf16 v[78:81], v[154:157], v[162:165], v[78:81]
	v_mfma_f32_16x16x32_bf16 v[98:101], v[146:149], v[170:173], v[98:101]
	v_mfma_f32_16x16x32_bf16 v[70:73], v[154:157], v[170:173], v[70:73]
	v_mfma_f32_16x16x32_bf16 v[90:93], v[146:149], v[178:181], v[90:93]
	v_mfma_f32_16x16x32_bf16 v[62:65], v[154:157], v[178:181], v[62:65]
	v_mfma_f32_16x16x32_bf16 v[82:85], v[146:149], v[186:189], v[82:85]
	v_mfma_f32_16x16x32_bf16 v[54:57], v[154:157], v[186:189], v[54:57]
	v_mfma_f32_16x16x32_bf16 v[106:109], v[150:153], v[166:169], v[106:109]
	v_mfma_f32_16x16x32_bf16 v[78:81], v[158:161], v[166:169], v[78:81]
	v_mfma_f32_16x16x32_bf16 v[98:101], v[150:153], v[174:177], v[98:101]
	v_mfma_f32_16x16x32_bf16 v[70:73], v[158:161], v[174:177], v[70:73]
	v_mfma_f32_16x16x32_bf16 v[90:93], v[150:153], v[182:185], v[90:93]
	v_mfma_f32_16x16x32_bf16 v[62:65], v[158:161], v[182:185], v[62:65]
	v_mfma_f32_16x16x32_bf16 v[82:85], v[150:153], v[190:193], v[82:85]
	v_mfma_f32_16x16x32_bf16 v[54:57], v[158:161], v[190:193], v[54:57]
	s_barrier
; #define PG8_STAGE(bufoff, gbase, voff) do { _Pragma("unroll") for (int _i = 0; _i < 2; ++_i) \
;         __builtin_amdgcn_global_load_lds((const unsigned*)((const char*)(gbase) + (voff)[_i]), (LAS unsigned*)(lds + (bufoff) + ldsw + _i * 8192), 16, 0, 0); } while (0)
; #define PG8_LDA(dst, b, h) do { _Pragma("unroll") for (int m = 0; m < 4; ++m) _Pragma("unroll") for (int k = 0; k < 2; ++k) dst[m][k] = *(const LAS bf16x8*)(lds + PG8_SA(b, h) + aoff + m * 2048 + k * 1024); } while (0)
; #define PG8_MMA(ai, bj, At, Bt) do { __builtin_amdgcn_s_setprio(1); _Pragma("unroll") for (int m = 0; m < 4; ++m) _Pragma("unroll") for (int n = 0; n < 2; ++n) _Pragma("unroll") for (int k = 0; k < 2; ++k) \
;         acc[ai][bj][m][n] = __builtin_amdgcn_mfma_f32_16x16x32_bf16(Bt[n][k], At[m][k], acc[ai][bj][m][n], 0, 0, 0); __builtin_amdgcn_s_setprio(0); } while (0)
; #define PG8_WAIT_V(n) asm volatile("s_waitcnt vmcnt(" #n ")" ::: "memory")
; #define PG8_WAIT_L(n) asm volatile("s_waitcnt lgkmcnt(" #n ")" ::: "memory")
; #define PG8_BAR __builtin_amdgcn_s_barrier()
; #define PG8_SCHED __builtin_amdgcn_sched_barrier(0)
; template <class Epi>
; __device__ __forceinline__ void gemm_phase(LAS unsigned char* lds, const Gemm g, const Sched& S, const Epi& E) {
;     ...
;             PG8_LDA(At, 1, 1); PG8_STAGE(PG8_SB(1, 0), b3, voffB); PG8_STAGE(PG8_SB(1, 1), b3 + hstepB, voffB); PG8_STAGE(PG8_SA(1, 0), a3, voffA);
;             PG8_WAIT_V(8); PG8_WAIT_L(0); PG8_BAR; PG8_MMA(1, 0, At, B0); PG8_MMA(1, 1, At, B1); PG8_BAR; PG8_SCHED;
;         }
	s_add_i32 s36, s62, s3
	v_lshl_add_u64 v[194:195], v[194:195], 0, s[14:15]
	s_mov_b32 m0, s36
	ds_read_b128 v[162:165], v229 offset:49152
	ds_read_b128 v[166:169], v229 offset:50176
	ds_read_b128 v[170:173], v229 offset:51200
	ds_read_b128 v[174:177], v229 offset:52224
	ds_read_b128 v[178:181], v229 offset:53248
	ds_read_b128 v[182:185], v229 offset:54272
	ds_read_b128 v[186:189], v229 offset:55296
	ds_read_b128 v[190:193], v229 offset:56320
	global_load_lds_dwordx4 v[194:195], off
	s_add_i32 m0, s36, 0x2000
	s_add_u32 s34, s34, 0x80080
	v_lshl_add_u64 v[194:195], v[196:197], 0, s[14:15]
	s_addc_u32 s35, s35, 0
	s_add_i32 s36, s63, s3
	global_load_lds_dwordx4 v[194:195], off
	v_lshl_add_u64 v[194:195], s[34:35], 0, v[202:203]
	s_mov_b32 m0, s36
	s_nop 0
	global_load_lds_dwordx4 v[194:195], off
	v_lshl_add_u64 v[194:195], s[34:35], 0, v[206:207]
	s_add_i32 m0, s36, 0x2000
	s_nop 0
	global_load_lds_dwordx4 v[194:195], off
	v_lshl_add_u64 v[194:195], v[218:219], 0, s[14:15]
	s_mov_b32 m0, s43
	s_nop 0
	global_load_lds_dwordx4 v[194:195], off
	v_lshl_add_u64 v[194:195], v[220:221], 0, s[14:15]
	s_mov_b32 m0, s44
	s_nop 0
	global_load_lds_dwordx4 v[194:195], off
	s_waitcnt vmcnt(8)
	s_waitcnt lgkmcnt(0)
	s_barrier
	s_waitcnt lgkmcnt(0)
	v_mfma_f32_16x16x32_bf16 v[74:77], v[130:133], v[162:165], v[74:77]
	v_mfma_f32_16x16x32_bf16 v[46:49], v[138:141], v[162:165], v[46:49]
	v_mfma_f32_16x16x32_bf16 v[66:69], v[130:133], v[170:173], v[66:69]
	v_mfma_f32_16x16x32_bf16 v[38:41], v[138:141], v[170:173], v[38:41]
	v_mfma_f32_16x16x32_bf16 v[58:61], v[130:133], v[178:181], v[58:61]
	v_mfma_f32_16x16x32_bf16 v[30:33], v[138:141], v[178:181], v[30:33]
	v_mfma_f32_16x16x32_bf16 v[50:53], v[130:133], v[186:189], v[50:53]
	v_mfma_f32_16x16x32_bf16 v[22:25], v[138:141], v[186:189], v[22:25]
	v_mfma_f32_16x16x32_bf16 v[74:77], v[134:137], v[166:169], v[74:77]
	v_mfma_f32_16x16x32_bf16 v[46:49], v[142:145], v[166:169], v[46:49]
	v_mfma_f32_16x16x32_bf16 v[66:69], v[134:137], v[174:177], v[66:69]
	v_mfma_f32_16x16x32_bf16 v[38:41], v[142:145], v[174:177], v[38:41]
	v_mfma_f32_16x16x32_bf16 v[58:61], v[134:137], v[182:185], v[58:61]
	v_mfma_f32_16x16x32_bf16 v[30:33], v[142:145], v[182:185], v[30:33]
	v_mfma_f32_16x16x32_bf16 v[50:53], v[134:137], v[190:193], v[50:53]
	v_mfma_f32_16x16x32_bf16 v[22:25], v[142:145], v[190:193], v[22:25]
	v_mfma_f32_16x16x32_bf16 v[42:45], v[146:149], v[162:165], v[42:45]
	v_mfma_f32_16x16x32_bf16 v[14:17], v[154:157], v[162:165], v[14:17]
	v_mfma_f32_16x16x32_bf16 v[34:37], v[146:149], v[170:173], v[34:37]
	v_mfma_f32_16x16x32_bf16 v[10:13], v[154:157], v[170:173], v[10:13]
	v_mfma_f32_16x16x32_bf16 v[26:29], v[146:149], v[178:181], v[26:29]
	v_mfma_f32_16x16x32_bf16 v[6:9], v[154:157], v[178:181], v[6:9]
	v_mfma_f32_16x16x32_bf16 v[18:21], v[146:149], v[186:189], v[18:21]
	v_mfma_f32_16x16x32_bf16 v[2:5], v[154:157], v[186:189], v[2:5]
	v_mfma_f32_16x16x32_bf16 v[42:45], v[150:153], v[166:169], v[42:45]
	v_mfma_f32_16x16x32_bf16 v[14:17], v[158:161], v[166:169], v[14:17]
	v_mfma_f32_16x16x32_bf16 v[34:37], v[150:153], v[174:177], v[34:37]
	v_mfma_f32_16x16x32_bf16 v[10:13], v[158:161], v[174:177], v[10:13]
	v_mfma_f32_16x16x32_bf16 v[26:29], v[150:153], v[182:185], v[26:29]
	v_mfma_f32_16x16x32_bf16 v[6:9], v[158:161], v[182:185], v[6:9]
	v_mfma_f32_16x16x32_bf16 v[18:21], v[150:153], v[190:193], v[18:21]
	v_mfma_f32_16x16x32_bf16 v[2:5], v[158:161], v[190:193], v[2:5]
	s_barrier
	s_add_i32 s61, s61, 2
	s_add_u32 s30, s30, 0x100
	s_addc_u32 s31, s31, 0
	s_add_u32 s59, s59, 0x100
	s_addc_u32 s60, s60, 0
	s_cmp_gt_u32 s61, 13
	s_cbranch_scc0 .LBB0_1413
	s_and_b64 vcc, exec, s[16:17]
	s_cbranch_vccz .LBB0_1416
	s_barrier

; __device__ __forceinline__ unsigned xb_ld(unsigned* p)              { return __hip_atomic_load(p, __ATOMIC_RELAXED, __HIP_MEMORY_SCOPE_AGENT); }
; __device__ __forceinline__ unsigned xb_add(unsigned* p, unsigned v) { return __hip_atomic_fetch_add(p, v, __ATOMIC_RELAXED, __HIP_MEMORY_SCOPE_AGENT); }
; #define XB_SPIN(cond, bar) do { unsigned _sp = 0; while (cond) { __builtin_amdgcn_s_sleep(1); \
;     if ((++_sp & 255u) == 0u) { if (xb_ld(&(bar)[XB_TMO])) break; if (_sp > XB_SPIN_CAP) { atomicAdd(&(bar)[XB_TMO], 1u); break; } } } } while (0)
; __device__ __forceinline__ void xcd_barrier(const XcdBarrier& b) {
;     asm volatile("s_waitcnt vmcnt(0)" ::: "memory");
;     __syncthreads();
;     if (threadIdx.x == 0) {
;         unsigned* bar = b.bar;
;         __builtin_amdgcn_s_waitcnt(0);
;         unsigned nloc = b.st[0], nx = b.st[1];
;         if (nloc == 0u) { xcd_barrier_complete(bar, b.x, nloc, nx); b.st[0] = nloc; b.st[1] = nx; }
;         const unsigned old = xb_add(&bar[XB_XSUB(b.x)], 1u);
;         const unsigned gen = old / nloc;
;         if (old + 1u == (gen + 1u) * nloc) {
;             __builtin_amdgcn_fence(__ATOMIC_RELEASE, "agent");
;             asm volatile("s_waitcnt vmcnt(0)" ::: "memory");
;             const unsigned og = xb_add(&bar[XB_TOP], 1u);
;             const unsigned tg = og / nx;
;             if (og + 1u == (tg + 1u) * nx) xb_add(&bar[XB_TOPGEN], 1u);
;             else XB_SPIN(xb_ld(&bar[XB_TOPGEN]) == tg, bar);
;             __builtin_amdgcn_fence(__ATOMIC_ACQUIRE, "agent");
;             xb_add(&bar[XB_XGEN(b.x)], 1u);
;             asm volatile("s_waitcnt vmcnt(0)" ::: "memory");
;         } else {
;             XB_SPIN(xb_ld(&bar[XB_XGEN(b.x)]) == gen, bar);
;             __builtin_amdgcn_fence(__ATOMIC_ACQUIRE, "agent");
;             asm volatile("s_waitcnt vmcnt(0)" ::: "memory");
;         }
;     }
;     __syncthreads();
; }
.LBB0_1493:
	s_cmp_gt_i32 s85, 8
	s_cselect_b64 s[0:1], -1, 0
	s_and_b64 s[4:5], s[8:9], s[0:1]
	s_andn2_b64 vcc, exec, s[4:5]
	s_cbranch_vccnz .LBB0_1543
	s_setprio 0
	s_waitcnt vmcnt(0) lgkmcnt(0)
	s_barrier
	v_readfirstlane_b32 s98, v0
	s_cmp_lg_u32 s98, 0
	s_cbranch_scc1 .Lxb7_end
	s_mov_b64 s[100:101], exec
	v_readlane_b32 s98, v253, 0
	s_cmp_lg_u32 s98, 0
	s_cbranch_scc1 .Lxb7_have
	s_mov_b64 exec, 0xffff
	v_mbcnt_lo_u32_b32 v254, -1, 0
	v_lshlrev_b32_e32 v254, 8, v254
	s_mov_b32 s99, 0
	v_writelane_b32 v253, s99, 3

; #define PG8_STAGE(bufoff, gbase, voff) do { _Pragma("unroll") for (int _i = 0; _i < 2; ++_i) \
;         __builtin_amdgcn_global_load_lds((const unsigned*)((const char*)(gbase) + (voff)[_i]), (LAS unsigned*)(lds + (bufoff) + ldsw + _i * 8192), 16, 0, 0); } while (0)
; #define PG8_LDA(dst, b, h) do { _Pragma("unroll") for (int m = 0; m < 4; ++m) _Pragma("unroll") for (int k = 0; k < 2; ++k) dst[m][k] = *(const LAS bf16x8*)(lds + PG8_SA(b, h) + aoff + m * 2048 + k * 1024); } while (0)
; #define PG8_LDB(dst, b, h) do { _Pragma("unroll") for (int n = 0; n < 2; ++n) _Pragma("unroll") for (int k = 0; k < 2; ++k) dst[n][k] = *(const LAS bf16x8*)(lds + PG8_SB(b, h) + boff + n * 2048 + k * 1024); } while (0)
; #define PG8_MMA(ai, bj, At, Bt) do { __builtin_amdgcn_s_setprio(1); _Pragma("unroll") for (int m = 0; m < 4; ++m) _Pragma("unroll") for (int n = 0; n < 2; ++n) _Pragma("unroll") for (int k = 0; k < 2; ++k) \
;         acc[ai][bj][m][n] = __builtin_amdgcn_mfma_f32_16x16x32_bf16(Bt[n][k], At[m][k], acc[ai][bj][m][n], 0, 0, 0); __builtin_amdgcn_s_setprio(0); } while (0)
; template <class Epi>
; __device__ __forceinline__ void gemm_phase(LAS unsigned char* lds, const Gemm g, const Sched& S, const Epi& E) {
;     ...
;     for (;;) {
;         const bool has_next = S.next(ui + 1, nxt);
;         const char* nA = has_next ? (const char*)g.A + (size_t)nxt.pm * tstepA + (size_t)nxt.part * g.koff * 2 : cA; const char* nB = has_next ? (const char*)g.Bt + (size_t)nxt.pn * tstepB + (size_t)nxt.part * g.koff * 2 : cB;
;         for (int t = 0; t < nt; t += 2) {
;             const bool last = (t == nt - 2);
;             const char* a1 = cA + (size_t)(t + 1) * kstep;
;             const char* a2 = last ? nA : cA + (size_t)(t + 2) * kstep; const char* b2 = last ? nB : cB + (size_t)(t + 2) * kstep;
;             const char* a3 = a2 + kstep; const char* b3 = b2 + kstep;
;             PG8_LDB(B0, 0, 0); PG8_LDB(B1, 0, 1); PG8_SCHED; PG8_LDA(At, 0, 0); PG8_STAGE(PG8_SA(1, 1), a1 + hstepA, voffA);
;             PG8_WAIT_V(8); PG8_WAIT_L(0); PG8_BAR; PG8_MMA(0, 0, At, B0); PG8_MMA(0, 1, At, B1); PG8_BAR; PG8_SCHED;
;             PG8_LDA(At, 0, 1); PG8_STAGE(PG8_SB(0, 0), b2, voffB); PG8_STAGE(PG8_SB(0, 1), b2 + hstepB, voffB); PG8_STAGE(PG8_SA(0, 0), a2, voffA);
;             PG8_WAIT_V(8); PG8_WAIT_L(0); PG8_BAR; PG8_MMA(1, 0, At, B0); PG8_MMA(1, 1, At, B1); PG8_BAR; PG8_SCHED;
.LBB0_1575:
	s_ashr_i32 s25, s24, 31
	s_lshl_b64 s[26:27], s[24:25], 20
	s_add_u32 s26, s94, s26
	s_addc_u32 s27, s95, s27
	s_and_b64 s[28:29], s[6:7], exec
	s_cselect_b32 s9, s27, s31
	s_cselect_b32 s25, s26, s30
	s_ashr_i32 s23, s22, 31
	s_lshl_b64 s[28:29], s[22:23], 19
	v_readlane_b32 s36, v252, 7
	v_readlane_b32 s37, v252, 8
	s_add_u32 s28, s36, s28
	s_addc_u32 s29, s37, s29
	s_and_b64 s[36:37], s[6:7], exec
	s_cselect_b32 s23, s29, s35
	s_cselect_b32 s64, s28, s34
	s_add_u32 s30, s30, 0x80080
	s_addc_u32 s31, s31, 0
	s_add_u32 s65, s34, 0x100
	s_addc_u32 s66, s35, 0
	s_mov_b32 s67, -2
	s_waitcnt lgkmcnt(0)
	v_readfirstlane_b32 s100, v0
	s_lshr_b32 s100, s100, 8
	s_cmp_eq_u32 s100, 0
	s_cbranch_scc0 .Lprio_4
	s_setprio 1
.Lprio_4:
.LBB0_1576:
	ds_read_b128 v[106:109], v211
	ds_read_b128 v[114:117], v211 offset:1024
	ds_read_b128 v[130:133], v211 offset:2048
	ds_read_b128 v[134:137], v211 offset:3072
	ds_read_b128 v[146:149], v212
	ds_read_b128 v[150:153], v212 offset:1024
	ds_read_b128 v[154:157], v212 offset:2048
	ds_read_b128 v[158:161], v212 offset:3072
	s_add_u32 s34, s30, 0xfff80080
	s_addc_u32 s35, s31, -1
	s_cmp_eq_u32 s67, 12
	s_cselect_b32 s37, s9, s35
	s_cselect_b32 s36, s25, s34
	s_cselect_b32 s35, s23, s66
	s_cselect_b32 s34, s64, s65
	v_lshl_add_u64 v[206:207], s[30:31], 0, v[196:197]
	s_add_i32 m0, s33, 0xc000
	ds_read_b128 v[162:165], v213
	ds_read_b128 v[166:169], v213 offset:1024
	ds_read_b128 v[170:173], v213 offset:2048
	ds_read_b128 v[174:177], v213 offset:3072
	ds_read_b128 v[178:181], v213 offset:4096
	ds_read_b128 v[182:185], v213 offset:5120
	ds_read_b128 v[216:219], v213 offset:6144
	ds_read_b128 v[220:223], v213 offset:7168
	global_load_lds_dwordx4 v[206:207], off
	v_lshl_add_u64 v[206:207], s[30:31], 0, v[200:201]
	s_add_i32 m0, s33, 0xe000
	s_nop 0
	global_load_lds_dwordx4 v[206:207], off
	s_waitcnt vmcnt(8)
	s_waitcnt lgkmcnt(0)
	s_cmp_eq_u32 s67, -2
	s_cbranch_scc1 .Lcz_p8_0
	s_barrier
	s_waitcnt lgkmcnt(0)
	v_mfma_f32_16x16x32_bf16 v[142:145], v[106:109], v[162:165], v[142:145]
	v_mfma_f32_16x16x32_bf16 v[138:141], v[130:133], v[162:165], v[138:141]
	v_mfma_f32_16x16x32_bf16 v[118:121], v[106:109], v[170:173], v[118:121]
	v_mfma_f32_16x16x32_bf16 v[110:113], v[130:133], v[170:173], v[110:113]
	v_mfma_f32_16x16x32_bf16 v[94:97], v[106:109], v[178:181], v[94:97]
	v_mfma_f32_16x16x32_bf16 v[90:93], v[130:133], v[178:181], v[90:93]
	v_mfma_f32_16x16x32_bf16 v[78:81], v[106:109], v[216:219], v[78:81]
	v_mfma_f32_16x16x32_bf16 v[74:77], v[130:133], v[216:219], v[74:77]
	v_mfma_f32_16x16x32_bf16 v[142:145], v[114:117], v[166:169], v[142:145]
	v_mfma_f32_16x16x32_bf16 v[138:141], v[134:137], v[166:169], v[138:141]
	v_mfma_f32_16x16x32_bf16 v[118:121], v[114:117], v[174:177], v[118:121]
	v_mfma_f32_16x16x32_bf16 v[110:113], v[134:137], v[174:177], v[110:113]
	v_mfma_f32_16x16x32_bf16 v[94:97], v[114:117], v[182:185], v[94:97]
	v_mfma_f32_16x16x32_bf16 v[90:93], v[134:137], v[182:185], v[90:93]
	v_mfma_f32_16x16x32_bf16 v[78:81], v[114:117], v[220:223], v[78:81]
	v_mfma_f32_16x16x32_bf16 v[74:77], v[134:137], v[220:223], v[74:77]
	v_mfma_f32_16x16x32_bf16 v[126:129], v[146:149], v[162:165], v[126:129]
	v_mfma_f32_16x16x32_bf16 v[122:125], v[154:157], v[162:165], v[122:125]
	v_mfma_f32_16x16x32_bf16 v[102:105], v[146:149], v[170:173], v[102:105]
	v_mfma_f32_16x16x32_bf16 v[98:101], v[154:157], v[170:173], v[98:101]
	v_mfma_f32_16x16x32_bf16 v[86:89], v[146:149], v[178:181], v[86:89]
	v_mfma_f32_16x16x32_bf16 v[82:85], v[154:157], v[178:181], v[82:85]
	v_mfma_f32_16x16x32_bf16 v[70:73], v[146:149], v[216:219], v[70:73]
	v_mfma_f32_16x16x32_bf16 v[66:69], v[154:157], v[216:219], v[66:69]
	v_mfma_f32_16x16x32_bf16 v[126:129], v[150:153], v[166:169], v[126:129]
	v_mfma_f32_16x16x32_bf16 v[122:125], v[158:161], v[166:169], v[122:125]
	v_mfma_f32_16x16x32_bf16 v[102:105], v[150:153], v[174:177], v[102:105]
	v_mfma_f32_16x16x32_bf16 v[98:101], v[158:161], v[174:177], v[98:101]
	v_mfma_f32_16x16x32_bf16 v[86:89], v[150:153], v[182:185], v[86:89]
	v_mfma_f32_16x16x32_bf16 v[82:85], v[158:161], v[182:185], v[82:85]
	v_mfma_f32_16x16x32_bf16 v[70:73], v[150:153], v[220:223], v[70:73]
	v_mfma_f32_16x16x32_bf16 v[66:69], v[158:161], v[220:223], v[66:69]
; #define PG8_STAGE(bufoff, gbase, voff) do { _Pragma("unroll") for (int _i = 0; _i < 2; ++_i) \
;         __builtin_amdgcn_global_load_lds((const unsigned*)((const char*)(gbase) + (voff)[_i]), (LAS unsigned*)(lds + (bufoff) + ldsw + _i * 8192), 16, 0, 0); } while (0)
; #define PG8_LDA(dst, b, h) do { _Pragma("unroll") for (int m = 0; m < 4; ++m) _Pragma("unroll") for (int k = 0; k < 2; ++k) dst[m][k] = *(const LAS bf16x8*)(lds + PG8_SA(b, h) + aoff + m * 2048 + k * 1024); } while (0)
; #define PG8_LDB(dst, b, h) do { _Pragma("unroll") for (int n = 0; n < 2; ++n) _Pragma("unroll") for (int k = 0; k < 2; ++k) dst[n][k] = *(const LAS bf16x8*)(lds + PG8_SB(b, h) + boff + n * 2048 + k * 1024); } while (0)
; #define PG8_MMA(ai, bj, At, Bt) do { __builtin_amdgcn_s_setprio(1); _Pragma("unroll") for (int m = 0; m < 4; ++m) _Pragma("unroll") for (int n = 0; n < 2; ++n) _Pragma("unroll") for (int k = 0; k < 2; ++k) \
;         acc[ai][bj][m][n] = __builtin_amdgcn_mfma_f32_16x16x32_bf16(Bt[n][k], At[m][k], acc[ai][bj][m][n], 0, 0, 0); __builtin_amdgcn_s_setprio(0); } while (0)
; #define PG8_WAIT_V(n) asm volatile("s_waitcnt vmcnt(" #n ")" ::: "memory")
; #define PG8_BAR __builtin_amdgcn_s_barrier()
; template <class Epi>
; __device__ __forceinline__ void gemm_phase(LAS unsigned char* lds, const Gemm g, const Sched& S, const Epi& E) {
;     ...
;             PG8_LDB(B0, 0, 0); PG8_LDB(B1, 0, 1); PG8_SCHED; PG8_LDA(At, 0, 0); PG8_STAGE(PG8_SA(1, 1), a1 + hstepA, voffA);
;             PG8_WAIT_V(8); PG8_WAIT_L(0); PG8_BAR; PG8_MMA(0, 0, At, B0); PG8_MMA(0, 1, At, B1); PG8_BAR; PG8_SCHED;
;             PG8_LDA(At, 0, 1); PG8_STAGE(PG8_SB(0, 0), b2, voffB); PG8_STAGE(PG8_SB(0, 1), b2 + hstepB, voffB); PG8_STAGE(PG8_SA(0, 0), a2, voffA);
;             PG8_WAIT_V(8); PG8_WAIT_L(0); PG8_BAR; PG8_MMA(1, 0, At, B0); PG8_MMA(1, 1, At, B1); PG8_BAR; PG8_SCHED;
;             PG8_LDB(B0, 1, 0); PG8_LDB(B1, 1, 1); PG8_SCHED; PG8_LDA(At, 1, 0); PG8_STAGE(PG8_SA(0, 1), a2 + hstepA, voffA);
;             PG8_WAIT_V(8); PG8_WAIT_L(0); PG8_BAR; PG8_MMA(0, 0, At, B0); PG8_MMA(0, 1, At, B1); PG8_BAR; PG8_SCHED;
;             PG8_LDA(At, 1, 1); PG8_STAGE(PG8_SB(1, 0), b3, voffB); PG8_STAGE(PG8_SB(1, 1), b3 + hstepB, voffB); PG8_STAGE(PG8_SA(1, 0), a3, voffA);
;             PG8_WAIT_V(8); PG8_WAIT_L(0); PG8_BAR; PG8_MMA(1, 0, At, B0); PG8_MMA(1, 1, At, B1); PG8_BAR; PG8_SCHED;
.Lcz_p8_0_j:
	s_barrier
	s_add_i32 s72, s57, s3
	v_lshl_add_u64 v[206:207], s[34:35], 0, v[188:189]
	s_mov_b32 m0, s72
	ds_read_b128 v[162:165], v213 offset:16384
	ds_read_b128 v[166:169], v213 offset:17408
	ds_read_b128 v[170:173], v213 offset:18432
	ds_read_b128 v[174:177], v213 offset:19456
	ds_read_b128 v[178:181], v213 offset:20480
	ds_read_b128 v[182:185], v213 offset:21504
	ds_read_b128 v[216:219], v213 offset:22528
	ds_read_b128 v[220:223], v213 offset:23552
	global_load_lds_dwordx4 v[206:207], off
	s_add_i32 m0, s72, 0x2000
	s_add_u32 s72, s34, 0x40000
	v_lshl_add_u64 v[224:225], s[34:35], 0, v[192:193]
	s_addc_u32 s73, s35, 0
	s_add_i32 s74, s58, s3
	global_load_lds_dwordx4 v[224:225], off
	v_lshl_add_u64 v[226:227], s[72:73], 0, v[188:189]
	s_mov_b32 m0, s74
	v_lshl_add_u64 v[228:229], s[36:37], 0, v[190:191]
	global_load_lds_dwordx4 v[226:227], off
	v_lshl_add_u64 v[226:227], s[72:73], 0, v[192:193]
	s_add_i32 m0, s74, 0x2000
	s_nop 0
	global_load_lds_dwordx4 v[226:227], off
	v_lshl_add_u64 v[226:227], s[36:37], 0, v[186:187]
	s_mov_b32 m0, s33
	s_nop 0
	global_load_lds_dwordx4 v[226:227], off
	s_mov_b32 m0, s38
	s_nop 0
	global_load_lds_dwordx4 v[228:229], off
	s_waitcnt vmcnt(8)
	s_waitcnt lgkmcnt(0)
	s_cmp_eq_u32 s67, -2
	s_cbranch_scc1 .Lcz_p8_1
	s_barrier
	s_waitcnt lgkmcnt(0)
	v_mfma_f32_16x16x32_bf16 v[62:65], v[106:109], v[162:165], v[62:65]
	v_mfma_f32_16x16x32_bf16 v[58:61], v[130:133], v[162:165], v[58:61]
	v_mfma_f32_16x16x32_bf16 v[46:49], v[106:109], v[170:173], v[46:49]
	v_mfma_f32_16x16x32_bf16 v[42:45], v[130:133], v[170:173], v[42:45]
	v_mfma_f32_16x16x32_bf16 v[30:33], v[106:109], v[178:181], v[30:33]
	v_mfma_f32_16x16x32_bf16 v[26:29], v[130:133], v[178:181], v[26:29]
	v_mfma_f32_16x16x32_bf16 v[14:17], v[106:109], v[216:219], v[14:17]
	v_mfma_f32_16x16x32_bf16 v[10:13], v[130:133], v[216:219], v[10:13]
	v_mfma_f32_16x16x32_bf16 v[62:65], v[114:117], v[166:169], v[62:65]
	v_mfma_f32_16x16x32_bf16 v[58:61], v[134:137], v[166:169], v[58:61]
	v_mfma_f32_16x16x32_bf16 v[46:49], v[114:117], v[174:177], v[46:49]
	v_mfma_f32_16x16x32_bf16 v[42:45], v[134:137], v[174:177], v[42:45]
	v_mfma_f32_16x16x32_bf16 v[30:33], v[114:117], v[182:185], v[30:33]
	v_mfma_f32_16x16x32_bf16 v[26:29], v[134:137], v[182:185], v[26:29]
	v_mfma_f32_16x16x32_bf16 v[14:17], v[114:117], v[220:223], v[14:17]
	v_mfma_f32_16x16x32_bf16 v[10:13], v[134:137], v[220:223], v[10:13]
	v_mfma_f32_16x16x32_bf16 v[54:57], v[146:149], v[162:165], v[54:57]
	v_mfma_f32_16x16x32_bf16 v[50:53], v[154:157], v[162:165], v[50:53]
	v_mfma_f32_16x16x32_bf16 v[38:41], v[146:149], v[170:173], v[38:41]
	v_mfma_f32_16x16x32_bf16 v[34:37], v[154:157], v[170:173], v[34:37]
	v_mfma_f32_16x16x32_bf16 v[22:25], v[146:149], v[178:181], v[22:25]
	v_mfma_f32_16x16x32_bf16 v[18:21], v[154:157], v[178:181], v[18:21]
	v_mfma_f32_16x16x32_bf16 v[6:9], v[146:149], v[216:219], v[6:9]
	v_mfma_f32_16x16x32_bf16 v[2:5], v[154:157], v[216:219], v[2:5]
	v_mfma_f32_16x16x32_bf16 v[54:57], v[150:153], v[166:169], v[54:57]
	v_mfma_f32_16x16x32_bf16 v[50:53], v[158:161], v[166:169], v[50:53]
	v_mfma_f32_16x16x32_bf16 v[38:41], v[150:153], v[174:177], v[38:41]
	v_mfma_f32_16x16x32_bf16 v[34:37], v[158:161], v[174:177], v[34:37]
	v_mfma_f32_16x16x32_bf16 v[22:25], v[150:153], v[182:185], v[22:25]
	v_mfma_f32_16x16x32_bf16 v[18:21], v[158:161], v[182:185], v[18:21]
	v_mfma_f32_16x16x32_bf16 v[6:9], v[150:153], v[220:223], v[6:9]
	v_mfma_f32_16x16x32_bf16 v[2:5], v[158:161], v[220:223], v[2:5]
.Lcz_p8_1_j:
	s_barrier
	s_add_i32 s72, 0, 0x18000
	s_add_i32 s73, 0, 0x1c000
	v_add_u32_e32 v134, s72, v210
	v_add_u32_e32 v158, s73, v210
	ds_read_b128 v[106:109], v134
	ds_read_b128 v[114:117], v134 offset:1024
	ds_read_b128 v[130:133], v134 offset:2048
	ds_read_b128 v[134:137], v134 offset:3072
	ds_read_b128 v[146:149], v158
	ds_read_b128 v[150:153], v158 offset:1024
	ds_read_b128 v[154:157], v158 offset:2048
	ds_read_b128 v[158:161], v158 offset:3072
	s_add_u32 s36, s36, 0x80000
	s_addc_u32 s37, s37, 0
	s_mov_b32 m0, s39
	v_lshl_add_u64 v[230:231], s[36:37], 0, v[186:187]
	ds_read_b128 v[162:165], v213 offset:32768
	ds_read_b128 v[166:169], v213 offset:33792
	ds_read_b128 v[170:173], v213 offset:34816
	ds_read_b128 v[174:177], v213 offset:35840
	ds_read_b128 v[178:181], v213 offset:36864
	ds_read_b128 v[182:185], v213 offset:37888
	ds_read_b128 v[216:219], v213 offset:38912
	ds_read_b128 v[220:223], v213 offset:39936
	global_load_lds_dwordx4 v[230:231], off
	v_lshl_add_u64 v[230:231], s[36:37], 0, v[190:191]
	s_mov_b32 m0, s42
	s_nop 0
	global_load_lds_dwordx4 v[230:231], off
	s_waitcnt vmcnt(8)
	s_waitcnt lgkmcnt(0)
	s_barrier
; #define PG8_STAGE(bufoff, gbase, voff) do { _Pragma("unroll") for (int _i = 0; _i < 2; ++_i) \
;         __builtin_amdgcn_global_load_lds((const unsigned*)((const char*)(gbase) + (voff)[_i]), (LAS unsigned*)(lds + (bufoff) + ldsw + _i * 8192), 16, 0, 0); } while (0)
; #define PG8_LDA(dst, b, h) do { _Pragma("unroll") for (int m = 0; m < 4; ++m) _Pragma("unroll") for (int k = 0; k < 2; ++k) dst[m][k] = *(const LAS bf16x8*)(lds + PG8_SA(b, h) + aoff + m * 2048 + k * 1024); } while (0)
; #define PG8_LDB(dst, b, h) do { _Pragma("unroll") for (int n = 0; n < 2; ++n) _Pragma("unroll") for (int k = 0; k < 2; ++k) dst[n][k] = *(const LAS bf16x8*)(lds + PG8_SB(b, h) + boff + n * 2048 + k * 1024); } while (0)
; #define PG8_MMA(ai, bj, At, Bt) do { __builtin_amdgcn_s_setprio(1); _Pragma("unroll") for (int m = 0; m < 4; ++m) _Pragma("unroll") for (int n = 0; n < 2; ++n) _Pragma("unroll") for (int k = 0; k < 2; ++k) \
;         acc[ai][bj][m][n] = __builtin_amdgcn_mfma_f32_16x16x32_bf16(Bt[n][k], At[m][k], acc[ai][bj][m][n], 0, 0, 0); __builtin_amdgcn_s_setprio(0); } while (0)
; #define PG8_WAIT_V(n) asm volatile("s_waitcnt vmcnt(" #n ")" ::: "memory")
; #define PG8_BAR __builtin_amdgcn_s_barrier()
; template <class Epi>
; __device__ __forceinline__ void gemm_phase(LAS unsigned char* lds, const Gemm g, const Sched& S, const Epi& E) {
;     ...
;             PG8_LDB(B0, 0, 0); PG8_LDB(B1, 0, 1); PG8_SCHED; PG8_LDA(At, 0, 0); PG8_STAGE(PG8_SA(1, 1), a1 + hstepA, voffA);
;             PG8_WAIT_V(8); PG8_WAIT_L(0); PG8_BAR; PG8_MMA(0, 0, At, B0); PG8_MMA(0, 1, At, B1); PG8_BAR; PG8_SCHED;
;             PG8_LDA(At, 0, 1); PG8_STAGE(PG8_SB(0, 0), b2, voffB); PG8_STAGE(PG8_SB(0, 1), b2 + hstepB, voffB); PG8_STAGE(PG8_SA(0, 0), a2, voffA);
;             PG8_WAIT_V(8); PG8_WAIT_L(0); PG8_BAR; PG8_MMA(1, 0, At, B0); PG8_MMA(1, 1, At, B1); PG8_BAR; PG8_SCHED;
;             PG8_LDB(B0, 1, 0); PG8_LDB(B1, 1, 1); PG8_SCHED; PG8_LDA(At, 1, 0); PG8_STAGE(PG8_SA(0, 1), a2 + hstepA, voffA);
;             PG8_WAIT_V(8); PG8_WAIT_L(0); PG8_BAR; PG8_MMA(0, 0, At, B0); PG8_MMA(0, 1, At, B1); PG8_BAR; PG8_SCHED;
;             PG8_LDA(At, 1, 1); PG8_STAGE(PG8_SB(1, 0), b3, voffB); PG8_STAGE(PG8_SB(1, 1), b3 + hstepB, voffB); PG8_STAGE(PG8_SA(1, 0), a3, voffA);
;             PG8_WAIT_V(8); PG8_WAIT_L(0); PG8_BAR; PG8_MMA(1, 0, At, B0); PG8_MMA(1, 1, At, B1); PG8_BAR; PG8_SCHED;
;         }
	s_waitcnt lgkmcnt(0)
	v_mfma_f32_16x16x32_bf16 v[142:145], v[106:109], v[162:165], v[142:145]
	v_mfma_f32_16x16x32_bf16 v[138:141], v[130:133], v[162:165], v[138:141]
	v_mfma_f32_16x16x32_bf16 v[118:121], v[106:109], v[170:173], v[118:121]
	v_mfma_f32_16x16x32_bf16 v[110:113], v[130:133], v[170:173], v[110:113]
	v_mfma_f32_16x16x32_bf16 v[94:97], v[106:109], v[178:181], v[94:97]
	v_mfma_f32_16x16x32_bf16 v[90:93], v[130:133], v[178:181], v[90:93]
	v_mfma_f32_16x16x32_bf16 v[78:81], v[106:109], v[216:219], v[78:81]
	v_mfma_f32_16x16x32_bf16 v[74:77], v[130:133], v[216:219], v[74:77]
	v_mfma_f32_16x16x32_bf16 v[142:145], v[114:117], v[166:169], v[142:145]
	v_mfma_f32_16x16x32_bf16 v[138:141], v[134:137], v[166:169], v[138:141]
	v_mfma_f32_16x16x32_bf16 v[118:121], v[114:117], v[174:177], v[118:121]
	v_mfma_f32_16x16x32_bf16 v[110:113], v[134:137], v[174:177], v[110:113]
	v_mfma_f32_16x16x32_bf16 v[94:97], v[114:117], v[182:185], v[94:97]
	v_mfma_f32_16x16x32_bf16 v[90:93], v[134:137], v[182:185], v[90:93]
	v_mfma_f32_16x16x32_bf16 v[78:81], v[114:117], v[220:223], v[78:81]
	v_mfma_f32_16x16x32_bf16 v[74:77], v[134:137], v[220:223], v[74:77]
	v_mfma_f32_16x16x32_bf16 v[126:129], v[146:149], v[162:165], v[126:129]
	v_mfma_f32_16x16x32_bf16 v[122:125], v[154:157], v[162:165], v[122:125]
	v_mfma_f32_16x16x32_bf16 v[102:105], v[146:149], v[170:173], v[102:105]
	v_mfma_f32_16x16x32_bf16 v[98:101], v[154:157], v[170:173], v[98:101]
	v_mfma_f32_16x16x32_bf16 v[86:89], v[146:149], v[178:181], v[86:89]
	v_mfma_f32_16x16x32_bf16 v[82:85], v[154:157], v[178:181], v[82:85]
	v_mfma_f32_16x16x32_bf16 v[70:73], v[146:149], v[216:219], v[70:73]
	v_mfma_f32_16x16x32_bf16 v[66:69], v[154:157], v[216:219], v[66:69]
	v_mfma_f32_16x16x32_bf16 v[126:129], v[150:153], v[166:169], v[126:129]
	v_mfma_f32_16x16x32_bf16 v[122:125], v[158:161], v[166:169], v[122:125]
	v_mfma_f32_16x16x32_bf16 v[102:105], v[150:153], v[174:177], v[102:105]
	v_mfma_f32_16x16x32_bf16 v[98:101], v[158:161], v[174:177], v[98:101]
	v_mfma_f32_16x16x32_bf16 v[86:89], v[150:153], v[182:185], v[86:89]
	v_mfma_f32_16x16x32_bf16 v[82:85], v[158:161], v[182:185], v[82:85]
	v_mfma_f32_16x16x32_bf16 v[70:73], v[150:153], v[220:223], v[70:73]
	v_mfma_f32_16x16x32_bf16 v[66:69], v[158:161], v[220:223], v[66:69]
	s_barrier
	s_add_i32 s36, s72, s3
	v_lshl_add_u64 v[206:207], v[206:207], 0, s[18:19]
	s_mov_b32 m0, s36
	ds_read_b128 v[162:165], v213 offset:49152
	ds_read_b128 v[166:169], v213 offset:50176
	ds_read_b128 v[170:173], v213 offset:51200
	ds_read_b128 v[174:177], v213 offset:52224
	ds_read_b128 v[178:181], v213 offset:53248
	ds_read_b128 v[182:185], v213 offset:54272
	ds_read_b128 v[216:219], v213 offset:55296
	ds_read_b128 v[220:223], v213 offset:56320
	global_load_lds_dwordx4 v[206:207], off
	s_add_i32 m0, s36, 0x2000
	s_add_u32 s34, s34, 0x40080
	v_lshl_add_u64 v[206:207], v[224:225], 0, s[18:19]
	s_addc_u32 s35, s35, 0
	s_add_i32 s36, s73, s3
	global_load_lds_dwordx4 v[206:207], off
	v_lshl_add_u64 v[206:207], s[34:35], 0, v[188:189]
	s_mov_b32 m0, s36
	s_nop 0
	global_load_lds_dwordx4 v[206:207], off
	v_lshl_add_u64 v[206:207], s[34:35], 0, v[192:193]
	s_add_i32 m0, s36, 0x2000
	s_nop 0
	global_load_lds_dwordx4 v[206:207], off
	v_lshl_add_u64 v[206:207], v[226:227], 0, s[18:19]
	s_mov_b32 m0, s45
	s_nop 0
	global_load_lds_dwordx4 v[206:207], off
	v_lshl_add_u64 v[206:207], v[228:229], 0, s[18:19]
	s_mov_b32 m0, s52
	s_nop 0
	global_load_lds_dwordx4 v[206:207], off
	s_waitcnt vmcnt(8)
	s_waitcnt lgkmcnt(0)
	s_barrier
	s_waitcnt lgkmcnt(0)
	v_mfma_f32_16x16x32_bf16 v[62:65], v[106:109], v[162:165], v[62:65]
	v_mfma_f32_16x16x32_bf16 v[58:61], v[130:133], v[162:165], v[58:61]
	v_mfma_f32_16x16x32_bf16 v[46:49], v[106:109], v[170:173], v[46:49]
	v_mfma_f32_16x16x32_bf16 v[42:45], v[130:133], v[170:173], v[42:45]
	v_mfma_f32_16x16x32_bf16 v[30:33], v[106:109], v[178:181], v[30:33]
	v_mfma_f32_16x16x32_bf16 v[26:29], v[130:133], v[178:181], v[26:29]
	v_mfma_f32_16x16x32_bf16 v[14:17], v[106:109], v[216:219], v[14:17]
	v_mfma_f32_16x16x32_bf16 v[10:13], v[130:133], v[216:219], v[10:13]
	v_mfma_f32_16x16x32_bf16 v[62:65], v[114:117], v[166:169], v[62:65]
	v_mfma_f32_16x16x32_bf16 v[58:61], v[134:137], v[166:169], v[58:61]
	v_mfma_f32_16x16x32_bf16 v[46:49], v[114:117], v[174:177], v[46:49]
	v_mfma_f32_16x16x32_bf16 v[42:45], v[134:137], v[174:177], v[42:45]
	v_mfma_f32_16x16x32_bf16 v[30:33], v[114:117], v[182:185], v[30:33]
	v_mfma_f32_16x16x32_bf16 v[26:29], v[134:137], v[182:185], v[26:29]
	v_mfma_f32_16x16x32_bf16 v[14:17], v[114:117], v[220:223], v[14:17]
	v_mfma_f32_16x16x32_bf16 v[10:13], v[134:137], v[220:223], v[10:13]
	v_mfma_f32_16x16x32_bf16 v[54:57], v[146:149], v[162:165], v[54:57]
	v_mfma_f32_16x16x32_bf16 v[50:53], v[154:157], v[162:165], v[50:53]
	v_mfma_f32_16x16x32_bf16 v[38:41], v[146:149], v[170:173], v[38:41]
	v_mfma_f32_16x16x32_bf16 v[34:37], v[154:157], v[170:173], v[34:37]
	v_mfma_f32_16x16x32_bf16 v[22:25], v[146:149], v[178:181], v[22:25]
	v_mfma_f32_16x16x32_bf16 v[18:21], v[154:157], v[178:181], v[18:21]
	v_mfma_f32_16x16x32_bf16 v[6:9], v[146:149], v[216:219], v[6:9]
	v_mfma_f32_16x16x32_bf16 v[2:5], v[154:157], v[216:219], v[2:5]
	v_mfma_f32_16x16x32_bf16 v[54:57], v[150:153], v[166:169], v[54:57]
	v_mfma_f32_16x16x32_bf16 v[50:53], v[158:161], v[166:169], v[50:53]
	v_mfma_f32_16x16x32_bf16 v[38:41], v[150:153], v[174:177], v[38:41]
	v_mfma_f32_16x16x32_bf16 v[34:37], v[158:161], v[174:177], v[34:37]
	v_mfma_f32_16x16x32_bf16 v[22:25], v[150:153], v[182:185], v[22:25]
	v_mfma_f32_16x16x32_bf16 v[18:21], v[158:161], v[182:185], v[18:21]
	v_mfma_f32_16x16x32_bf16 v[6:9], v[150:153], v[220:223], v[6:9]
	v_mfma_f32_16x16x32_bf16 v[2:5], v[158:161], v[220:223], v[2:5]
	s_barrier
	s_add_i32 s67, s67, 2
	s_add_u32 s30, s30, 0x100
	s_addc_u32 s31, s31, 0
	s_add_u32 s65, s65, 0x100
	s_addc_u32 s66, s66, 0
	s_cmp_gt_u32 s67, 13
	s_cbranch_scc0 .LBB0_1576
	s_and_b64 vcc, exec, s[20:21]
	s_cbranch_vccz .LBB0_1579
	s_barrier

; #define PG8_STAGE(bufoff, gbase, voff) do { _Pragma("unroll") for (int _i = 0; _i < 2; ++_i) \
;         __builtin_amdgcn_global_load_lds((const unsigned*)((const char*)(gbase) + (voff)[_i]), (LAS unsigned*)(lds + (bufoff) + ldsw + _i * 8192), 16, 0, 0); } while (0)
; #define PG8_LDA(dst, b, h) do { _Pragma("unroll") for (int m = 0; m < 4; ++m) _Pragma("unroll") for (int k = 0; k < 2; ++k) dst[m][k] = *(const LAS bf16x8*)(lds + PG8_SA(b, h) + aoff + m * 2048 + k * 1024); } while (0)
; #define PG8_LDB(dst, b, h) do { _Pragma("unroll") for (int n = 0; n < 2; ++n) _Pragma("unroll") for (int k = 0; k < 2; ++k) dst[n][k] = *(const LAS bf16x8*)(lds + PG8_SB(b, h) + boff + n * 2048 + k * 1024); } while (0)
; #define PG8_MMA(ai, bj, At, Bt) do { __builtin_amdgcn_s_setprio(1); _Pragma("unroll") for (int m = 0; m < 4; ++m) _Pragma("unroll") for (int n = 0; n < 2; ++n) _Pragma("unroll") for (int k = 0; k < 2; ++k) \
;         acc[ai][bj][m][n] = __builtin_amdgcn_mfma_f32_16x16x32_bf16(Bt[n][k], At[m][k], acc[ai][bj][m][n], 0, 0, 0); __builtin_amdgcn_s_setprio(0); } while (0)
; #define PG8_WAIT_V(n) asm volatile("s_waitcnt vmcnt(" #n ")" ::: "memory")
; #define PG8_WAIT_L(n) asm volatile("s_waitcnt lgkmcnt(" #n ")" ::: "memory")
; #define PG8_BAR __builtin_amdgcn_s_barrier()
; #define PG8_SCHED __builtin_amdgcn_sched_barrier(0)
; template <class Epi>
; __device__ __forceinline__ void gemm_phase(LAS unsigned char* lds, const Gemm g, const Sched& S, const Epi& E) {
;     ...
;             PG8_LDB(B0, 0, 0); PG8_LDB(B1, 0, 1); PG8_SCHED; PG8_LDA(At, 0, 0); PG8_STAGE(PG8_SA(1, 1), a1 + hstepA, voffA);
;             PG8_WAIT_V(8); PG8_WAIT_L(0); PG8_BAR; PG8_MMA(0, 0, At, B0); PG8_MMA(0, 1, At, B1); PG8_BAR; PG8_SCHED;
;             PG8_LDA(At, 0, 1); PG8_STAGE(PG8_SB(0, 0), b2, voffB); PG8_STAGE(PG8_SB(0, 1), b2 + hstepB, voffB); PG8_STAGE(PG8_SA(0, 0), a2, voffA);
;             PG8_WAIT_V(8); PG8_WAIT_L(0); PG8_BAR; PG8_MMA(1, 0, At, B0); PG8_MMA(1, 1, At, B1); PG8_BAR; PG8_SCHED;
.Lcz_p8_0:
	s_barrier
	s_waitcnt lgkmcnt(0)
	v_mfma_f32_16x16x32_bf16 v[142:145], v[106:109], v[162:165], 0
	v_mfma_f32_16x16x32_bf16 v[138:141], v[130:133], v[162:165], 0
	v_mfma_f32_16x16x32_bf16 v[118:121], v[106:109], v[170:173], 0
	v_mfma_f32_16x16x32_bf16 v[110:113], v[130:133], v[170:173], 0
	v_mfma_f32_16x16x32_bf16 v[94:97], v[106:109], v[178:181], 0
	v_mfma_f32_16x16x32_bf16 v[90:93], v[130:133], v[178:181], 0
	v_mfma_f32_16x16x32_bf16 v[78:81], v[106:109], v[216:219], 0
	v_mfma_f32_16x16x32_bf16 v[74:77], v[130:133], v[216:219], 0
	v_mfma_f32_16x16x32_bf16 v[142:145], v[114:117], v[166:169], v[142:145]
	v_mfma_f32_16x16x32_bf16 v[138:141], v[134:137], v[166:169], v[138:141]
	v_mfma_f32_16x16x32_bf16 v[118:121], v[114:117], v[174:177], v[118:121]
	v_mfma_f32_16x16x32_bf16 v[110:113], v[134:137], v[174:177], v[110:113]
	v_mfma_f32_16x16x32_bf16 v[94:97], v[114:117], v[182:185], v[94:97]
	v_mfma_f32_16x16x32_bf16 v[90:93], v[134:137], v[182:185], v[90:93]
	v_mfma_f32_16x16x32_bf16 v[78:81], v[114:117], v[220:223], v[78:81]
	v_mfma_f32_16x16x32_bf16 v[74:77], v[134:137], v[220:223], v[74:77]
	v_mfma_f32_16x16x32_bf16 v[126:129], v[146:149], v[162:165], 0
	v_mfma_f32_16x16x32_bf16 v[122:125], v[154:157], v[162:165], 0
	v_mfma_f32_16x16x32_bf16 v[102:105], v[146:149], v[170:173], 0
	v_mfma_f32_16x16x32_bf16 v[98:101], v[154:157], v[170:173], 0
	v_mfma_f32_16x16x32_bf16 v[86:89], v[146:149], v[178:181], 0
	v_mfma_f32_16x16x32_bf16 v[82:85], v[154:157], v[178:181], 0
	v_mfma_f32_16x16x32_bf16 v[70:73], v[146:149], v[216:219], 0
	v_mfma_f32_16x16x32_bf16 v[66:69], v[154:157], v[216:219], 0
	v_mfma_f32_16x16x32_bf16 v[126:129], v[150:153], v[166:169], v[126:129]
	v_mfma_f32_16x16x32_bf16 v[122:125], v[158:161], v[166:169], v[122:125]
	v_mfma_f32_16x16x32_bf16 v[102:105], v[150:153], v[174:177], v[102:105]
	v_mfma_f32_16x16x32_bf16 v[98:101], v[158:161], v[174:177], v[98:101]
	v_mfma_f32_16x16x32_bf16 v[86:89], v[150:153], v[182:185], v[86:89]
	v_mfma_f32_16x16x32_bf16 v[82:85], v[158:161], v[182:185], v[82:85]
	v_mfma_f32_16x16x32_bf16 v[70:73], v[150:153], v[220:223], v[70:73]
	v_mfma_f32_16x16x32_bf16 v[66:69], v[158:161], v[220:223], v[66:69]
	s_branch .Lcz_p8_0_j
.Lcz_p8_1:
	s_barrier
	s_waitcnt lgkmcnt(0)
	v_mfma_f32_16x16x32_bf16 v[62:65], v[106:109], v[162:165], 0
	v_mfma_f32_16x16x32_bf16 v[58:61], v[130:133], v[162:165], 0
	v_mfma_f32_16x16x32_bf16 v[46:49], v[106:109], v[170:173], 0
	v_mfma_f32_16x16x32_bf16 v[42:45], v[130:133], v[170:173], 0
	v_mfma_f32_16x16x32_bf16 v[30:33], v[106:109], v[178:181], 0
	v_mfma_f32_16x16x32_bf16 v[26:29], v[130:133], v[178:181], 0
	v_mfma_f32_16x16x32_bf16 v[14:17], v[106:109], v[216:219], 0
	v_mfma_f32_16x16x32_bf16 v[10:13], v[130:133], v[216:219], 0
	v_mfma_f32_16x16x32_bf16 v[62:65], v[114:117], v[166:169], v[62:65]
	v_mfma_f32_16x16x32_bf16 v[58:61], v[134:137], v[166:169], v[58:61]
	v_mfma_f32_16x16x32_bf16 v[46:49], v[114:117], v[174:177], v[46:49]
	v_mfma_f32_16x16x32_bf16 v[42:45], v[134:137], v[174:177], v[42:45]
	v_mfma_f32_16x16x32_bf16 v[30:33], v[114:117], v[182:185], v[30:33]
	v_mfma_f32_16x16x32_bf16 v[26:29], v[134:137], v[182:185], v[26:29]
	v_mfma_f32_16x16x32_bf16 v[14:17], v[114:117], v[220:223], v[14:17]
	v_mfma_f32_16x16x32_bf16 v[10:13], v[134:137], v[220:223], v[10:13]
	v_mfma_f32_16x16x32_bf16 v[54:57], v[146:149], v[162:165], 0
	v_mfma_f32_16x16x32_bf16 v[50:53], v[154:157], v[162:165], 0
	v_mfma_f32_16x16x32_bf16 v[38:41], v[146:149], v[170:173], 0
	v_mfma_f32_16x16x32_bf16 v[34:37], v[154:157], v[170:173], 0
	v_mfma_f32_16x16x32_bf16 v[22:25], v[146:149], v[178:181], 0
	v_mfma_f32_16x16x32_bf16 v[18:21], v[154:157], v[178:181], 0
	v_mfma_f32_16x16x32_bf16 v[6:9], v[146:149], v[216:219], 0
	v_mfma_f32_16x16x32_bf16 v[2:5], v[154:157], v[216:219], 0
	v_mfma_f32_16x16x32_bf16 v[54:57], v[150:153], v[166:169], v[54:57]
	v_mfma_f32_16x16x32_bf16 v[50:53], v[158:161], v[166:169], v[50:53]
	v_mfma_f32_16x16x32_bf16 v[38:41], v[150:153], v[174:177], v[38:41]
	v_mfma_f32_16x16x32_bf16 v[34:37], v[158:161], v[174:177], v[34:37]
	v_mfma_f32_16x16x32_bf16 v[22:25], v[150:153], v[182:185], v[22:25]
	v_mfma_f32_16x16x32_bf16 v[18:21], v[158:161], v[182:185], v[18:21]
	v_mfma_f32_16x16x32_bf16 v[6:9], v[150:153], v[220:223], v[6:9]
	v_mfma_f32_16x16x32_bf16 v[2:5], v[158:161], v[220:223], v[2:5]
	s_branch .Lcz_p8_1_j

; __device__ __forceinline__ unsigned xb_add(unsigned* p, unsigned v) { return __hip_atomic_fetch_add(p, v, __ATOMIC_RELAXED, __HIP_MEMORY_SCOPE_AGENT); }
; __device__ __forceinline__ void xcd_barrier(const XcdBarrier& b) {
;     asm volatile("s_waitcnt vmcnt(0)" ::: "memory");
;     __syncthreads();
;     if (threadIdx.x == 0) {
;         unsigned* bar = b.bar;
;         __builtin_amdgcn_s_waitcnt(0);
;         unsigned nloc = b.st[0], nx = b.st[1];
;         if (nloc == 0u) { xcd_barrier_complete(bar, b.x, nloc, nx); b.st[0] = nloc; b.st[1] = nx; }
;         const unsigned old = xb_add(&bar[XB_XSUB(b.x)], 1u);
;         const unsigned gen = old / nloc;
;         if (old + 1u == (gen + 1u) * nloc) {
;             __builtin_amdgcn_fence(__ATOMIC_RELEASE, "agent");
.LBB0_1608:
	s_cmp_gt_i32 s85, 9
	s_cselect_b64 s[0:1], -1, 0
	s_and_b64 s[4:5], s[12:13], s[0:1]
	s_andn2_b64 vcc, exec, s[4:5]
	v_readlane_b32 s82, v252, 26
	v_readlane_b32 s83, v252, 27
	s_cbranch_vccnz .LBB0_1658
	s_setprio 0
	s_waitcnt vmcnt(0) lgkmcnt(0)
	s_barrier
	v_readfirstlane_b32 s98, v0
	s_cmp_lg_u32 s98, 0
	s_cbranch_scc1 .Lxb8_end
	s_mov_b64 s[100:101], exec
	v_readlane_b32 s98, v253, 0
	s_cmp_lg_u32 s98, 0
	s_cbranch_scc1 .Lxb8_have
	s_mov_b64 exec, 0xffff
	v_mbcnt_lo_u32_b32 v254, -1, 0
	v_lshlrev_b32_e32 v254, 8, v254
	s_mov_b32 s99, 0
	v_writelane_b32 v253, s99, 3

; #define PG8_STAGE(bufoff, gbase, voff) do { _Pragma("unroll") for (int _i = 0; _i < 2; ++_i) \
;         __builtin_amdgcn_global_load_lds((const unsigned*)((const char*)(gbase) + (voff)[_i]), (LAS unsigned*)(lds + (bufoff) + ldsw + _i * 8192), 16, 0, 0); } while (0)
; #define PG8_LDA(dst, b, h) do { _Pragma("unroll") for (int m = 0; m < 4; ++m) _Pragma("unroll") for (int k = 0; k < 2; ++k) dst[m][k] = *(const LAS bf16x8*)(lds + PG8_SA(b, h) + aoff + m * 2048 + k * 1024); } while (0)
; #define PG8_LDB(dst, b, h) do { _Pragma("unroll") for (int n = 0; n < 2; ++n) _Pragma("unroll") for (int k = 0; k < 2; ++k) dst[n][k] = *(const LAS bf16x8*)(lds + PG8_SB(b, h) + boff + n * 2048 + k * 1024); } while (0)
; #define PG8_SCHED __builtin_amdgcn_sched_barrier(0)
; template <class Epi>
; __device__ __forceinline__ void gemm_phase(LAS unsigned char* lds, const Gemm g, const Sched& S, const Epi& E) {
;     ...
;         const bool has_next = S.next(ui + 1, nxt);
;         const char* nA = has_next ? (const char*)g.A + (size_t)nxt.pm * tstepA + (size_t)nxt.part * g.koff * 2 : cA; const char* nB = has_next ? (const char*)g.Bt + (size_t)nxt.pn * tstepB + (size_t)nxt.part * g.koff * 2 : cB;
;         for (int t = 0; t < nt; t += 2) {
;             const bool last = (t == nt - 2);
;             const char* a1 = cA + (size_t)(t + 1) * kstep;
;             const char* a2 = last ? nA : cA + (size_t)(t + 2) * kstep; const char* b2 = last ? nB : cB + (size_t)(t + 2) * kstep;
;             const char* a3 = a2 + kstep; const char* b3 = b2 + kstep;
;             PG8_LDB(B0, 0, 0); PG8_LDB(B1, 0, 1); PG8_SCHED; PG8_LDA(At, 0, 0); PG8_STAGE(PG8_SA(1, 1), a1 + hstepA, voffA);
.LBB0_1717:
	s_ashr_i32 s15, s14, 31
	s_lshl_b64 s[16:17], s[14:15], 19
	s_add_u32 s16, s40, s16
	s_addc_u32 s17, s41, s17
	s_and_b64 s[18:19], s[0:1], exec
	s_cselect_b32 s15, s17, s23
	s_cselect_b32 s45, s16, s22
	s_ashr_i32 s11, s10, 31
	s_lshl_b64 s[18:19], s[10:11], 19
	v_readlane_b32 s26, v252, 9
	v_readlane_b32 s27, v252, 10
	s_add_u32 s18, s26, s18
	s_addc_u32 s19, s27, s19
	s_and_b64 s[26:27], s[0:1], exec
	s_cselect_b32 s11, s19, s25
	s_cselect_b32 s46, s18, s24
	s_add_u32 s22, s22, 0x40080
	s_addc_u32 s23, s23, 0
	s_add_u32 s47, s24, 0x100
	s_addc_u32 s52, s25, 0
	s_mov_b32 s53, -2
	v_readfirstlane_b32 s100, v0
	s_lshr_b32 s100, s100, 8
	s_cmp_eq_u32 s100, 0
	s_cbranch_scc0 .Lprio_5
	s_setprio 1
.Lprio_5:
.LBB0_1718:
	ds_read_b128 v[156:159], v153
	ds_read_b128 v[160:163], v153 offset:1024
	ds_read_b128 v[164:167], v153 offset:2048
	ds_read_b128 v[168:171], v153 offset:3072
	ds_read_b128 v[172:175], v154
	ds_read_b128 v[176:179], v154 offset:1024
	ds_read_b128 v[180:183], v154 offset:2048
	ds_read_b128 v[184:187], v154 offset:3072
	s_add_u32 s24, s22, 0xfffc0080
	s_addc_u32 s25, s23, -1
	s_cmp_eq_u32 s53, 12
	s_cselect_b32 s27, s15, s25
	s_cselect_b32 s26, s45, s24
	s_cselect_b32 s25, s11, s52
	s_cselect_b32 s24, s46, s47
	v_lshl_add_u64 v[196:197], s[22:23], 0, v[138:139]
	s_add_i32 m0, s21, 0xc000
	ds_read_b128 v[188:191], v155
	ds_read_b128 v[192:195], v155 offset:1024
	ds_read_b128 v[200:203], v155 offset:2048
	ds_read_b128 v[204:207], v155 offset:3072
	ds_read_b128 v[208:211], v155 offset:4096
	ds_read_b128 v[212:215], v155 offset:5120
	ds_read_b128 v[216:219], v155 offset:6144
	ds_read_b128 v[220:223], v155 offset:7168
	s_cmp_lg_u32 s98, 0
	s_cbranch_scc1 .Lpi_p9_s
	global_load_lds_dwordx4 v[196:197], off
	v_lshl_add_u64 v[196:197], s[22:23], 0, v[140:141]
	s_add_i32 m0, s21, 0xe000
	s_nop 0
	global_load_lds_dwordx4 v[196:197], off

; #define PG8_STAGE(bufoff, gbase, voff) do { _Pragma("unroll") for (int _i = 0; _i < 2; ++_i) \
;         __builtin_amdgcn_global_load_lds((const unsigned*)((const char*)(gbase) + (voff)[_i]), (LAS unsigned*)(lds + (bufoff) + ldsw + _i * 8192), 16, 0, 0); } while (0)
; #define PG8_LDA(dst, b, h) do { _Pragma("unroll") for (int m = 0; m < 4; ++m) _Pragma("unroll") for (int k = 0; k < 2; ++k) dst[m][k] = *(const LAS bf16x8*)(lds + PG8_SA(b, h) + aoff + m * 2048 + k * 1024); } while (0)
; #define PG8_LDB(dst, b, h) do { _Pragma("unroll") for (int n = 0; n < 2; ++n) _Pragma("unroll") for (int k = 0; k < 2; ++k) dst[n][k] = *(const LAS bf16x8*)(lds + PG8_SB(b, h) + boff + n * 2048 + k * 1024); } while (0)
; #define PG8_MMA(ai, bj, At, Bt) do { __builtin_amdgcn_s_setprio(1); _Pragma("unroll") for (int m = 0; m < 4; ++m) _Pragma("unroll") for (int n = 0; n < 2; ++n) _Pragma("unroll") for (int k = 0; k < 2; ++k) \
;         acc[ai][bj][m][n] = __builtin_amdgcn_mfma_f32_16x16x32_bf16(Bt[n][k], At[m][k], acc[ai][bj][m][n], 0, 0, 0); __builtin_amdgcn_s_setprio(0); } while (0)
; #define PG8_WAIT_V(n) asm volatile("s_waitcnt vmcnt(" #n ")" ::: "memory")
; #define PG8_BAR __builtin_amdgcn_s_barrier()
; template <class Epi>
; __device__ __forceinline__ void gemm_phase(LAS unsigned char* lds, const Gemm g, const Sched& S, const Epi& E) {
;     ...
;             PG8_LDB(B0, 0, 0); PG8_LDB(B1, 0, 1); PG8_SCHED; PG8_LDA(At, 0, 0); PG8_STAGE(PG8_SA(1, 1), a1 + hstepA, voffA);
;             PG8_WAIT_V(8); PG8_WAIT_L(0); PG8_BAR; PG8_MMA(0, 0, At, B0); PG8_MMA(0, 1, At, B1); PG8_BAR; PG8_SCHED;
;             PG8_LDA(At, 0, 1); PG8_STAGE(PG8_SB(0, 0), b2, voffB); PG8_STAGE(PG8_SB(0, 1), b2 + hstepB, voffB); PG8_STAGE(PG8_SA(0, 0), a2, voffA);
;             PG8_WAIT_V(8); PG8_WAIT_L(0); PG8_BAR; PG8_MMA(1, 0, At, B0); PG8_MMA(1, 1, At, B1); PG8_BAR; PG8_SCHED;
;             PG8_LDB(B0, 1, 0); PG8_LDB(B1, 1, 1); PG8_SCHED; PG8_LDA(At, 1, 0); PG8_STAGE(PG8_SA(0, 1), a2 + hstepA, voffA);
;             PG8_WAIT_V(8); PG8_WAIT_L(0); PG8_BAR; PG8_MMA(0, 0, At, B0); PG8_MMA(0, 1, At, B1); PG8_BAR; PG8_SCHED;
;             PG8_LDA(At, 1, 1); PG8_STAGE(PG8_SB(1, 0), b3, voffB); PG8_STAGE(PG8_SB(1, 1), b3 + hstepB, voffB); PG8_STAGE(PG8_SA(1, 0), a3, voffA);
;             PG8_WAIT_V(8); PG8_WAIT_L(0); PG8_BAR; PG8_MMA(1, 0, At, B0); PG8_MMA(1, 1, At, B1); PG8_BAR; PG8_SCHED;
.Lrx_p9_0_j:
	s_waitcnt lgkmcnt(0)
	s_cmp_eq_u32 s53, -2
	s_cbranch_scc1 .Lcz_p9_0
	s_barrier
	s_waitcnt lgkmcnt(0)
	v_mfma_f32_16x16x32_bf16 v[126:129], v[156:159], v[188:191], v[126:129]
	v_mfma_f32_16x16x32_bf16 v[122:125], v[164:167], v[188:191], v[122:125]
	v_mfma_f32_16x16x32_bf16 v[110:113], v[156:159], v[200:203], v[110:113]
	v_mfma_f32_16x16x32_bf16 v[106:109], v[164:167], v[200:203], v[106:109]
	v_mfma_f32_16x16x32_bf16 v[94:97], v[156:159], v[208:211], v[94:97]
	v_mfma_f32_16x16x32_bf16 v[90:93], v[164:167], v[208:211], v[90:93]
	v_mfma_f32_16x16x32_bf16 v[78:81], v[156:159], v[216:219], v[78:81]
	v_mfma_f32_16x16x32_bf16 v[74:77], v[164:167], v[216:219], v[74:77]
	v_mfma_f32_16x16x32_bf16 v[126:129], v[160:163], v[192:195], v[126:129]
	v_mfma_f32_16x16x32_bf16 v[122:125], v[168:171], v[192:195], v[122:125]
	v_mfma_f32_16x16x32_bf16 v[110:113], v[160:163], v[204:207], v[110:113]
	v_mfma_f32_16x16x32_bf16 v[106:109], v[168:171], v[204:207], v[106:109]
	v_mfma_f32_16x16x32_bf16 v[94:97], v[160:163], v[212:215], v[94:97]
	v_mfma_f32_16x16x32_bf16 v[90:93], v[168:171], v[212:215], v[90:93]
	v_mfma_f32_16x16x32_bf16 v[78:81], v[160:163], v[220:223], v[78:81]
	v_mfma_f32_16x16x32_bf16 v[74:77], v[168:171], v[220:223], v[74:77]
	v_mfma_f32_16x16x32_bf16 v[118:121], v[172:175], v[188:191], v[118:121]
	v_mfma_f32_16x16x32_bf16 v[114:117], v[180:183], v[188:191], v[114:117]
	v_mfma_f32_16x16x32_bf16 v[102:105], v[172:175], v[200:203], v[102:105]
	v_mfma_f32_16x16x32_bf16 v[98:101], v[180:183], v[200:203], v[98:101]
	v_mfma_f32_16x16x32_bf16 v[86:89], v[172:175], v[208:211], v[86:89]
	v_mfma_f32_16x16x32_bf16 v[82:85], v[180:183], v[208:211], v[82:85]
	v_mfma_f32_16x16x32_bf16 v[70:73], v[172:175], v[216:219], v[70:73]
	v_mfma_f32_16x16x32_bf16 v[66:69], v[180:183], v[216:219], v[66:69]
	v_mfma_f32_16x16x32_bf16 v[118:121], v[176:179], v[192:195], v[118:121]
	v_mfma_f32_16x16x32_bf16 v[114:117], v[184:187], v[192:195], v[114:117]
	v_mfma_f32_16x16x32_bf16 v[102:105], v[176:179], v[204:207], v[102:105]
	v_mfma_f32_16x16x32_bf16 v[98:101], v[184:187], v[204:207], v[98:101]
	v_mfma_f32_16x16x32_bf16 v[86:89], v[176:179], v[212:215], v[86:89]
	v_mfma_f32_16x16x32_bf16 v[82:85], v[184:187], v[212:215], v[82:85]
	v_mfma_f32_16x16x32_bf16 v[70:73], v[176:179], v[220:223], v[70:73]
	v_mfma_f32_16x16x32_bf16 v[66:69], v[184:187], v[220:223], v[66:69]
.Lcz_p9_0_j:
	s_barrier
	s_add_i32 s54, s36, s29
	v_lshl_add_u64 v[196:197], s[24:25], 0, v[132:133]
	s_mov_b32 m0, s54
	ds_read_b128 v[188:191], v155 offset:16384
	ds_read_b128 v[192:195], v155 offset:17408
	ds_read_b128 v[200:203], v155 offset:18432
	ds_read_b128 v[204:207], v155 offset:19456
	ds_read_b128 v[208:211], v155 offset:20480
	ds_read_b128 v[212:215], v155 offset:21504
	ds_read_b128 v[216:219], v155 offset:22528
	ds_read_b128 v[220:223], v155 offset:23552
	global_load_lds_dwordx4 v[196:197], off
	s_add_i32 m0, s54, 0x2000
	s_add_u32 s54, s24, 0x40000
	v_lshl_add_u64 v[224:225], s[24:25], 0, v[136:137]
	s_addc_u32 s55, s25, 0
	s_add_i32 s56, s37, s29
	global_load_lds_dwordx4 v[224:225], off
	v_lshl_add_u64 v[226:227], s[54:55], 0, v[132:133]
	s_mov_b32 m0, s56
	v_lshl_add_u64 v[228:229], s[26:27], 0, v[134:135]
	global_load_lds_dwordx4 v[226:227], off
	v_lshl_add_u64 v[226:227], s[54:55], 0, v[136:137]
	s_add_i32 m0, s56, 0x2000
	s_nop 0
	global_load_lds_dwordx4 v[226:227], off
	v_lshl_add_u64 v[226:227], s[26:27], 0, v[130:131]
	s_mov_b32 m0, s21
	s_nop 0
	global_load_lds_dwordx4 v[226:227], off
	s_mov_b32 m0, s30
	s_nop 0
	global_load_lds_dwordx4 v[228:229], off
	s_cmp_eq_u32 s98, 0
	s_cbranch_scc1 .Lrx_p9_1_n
	s_sub_u32 s98, s98, 1
	s_waitcnt vmcnt(16)
	s_branch .Lrx_p9_1_j

; #define PG8_STAGE(bufoff, gbase, voff) do { _Pragma("unroll") for (int _i = 0; _i < 2; ++_i) \
;         __builtin_amdgcn_global_load_lds((const unsigned*)((const char*)(gbase) + (voff)[_i]), (LAS unsigned*)(lds + (bufoff) + ldsw + _i * 8192), 16, 0, 0); } while (0)
; #define PG8_LDA(dst, b, h) do { _Pragma("unroll") for (int m = 0; m < 4; ++m) _Pragma("unroll") for (int k = 0; k < 2; ++k) dst[m][k] = *(const LAS bf16x8*)(lds + PG8_SA(b, h) + aoff + m * 2048 + k * 1024); } while (0)
; #define PG8_LDB(dst, b, h) do { _Pragma("unroll") for (int n = 0; n < 2; ++n) _Pragma("unroll") for (int k = 0; k < 2; ++k) dst[n][k] = *(const LAS bf16x8*)(lds + PG8_SB(b, h) + boff + n * 2048 + k * 1024); } while (0)
; #define PG8_MMA(ai, bj, At, Bt) do { __builtin_amdgcn_s_setprio(1); _Pragma("unroll") for (int m = 0; m < 4; ++m) _Pragma("unroll") for (int n = 0; n < 2; ++n) _Pragma("unroll") for (int k = 0; k < 2; ++k) \
;         acc[ai][bj][m][n] = __builtin_amdgcn_mfma_f32_16x16x32_bf16(Bt[n][k], At[m][k], acc[ai][bj][m][n], 0, 0, 0); __builtin_amdgcn_s_setprio(0); } while (0)
; #define PG8_WAIT_V(n) asm volatile("s_waitcnt vmcnt(" #n ")" ::: "memory")
; #define PG8_BAR __builtin_amdgcn_s_barrier()
; template <class Epi>
; __device__ __forceinline__ void gemm_phase(LAS unsigned char* lds, const Gemm g, const Sched& S, const Epi& E) {
;     ...
;             PG8_LDB(B0, 0, 0); PG8_LDB(B1, 0, 1); PG8_SCHED; PG8_LDA(At, 0, 0); PG8_STAGE(PG8_SA(1, 1), a1 + hstepA, voffA);
;             PG8_WAIT_V(8); PG8_WAIT_L(0); PG8_BAR; PG8_MMA(0, 0, At, B0); PG8_MMA(0, 1, At, B1); PG8_BAR; PG8_SCHED;
;             PG8_LDA(At, 0, 1); PG8_STAGE(PG8_SB(0, 0), b2, voffB); PG8_STAGE(PG8_SB(0, 1), b2 + hstepB, voffB); PG8_STAGE(PG8_SA(0, 0), a2, voffA);
;             PG8_WAIT_V(8); PG8_WAIT_L(0); PG8_BAR; PG8_MMA(1, 0, At, B0); PG8_MMA(1, 1, At, B1); PG8_BAR; PG8_SCHED;
;             PG8_LDB(B0, 1, 0); PG8_LDB(B1, 1, 1); PG8_SCHED; PG8_LDA(At, 1, 0); PG8_STAGE(PG8_SA(0, 1), a2 + hstepA, voffA);
;             PG8_WAIT_V(8); PG8_WAIT_L(0); PG8_BAR; PG8_MMA(0, 0, At, B0); PG8_MMA(0, 1, At, B1); PG8_BAR; PG8_SCHED;
;             PG8_LDA(At, 1, 1); PG8_STAGE(PG8_SB(1, 0), b3, voffB); PG8_STAGE(PG8_SB(1, 1), b3 + hstepB, voffB); PG8_STAGE(PG8_SA(1, 0), a3, voffA);
;             PG8_WAIT_V(8); PG8_WAIT_L(0); PG8_BAR; PG8_MMA(1, 0, At, B0); PG8_MMA(1, 1, At, B1); PG8_BAR; PG8_SCHED;
.Lrx_p9_1_j:
	s_waitcnt lgkmcnt(0)
	s_cmp_eq_u32 s53, -2
	s_cbranch_scc1 .Lcz_p9_1
	s_barrier
	s_waitcnt lgkmcnt(0)
	v_mfma_f32_16x16x32_bf16 v[62:65], v[156:159], v[188:191], v[62:65]
	v_mfma_f32_16x16x32_bf16 v[58:61], v[164:167], v[188:191], v[58:61]
	v_mfma_f32_16x16x32_bf16 v[46:49], v[156:159], v[200:203], v[46:49]
	v_mfma_f32_16x16x32_bf16 v[42:45], v[164:167], v[200:203], v[42:45]
	v_mfma_f32_16x16x32_bf16 v[30:33], v[156:159], v[208:211], v[30:33]
	v_mfma_f32_16x16x32_bf16 v[26:29], v[164:167], v[208:211], v[26:29]
	v_mfma_f32_16x16x32_bf16 v[14:17], v[156:159], v[216:219], v[14:17]
	v_mfma_f32_16x16x32_bf16 v[10:13], v[164:167], v[216:219], v[10:13]
	v_mfma_f32_16x16x32_bf16 v[62:65], v[160:163], v[192:195], v[62:65]
	v_mfma_f32_16x16x32_bf16 v[58:61], v[168:171], v[192:195], v[58:61]
	v_mfma_f32_16x16x32_bf16 v[46:49], v[160:163], v[204:207], v[46:49]
	v_mfma_f32_16x16x32_bf16 v[42:45], v[168:171], v[204:207], v[42:45]
	v_mfma_f32_16x16x32_bf16 v[30:33], v[160:163], v[212:215], v[30:33]
	v_mfma_f32_16x16x32_bf16 v[26:29], v[168:171], v[212:215], v[26:29]
	v_mfma_f32_16x16x32_bf16 v[14:17], v[160:163], v[220:223], v[14:17]
	v_mfma_f32_16x16x32_bf16 v[10:13], v[168:171], v[220:223], v[10:13]
	v_mfma_f32_16x16x32_bf16 v[54:57], v[172:175], v[188:191], v[54:57]
	v_mfma_f32_16x16x32_bf16 v[50:53], v[180:183], v[188:191], v[50:53]
	v_mfma_f32_16x16x32_bf16 v[38:41], v[172:175], v[200:203], v[38:41]
	v_mfma_f32_16x16x32_bf16 v[34:37], v[180:183], v[200:203], v[34:37]
	v_mfma_f32_16x16x32_bf16 v[22:25], v[172:175], v[208:211], v[22:25]
	v_mfma_f32_16x16x32_bf16 v[18:21], v[180:183], v[208:211], v[18:21]
	v_mfma_f32_16x16x32_bf16 v[6:9], v[172:175], v[216:219], v[6:9]
	v_mfma_f32_16x16x32_bf16 v[2:5], v[180:183], v[216:219], v[2:5]
	v_mfma_f32_16x16x32_bf16 v[54:57], v[176:179], v[192:195], v[54:57]
	v_mfma_f32_16x16x32_bf16 v[50:53], v[184:187], v[192:195], v[50:53]
	v_mfma_f32_16x16x32_bf16 v[38:41], v[176:179], v[204:207], v[38:41]
	v_mfma_f32_16x16x32_bf16 v[34:37], v[184:187], v[204:207], v[34:37]
	v_mfma_f32_16x16x32_bf16 v[22:25], v[176:179], v[212:215], v[22:25]
	v_mfma_f32_16x16x32_bf16 v[18:21], v[184:187], v[212:215], v[18:21]
	v_mfma_f32_16x16x32_bf16 v[6:9], v[176:179], v[220:223], v[6:9]
	v_mfma_f32_16x16x32_bf16 v[2:5], v[184:187], v[220:223], v[2:5]
.Lcz_p9_1_j:
	s_barrier
	s_add_i32 s54, 0, 0x18000
	s_add_i32 s55, 0, 0x1c000
	v_add_u32_e32 v168, s54, v147
	v_add_u32_e32 v184, s55, v147
	ds_read_b128 v[156:159], v168
	ds_read_b128 v[160:163], v168 offset:1024
	ds_read_b128 v[164:167], v168 offset:2048
	ds_read_b128 v[168:171], v168 offset:3072
	ds_read_b128 v[172:175], v184
	ds_read_b128 v[176:179], v184 offset:1024
	ds_read_b128 v[180:183], v184 offset:2048
	ds_read_b128 v[184:187], v184 offset:3072
	s_add_u32 s26, s26, 0x40000
	s_addc_u32 s27, s27, 0
	s_mov_b32 m0, s31
	v_lshl_add_u64 v[230:231], s[26:27], 0, v[130:131]
	ds_read_b128 v[188:191], v155 offset:32768
	ds_read_b128 v[192:195], v155 offset:33792
	ds_read_b128 v[200:203], v155 offset:34816
	ds_read_b128 v[204:207], v155 offset:35840
	ds_read_b128 v[208:211], v155 offset:36864
	ds_read_b128 v[212:215], v155 offset:37888
	ds_read_b128 v[216:219], v155 offset:38912
	ds_read_b128 v[220:223], v155 offset:39936
	global_load_lds_dwordx4 v[230:231], off
	v_lshl_add_u64 v[230:231], s[26:27], 0, v[134:135]
	s_mov_b32 m0, s33
	s_nop 0
	global_load_lds_dwordx4 v[230:231], off
	s_cmp_eq_u32 s98, 0
	s_cbranch_scc1 .Lrx_p9_2_n
	s_sub_u32 s98, s98, 1
	s_waitcnt vmcnt(10)
	s_branch .Lrx_p9_2_j

; #define PG8_STAGE(bufoff, gbase, voff) do { _Pragma("unroll") for (int _i = 0; _i < 2; ++_i) \
;         __builtin_amdgcn_global_load_lds((const unsigned*)((const char*)(gbase) + (voff)[_i]), (LAS unsigned*)(lds + (bufoff) + ldsw + _i * 8192), 16, 0, 0); } while (0)
; #define PG8_LDA(dst, b, h) do { _Pragma("unroll") for (int m = 0; m < 4; ++m) _Pragma("unroll") for (int k = 0; k < 2; ++k) dst[m][k] = *(const LAS bf16x8*)(lds + PG8_SA(b, h) + aoff + m * 2048 + k * 1024); } while (0)
; #define PG8_LDB(dst, b, h) do { _Pragma("unroll") for (int n = 0; n < 2; ++n) _Pragma("unroll") for (int k = 0; k < 2; ++k) dst[n][k] = *(const LAS bf16x8*)(lds + PG8_SB(b, h) + boff + n * 2048 + k * 1024); } while (0)
; #define PG8_MMA(ai, bj, At, Bt) do { __builtin_amdgcn_s_setprio(1); _Pragma("unroll") for (int m = 0; m < 4; ++m) _Pragma("unroll") for (int n = 0; n < 2; ++n) _Pragma("unroll") for (int k = 0; k < 2; ++k) \
;         acc[ai][bj][m][n] = __builtin_amdgcn_mfma_f32_16x16x32_bf16(Bt[n][k], At[m][k], acc[ai][bj][m][n], 0, 0, 0); __builtin_amdgcn_s_setprio(0); } while (0)
; #define PG8_WAIT_V(n) asm volatile("s_waitcnt vmcnt(" #n ")" ::: "memory")
; #define PG8_BAR __builtin_amdgcn_s_barrier()
; template <class Epi>
; __device__ __forceinline__ void gemm_phase(LAS unsigned char* lds, const Gemm g, const Sched& S, const Epi& E) {
;     ...
;             PG8_LDB(B0, 0, 0); PG8_LDB(B1, 0, 1); PG8_SCHED; PG8_LDA(At, 0, 0); PG8_STAGE(PG8_SA(1, 1), a1 + hstepA, voffA);
;             PG8_WAIT_V(8); PG8_WAIT_L(0); PG8_BAR; PG8_MMA(0, 0, At, B0); PG8_MMA(0, 1, At, B1); PG8_BAR; PG8_SCHED;
;             PG8_LDA(At, 0, 1); PG8_STAGE(PG8_SB(0, 0), b2, voffB); PG8_STAGE(PG8_SB(0, 1), b2 + hstepB, voffB); PG8_STAGE(PG8_SA(0, 0), a2, voffA);
;             PG8_WAIT_V(8); PG8_WAIT_L(0); PG8_BAR; PG8_MMA(1, 0, At, B0); PG8_MMA(1, 1, At, B1); PG8_BAR; PG8_SCHED;
;             PG8_LDB(B0, 1, 0); PG8_LDB(B1, 1, 1); PG8_SCHED; PG8_LDA(At, 1, 0); PG8_STAGE(PG8_SA(0, 1), a2 + hstepA, voffA);
;             PG8_WAIT_V(8); PG8_WAIT_L(0); PG8_BAR; PG8_MMA(0, 0, At, B0); PG8_MMA(0, 1, At, B1); PG8_BAR; PG8_SCHED;
;             PG8_LDA(At, 1, 1); PG8_STAGE(PG8_SB(1, 0), b3, voffB); PG8_STAGE(PG8_SB(1, 1), b3 + hstepB, voffB); PG8_STAGE(PG8_SA(1, 0), a3, voffA);
;             PG8_WAIT_V(8); PG8_WAIT_L(0); PG8_BAR; PG8_MMA(1, 0, At, B0); PG8_MMA(1, 1, At, B1); PG8_BAR; PG8_SCHED;
.Lrx_p9_2_j:
	s_waitcnt lgkmcnt(0)
	s_barrier
	s_waitcnt lgkmcnt(0)
	v_mfma_f32_16x16x32_bf16 v[126:129], v[156:159], v[188:191], v[126:129]
	v_mfma_f32_16x16x32_bf16 v[122:125], v[164:167], v[188:191], v[122:125]
	v_mfma_f32_16x16x32_bf16 v[110:113], v[156:159], v[200:203], v[110:113]
	v_mfma_f32_16x16x32_bf16 v[106:109], v[164:167], v[200:203], v[106:109]
	v_mfma_f32_16x16x32_bf16 v[94:97], v[156:159], v[208:211], v[94:97]
	v_mfma_f32_16x16x32_bf16 v[90:93], v[164:167], v[208:211], v[90:93]
	v_mfma_f32_16x16x32_bf16 v[78:81], v[156:159], v[216:219], v[78:81]
	v_mfma_f32_16x16x32_bf16 v[74:77], v[164:167], v[216:219], v[74:77]
	v_mfma_f32_16x16x32_bf16 v[126:129], v[160:163], v[192:195], v[126:129]
	v_mfma_f32_16x16x32_bf16 v[122:125], v[168:171], v[192:195], v[122:125]
	v_mfma_f32_16x16x32_bf16 v[110:113], v[160:163], v[204:207], v[110:113]
	v_mfma_f32_16x16x32_bf16 v[106:109], v[168:171], v[204:207], v[106:109]
	v_mfma_f32_16x16x32_bf16 v[94:97], v[160:163], v[212:215], v[94:97]
	v_mfma_f32_16x16x32_bf16 v[90:93], v[168:171], v[212:215], v[90:93]
	v_mfma_f32_16x16x32_bf16 v[78:81], v[160:163], v[220:223], v[78:81]
	v_mfma_f32_16x16x32_bf16 v[74:77], v[168:171], v[220:223], v[74:77]
	v_mfma_f32_16x16x32_bf16 v[118:121], v[172:175], v[188:191], v[118:121]
	v_mfma_f32_16x16x32_bf16 v[114:117], v[180:183], v[188:191], v[114:117]
	v_mfma_f32_16x16x32_bf16 v[102:105], v[172:175], v[200:203], v[102:105]
	v_mfma_f32_16x16x32_bf16 v[98:101], v[180:183], v[200:203], v[98:101]
	v_mfma_f32_16x16x32_bf16 v[86:89], v[172:175], v[208:211], v[86:89]
	v_mfma_f32_16x16x32_bf16 v[82:85], v[180:183], v[208:211], v[82:85]
	v_mfma_f32_16x16x32_bf16 v[70:73], v[172:175], v[216:219], v[70:73]
	v_mfma_f32_16x16x32_bf16 v[66:69], v[180:183], v[216:219], v[66:69]
	v_mfma_f32_16x16x32_bf16 v[118:121], v[176:179], v[192:195], v[118:121]
	v_mfma_f32_16x16x32_bf16 v[114:117], v[184:187], v[192:195], v[114:117]
	v_mfma_f32_16x16x32_bf16 v[102:105], v[176:179], v[204:207], v[102:105]
	v_mfma_f32_16x16x32_bf16 v[98:101], v[184:187], v[204:207], v[98:101]
	v_mfma_f32_16x16x32_bf16 v[86:89], v[176:179], v[212:215], v[86:89]
	v_mfma_f32_16x16x32_bf16 v[82:85], v[184:187], v[212:215], v[82:85]
	v_mfma_f32_16x16x32_bf16 v[70:73], v[176:179], v[220:223], v[70:73]
	v_mfma_f32_16x16x32_bf16 v[66:69], v[184:187], v[220:223], v[66:69]
	s_barrier
	s_add_i32 s26, s54, s29
	v_lshl_add_u64 v[196:197], v[196:197], 0, s[6:7]
	s_mov_b32 m0, s26
	ds_read_b128 v[188:191], v155 offset:49152
	ds_read_b128 v[192:195], v155 offset:50176
	ds_read_b128 v[200:203], v155 offset:51200
	ds_read_b128 v[204:207], v155 offset:52224
	ds_read_b128 v[208:211], v155 offset:53248
	ds_read_b128 v[212:215], v155 offset:54272
	ds_read_b128 v[216:219], v155 offset:55296
	ds_read_b128 v[220:223], v155 offset:56320
	global_load_lds_dwordx4 v[196:197], off
	s_add_i32 m0, s26, 0x2000
	s_add_u32 s24, s24, 0x40080
	v_lshl_add_u64 v[196:197], v[224:225], 0, s[6:7]
	s_addc_u32 s25, s25, 0
	s_add_i32 s26, s55, s29
	global_load_lds_dwordx4 v[196:197], off
	v_lshl_add_u64 v[196:197], s[24:25], 0, v[132:133]
	s_mov_b32 m0, s26
	s_nop 0
	global_load_lds_dwordx4 v[196:197], off
	v_lshl_add_u64 v[196:197], s[24:25], 0, v[136:137]
	s_add_i32 m0, s26, 0x2000
	s_nop 0
	global_load_lds_dwordx4 v[196:197], off
	v_lshl_add_u64 v[196:197], v[226:227], 0, s[6:7]
	s_mov_b32 m0, s34
	s_nop 0
	global_load_lds_dwordx4 v[196:197], off
	v_lshl_add_u64 v[196:197], v[228:229], 0, s[6:7]
	s_mov_b32 m0, s35
	s_nop 0
	global_load_lds_dwordx4 v[196:197], off
	s_waitcnt vmcnt(8)
	s_waitcnt lgkmcnt(0)
	s_barrier
	s_waitcnt lgkmcnt(0)
	v_mfma_f32_16x16x32_bf16 v[62:65], v[156:159], v[188:191], v[62:65]
	v_mfma_f32_16x16x32_bf16 v[58:61], v[164:167], v[188:191], v[58:61]
	v_mfma_f32_16x16x32_bf16 v[46:49], v[156:159], v[200:203], v[46:49]
	v_mfma_f32_16x16x32_bf16 v[42:45], v[164:167], v[200:203], v[42:45]
	v_mfma_f32_16x16x32_bf16 v[30:33], v[156:159], v[208:211], v[30:33]
	v_mfma_f32_16x16x32_bf16 v[26:29], v[164:167], v[208:211], v[26:29]
	v_mfma_f32_16x16x32_bf16 v[14:17], v[156:159], v[216:219], v[14:17]
	v_mfma_f32_16x16x32_bf16 v[10:13], v[164:167], v[216:219], v[10:13]
	v_mfma_f32_16x16x32_bf16 v[62:65], v[160:163], v[192:195], v[62:65]
	v_mfma_f32_16x16x32_bf16 v[58:61], v[168:171], v[192:195], v[58:61]
	v_mfma_f32_16x16x32_bf16 v[46:49], v[160:163], v[204:207], v[46:49]
	v_mfma_f32_16x16x32_bf16 v[42:45], v[168:171], v[204:207], v[42:45]
	v_mfma_f32_16x16x32_bf16 v[30:33], v[160:163], v[212:215], v[30:33]
	v_mfma_f32_16x16x32_bf16 v[26:29], v[168:171], v[212:215], v[26:29]
	v_mfma_f32_16x16x32_bf16 v[14:17], v[160:163], v[220:223], v[14:17]
	v_mfma_f32_16x16x32_bf16 v[10:13], v[168:171], v[220:223], v[10:13]
	v_mfma_f32_16x16x32_bf16 v[54:57], v[172:175], v[188:191], v[54:57]
	v_mfma_f32_16x16x32_bf16 v[50:53], v[180:183], v[188:191], v[50:53]
	v_mfma_f32_16x16x32_bf16 v[38:41], v[172:175], v[200:203], v[38:41]
	v_mfma_f32_16x16x32_bf16 v[34:37], v[180:183], v[200:203], v[34:37]
	v_mfma_f32_16x16x32_bf16 v[22:25], v[172:175], v[208:211], v[22:25]
	v_mfma_f32_16x16x32_bf16 v[18:21], v[180:183], v[208:211], v[18:21]
	v_mfma_f32_16x16x32_bf16 v[6:9], v[172:175], v[216:219], v[6:9]
	v_mfma_f32_16x16x32_bf16 v[2:5], v[180:183], v[216:219], v[2:5]
	v_mfma_f32_16x16x32_bf16 v[54:57], v[176:179], v[192:195], v[54:57]
	v_mfma_f32_16x16x32_bf16 v[50:53], v[184:187], v[192:195], v[50:53]
	v_mfma_f32_16x16x32_bf16 v[38:41], v[176:179], v[204:207], v[38:41]
	v_mfma_f32_16x16x32_bf16 v[34:37], v[184:187], v[204:207], v[34:37]
	v_mfma_f32_16x16x32_bf16 v[22:25], v[176:179], v[212:215], v[22:25]
	v_mfma_f32_16x16x32_bf16 v[18:21], v[184:187], v[212:215], v[18:21]
	v_mfma_f32_16x16x32_bf16 v[6:9], v[176:179], v[220:223], v[6:9]
	v_mfma_f32_16x16x32_bf16 v[2:5], v[184:187], v[220:223], v[2:5]
	s_barrier
	s_add_i32 s53, s53, 2
	s_add_u32 s22, s22, 0x100
	s_addc_u32 s23, s23, 0
	s_add_u32 s47, s47, 0x100
	s_addc_u32 s52, s52, 0
	s_cmp_gt_u32 s53, 13
	s_cbranch_scc0 .LBB0_1718
	s_and_b64 vcc, exec, s[8:9]
	s_cbranch_vccz .LBB0_1721
	s_barrier

; __device__ __forceinline__ unsigned xb_add(unsigned* p, unsigned v) { return __hip_atomic_fetch_add(p, v, __ATOMIC_RELAXED, __HIP_MEMORY_SCOPE_AGENT); }
; __device__ __forceinline__ void xcd_barrier(const XcdBarrier& b) {
;     asm volatile("s_waitcnt vmcnt(0)" ::: "memory");
;     __syncthreads();
;     if (threadIdx.x == 0) {
;         unsigned* bar = b.bar;
;         __builtin_amdgcn_s_waitcnt(0);
;         unsigned nloc = b.st[0], nx = b.st[1];
;         if (nloc == 0u) { xcd_barrier_complete(bar, b.x, nloc, nx); b.st[0] = nloc; b.st[1] = nx; }
;         const unsigned old = xb_add(&bar[XB_XSUB(b.x)], 1u);
;         const unsigned gen = old / nloc;
;         if (old + 1u == (gen + 1u) * nloc) {
;             __builtin_amdgcn_fence(__ATOMIC_RELEASE, "agent");
.LBB0_1725:
	s_cmp_gt_i32 s85, 10
	s_cselect_b64 s[0:1], -1, 0
	s_and_b64 s[4:5], s[12:13], s[0:1]
	s_andn2_b64 vcc, exec, s[4:5]
	s_cbranch_vccnz .LBB0_1775
	s_setprio 0
	s_waitcnt vmcnt(0) lgkmcnt(0)
	s_barrier
	v_readfirstlane_b32 s98, v0
	s_cmp_lg_u32 s98, 0
	s_cbranch_scc1 .Lxb9_end
	s_mov_b64 s[100:101], exec
	v_readlane_b32 s98, v253, 0
	s_cmp_lg_u32 s98, 0
	s_cbranch_scc1 .Lxb9_have
	s_mov_b64 exec, 0xffff
	v_mbcnt_lo_u32_b32 v254, -1, 0
	v_lshlrev_b32_e32 v254, 8, v254
	s_mov_b32 s99, 0
	v_writelane_b32 v253, s99, 3

; #define PG8_STAGE(bufoff, gbase, voff) do { _Pragma("unroll") for (int _i = 0; _i < 2; ++_i) \
;         __builtin_amdgcn_global_load_lds((const unsigned*)((const char*)(gbase) + (voff)[_i]), (LAS unsigned*)(lds + (bufoff) + ldsw + _i * 8192), 16, 0, 0); } while (0)
; #define PG8_LDA(dst, b, h) do { _Pragma("unroll") for (int m = 0; m < 4; ++m) _Pragma("unroll") for (int k = 0; k < 2; ++k) dst[m][k] = *(const LAS bf16x8*)(lds + PG8_SA(b, h) + aoff + m * 2048 + k * 1024); } while (0)
; #define PG8_LDB(dst, b, h) do { _Pragma("unroll") for (int n = 0; n < 2; ++n) _Pragma("unroll") for (int k = 0; k < 2; ++k) dst[n][k] = *(const LAS bf16x8*)(lds + PG8_SB(b, h) + boff + n * 2048 + k * 1024); } while (0)
; #define PG8_MMA(ai, bj, At, Bt) do { __builtin_amdgcn_s_setprio(1); _Pragma("unroll") for (int m = 0; m < 4; ++m) _Pragma("unroll") for (int n = 0; n < 2; ++n) _Pragma("unroll") for (int k = 0; k < 2; ++k) \
;         acc[ai][bj][m][n] = __builtin_amdgcn_mfma_f32_16x16x32_bf16(Bt[n][k], At[m][k], acc[ai][bj][m][n], 0, 0, 0); __builtin_amdgcn_s_setprio(0); } while (0)
; template <class Epi>
; __device__ __forceinline__ void gemm_phase(LAS unsigned char* lds, const Gemm g, const Sched& S, const Epi& E) {
;     ...
;         const bool has_next = S.next(ui + 1, nxt);
;         const char* nA = has_next ? (const char*)g.A + (size_t)nxt.pm * tstepA + (size_t)nxt.part * g.koff * 2 : cA; const char* nB = has_next ? (const char*)g.Bt + (size_t)nxt.pn * tstepB + (size_t)nxt.part * g.koff * 2 : cB;
;         for (int t = 0; t < nt; t += 2) {
;             const bool last = (t == nt - 2);
;             const char* a1 = cA + (size_t)(t + 1) * kstep;
;             const char* a2 = last ? nA : cA + (size_t)(t + 2) * kstep; const char* b2 = last ? nB : cB + (size_t)(t + 2) * kstep;
;             const char* a3 = a2 + kstep; const char* b3 = b2 + kstep;
;             PG8_LDB(B0, 0, 0); PG8_LDB(B1, 0, 1); PG8_SCHED; PG8_LDA(At, 0, 0); PG8_STAGE(PG8_SA(1, 1), a1 + hstepA, voffA);
;             PG8_WAIT_V(8); PG8_WAIT_L(0); PG8_BAR; PG8_MMA(0, 0, At, B0); PG8_MMA(0, 1, At, B1); PG8_BAR; PG8_SCHED;
;             PG8_LDA(At, 0, 1); PG8_STAGE(PG8_SB(0, 0), b2, voffB); PG8_STAGE(PG8_SB(0, 1), b2 + hstepB, voffB); PG8_STAGE(PG8_SA(0, 0), a2, voffA);
;             PG8_WAIT_V(8); PG8_WAIT_L(0); PG8_BAR; PG8_MMA(1, 0, At, B0); PG8_MMA(1, 1, At, B1); PG8_BAR; PG8_SCHED;
.LBB0_1799:
	s_add_u32 s8, s34, 0xb0080
	s_addc_u32 s9, s35, 0
	s_add_u32 s73, s30, 0x100
	s_addc_u32 s74, s31, 0
	s_mov_b32 s75, -2
	s_waitcnt lgkmcnt(0)
	v_readfirstlane_b32 s100, v0
	s_lshr_b32 s100, s100, 8
	s_cmp_eq_u32 s100, 0
	s_cbranch_scc0 .Lprio_6
	s_setprio 1
.Lprio_6:
.LBB0_1800:
	ds_read_b128 v[106:109], v210
	ds_read_b128 v[114:117], v210 offset:1024
	ds_read_b128 v[130:133], v210 offset:2048
	ds_read_b128 v[142:145], v210 offset:3072
	ds_read_b128 v[146:149], v211
	ds_read_b128 v[150:153], v211 offset:1024
	ds_read_b128 v[154:157], v211 offset:2048
	ds_read_b128 v[158:161], v211 offset:3072
	s_add_u32 s30, s8, 0xfff50080
	s_addc_u32 s31, s9, -1
	s_cmp_eq_u32 s75, 40
	s_cselect_b32 s35, s27, s31
	s_cselect_b32 s34, s26, s30
	s_cselect_b32 s31, s29, s74
	s_cselect_b32 s30, s28, s73
	v_lshl_add_u64 v[206:207], s[8:9], 0, v[196:197]
	s_add_i32 m0, s33, 0xc000
	ds_read_b128 v[162:165], v212
	ds_read_b128 v[166:169], v212 offset:1024
	ds_read_b128 v[170:173], v212 offset:2048
	ds_read_b128 v[174:177], v212 offset:3072
	ds_read_b128 v[178:181], v212 offset:4096
	ds_read_b128 v[182:185], v212 offset:5120
	ds_read_b128 v[214:217], v212 offset:6144
	ds_read_b128 v[218:221], v212 offset:7168
	global_load_lds_dwordx4 v[206:207], off
	v_lshl_add_u64 v[206:207], s[8:9], 0, v[200:201]
	s_add_i32 m0, s33, 0xe000
	s_nop 0
	global_load_lds_dwordx4 v[206:207], off
	s_waitcnt vmcnt(8)
	s_waitcnt lgkmcnt(0)
	s_cmp_eq_u32 s75, -2
	s_cbranch_scc1 .Lcz_p10_0
	s_barrier
	s_waitcnt lgkmcnt(0)
	v_mfma_f32_16x16x32_bf16 v[138:141], v[106:109], v[162:165], v[138:141]
	v_mfma_f32_16x16x32_bf16 v[134:137], v[130:133], v[162:165], v[134:137]
	v_mfma_f32_16x16x32_bf16 v[118:121], v[106:109], v[170:173], v[118:121]
	v_mfma_f32_16x16x32_bf16 v[110:113], v[130:133], v[170:173], v[110:113]
	v_mfma_f32_16x16x32_bf16 v[94:97], v[106:109], v[178:181], v[94:97]
	v_mfma_f32_16x16x32_bf16 v[90:93], v[130:133], v[178:181], v[90:93]
	v_mfma_f32_16x16x32_bf16 v[78:81], v[106:109], v[214:217], v[78:81]
	v_mfma_f32_16x16x32_bf16 v[74:77], v[130:133], v[214:217], v[74:77]
	v_mfma_f32_16x16x32_bf16 v[138:141], v[114:117], v[166:169], v[138:141]
	v_mfma_f32_16x16x32_bf16 v[134:137], v[142:145], v[166:169], v[134:137]
	v_mfma_f32_16x16x32_bf16 v[118:121], v[114:117], v[174:177], v[118:121]
	v_mfma_f32_16x16x32_bf16 v[110:113], v[142:145], v[174:177], v[110:113]
	v_mfma_f32_16x16x32_bf16 v[94:97], v[114:117], v[182:185], v[94:97]
	v_mfma_f32_16x16x32_bf16 v[90:93], v[142:145], v[182:185], v[90:93]
	v_mfma_f32_16x16x32_bf16 v[78:81], v[114:117], v[218:221], v[78:81]
	v_mfma_f32_16x16x32_bf16 v[74:77], v[142:145], v[218:221], v[74:77]
	v_mfma_f32_16x16x32_bf16 v[126:129], v[146:149], v[162:165], v[126:129]
	v_mfma_f32_16x16x32_bf16 v[122:125], v[154:157], v[162:165], v[122:125]
	v_mfma_f32_16x16x32_bf16 v[102:105], v[146:149], v[170:173], v[102:105]
	v_mfma_f32_16x16x32_bf16 v[98:101], v[154:157], v[170:173], v[98:101]
	v_mfma_f32_16x16x32_bf16 v[86:89], v[146:149], v[178:181], v[86:89]
	v_mfma_f32_16x16x32_bf16 v[82:85], v[154:157], v[178:181], v[82:85]
	v_mfma_f32_16x16x32_bf16 v[70:73], v[146:149], v[214:217], v[70:73]
	v_mfma_f32_16x16x32_bf16 v[66:69], v[154:157], v[214:217], v[66:69]
	v_mfma_f32_16x16x32_bf16 v[126:129], v[150:153], v[166:169], v[126:129]
	v_mfma_f32_16x16x32_bf16 v[122:125], v[158:161], v[166:169], v[122:125]
	v_mfma_f32_16x16x32_bf16 v[102:105], v[150:153], v[174:177], v[102:105]
	v_mfma_f32_16x16x32_bf16 v[98:101], v[158:161], v[174:177], v[98:101]
	v_mfma_f32_16x16x32_bf16 v[86:89], v[150:153], v[182:185], v[86:89]
	v_mfma_f32_16x16x32_bf16 v[82:85], v[158:161], v[182:185], v[82:85]
	v_mfma_f32_16x16x32_bf16 v[70:73], v[150:153], v[218:221], v[70:73]
	v_mfma_f32_16x16x32_bf16 v[66:69], v[158:161], v[218:221], v[66:69]
.Lcz_p10_0_j:
	s_barrier
	s_add_i32 s76, s53, s3
	v_lshl_add_u64 v[206:207], s[30:31], 0, v[188:189]
	s_mov_b32 m0, s76
	ds_read_b128 v[162:165], v212 offset:16384
	ds_read_b128 v[166:169], v212 offset:17408
	ds_read_b128 v[170:173], v212 offset:18432
	ds_read_b128 v[174:177], v212 offset:19456
	ds_read_b128 v[178:181], v212 offset:20480
	ds_read_b128 v[182:185], v212 offset:21504
	ds_read_b128 v[214:217], v212 offset:22528
	ds_read_b128 v[218:221], v212 offset:23552
	global_load_lds_dwordx4 v[206:207], off
	s_add_i32 m0, s76, 0x2000
	s_add_u32 s76, s30, 0xb0000
	v_lshl_add_u64 v[222:223], s[30:31], 0, v[192:193]
	s_addc_u32 s77, s31, 0
	s_add_i32 s78, s54, s3
	global_load_lds_dwordx4 v[222:223], off
	v_lshl_add_u64 v[224:225], s[76:77], 0, v[188:189]
	s_mov_b32 m0, s78
	v_lshl_add_u64 v[226:227], s[34:35], 0, v[190:191]
	global_load_lds_dwordx4 v[224:225], off
	v_lshl_add_u64 v[224:225], s[76:77], 0, v[192:193]
	s_add_i32 m0, s78, 0x2000
	s_nop 0
	global_load_lds_dwordx4 v[224:225], off
	v_lshl_add_u64 v[224:225], s[34:35], 0, v[186:187]
	s_mov_b32 m0, s33
	s_nop 0
	global_load_lds_dwordx4 v[224:225], off
	s_mov_b32 m0, s36
	s_nop 0
	global_load_lds_dwordx4 v[226:227], off
	s_waitcnt vmcnt(8)
	s_waitcnt lgkmcnt(0)
	s_cmp_eq_u32 s75, -2
	s_cbranch_scc1 .Lcz_p10_1
	s_barrier
; #define PG8_STAGE(bufoff, gbase, voff) do { _Pragma("unroll") for (int _i = 0; _i < 2; ++_i) \
;         __builtin_amdgcn_global_load_lds((const unsigned*)((const char*)(gbase) + (voff)[_i]), (LAS unsigned*)(lds + (bufoff) + ldsw + _i * 8192), 16, 0, 0); } while (0)
; #define PG8_LDA(dst, b, h) do { _Pragma("unroll") for (int m = 0; m < 4; ++m) _Pragma("unroll") for (int k = 0; k < 2; ++k) dst[m][k] = *(const LAS bf16x8*)(lds + PG8_SA(b, h) + aoff + m * 2048 + k * 1024); } while (0)
; #define PG8_LDB(dst, b, h) do { _Pragma("unroll") for (int n = 0; n < 2; ++n) _Pragma("unroll") for (int k = 0; k < 2; ++k) dst[n][k] = *(const LAS bf16x8*)(lds + PG8_SB(b, h) + boff + n * 2048 + k * 1024); } while (0)
; #define PG8_MMA(ai, bj, At, Bt) do { __builtin_amdgcn_s_setprio(1); _Pragma("unroll") for (int m = 0; m < 4; ++m) _Pragma("unroll") for (int n = 0; n < 2; ++n) _Pragma("unroll") for (int k = 0; k < 2; ++k) \
;         acc[ai][bj][m][n] = __builtin_amdgcn_mfma_f32_16x16x32_bf16(Bt[n][k], At[m][k], acc[ai][bj][m][n], 0, 0, 0); __builtin_amdgcn_s_setprio(0); } while (0)
; #define PG8_WAIT_V(n) asm volatile("s_waitcnt vmcnt(" #n ")" ::: "memory")
; #define PG8_WAIT_L(n) asm volatile("s_waitcnt lgkmcnt(" #n ")" ::: "memory")
; #define PG8_BAR __builtin_amdgcn_s_barrier()
; #define PG8_SCHED __builtin_amdgcn_sched_barrier(0)
; template <class Epi>
; __device__ __forceinline__ void gemm_phase(LAS unsigned char* lds, const Gemm g, const Sched& S, const Epi& E) {
;     ...
;             PG8_WAIT_V(8); PG8_WAIT_L(0); PG8_BAR; PG8_MMA(1, 0, At, B0); PG8_MMA(1, 1, At, B1); PG8_BAR; PG8_SCHED;
;             PG8_LDB(B0, 1, 0); PG8_LDB(B1, 1, 1); PG8_SCHED; PG8_LDA(At, 1, 0); PG8_STAGE(PG8_SA(0, 1), a2 + hstepA, voffA);
;             PG8_WAIT_V(8); PG8_WAIT_L(0); PG8_BAR; PG8_MMA(0, 0, At, B0); PG8_MMA(0, 1, At, B1); PG8_BAR; PG8_SCHED;
;             PG8_LDA(At, 1, 1); PG8_STAGE(PG8_SB(1, 0), b3, voffB); PG8_STAGE(PG8_SB(1, 1), b3 + hstepB, voffB); PG8_STAGE(PG8_SA(1, 0), a3, voffA);
;             PG8_WAIT_V(8); PG8_WAIT_L(0); PG8_BAR; PG8_MMA(1, 0, At, B0); PG8_MMA(1, 1, At, B1); PG8_BAR; PG8_SCHED;
;         }
	s_waitcnt lgkmcnt(0)
	v_mfma_f32_16x16x32_bf16 v[62:65], v[106:109], v[162:165], v[62:65]
	v_mfma_f32_16x16x32_bf16 v[58:61], v[130:133], v[162:165], v[58:61]
	v_mfma_f32_16x16x32_bf16 v[46:49], v[106:109], v[170:173], v[46:49]
	v_mfma_f32_16x16x32_bf16 v[42:45], v[130:133], v[170:173], v[42:45]
	v_mfma_f32_16x16x32_bf16 v[30:33], v[106:109], v[178:181], v[30:33]
	v_mfma_f32_16x16x32_bf16 v[26:29], v[130:133], v[178:181], v[26:29]
	v_mfma_f32_16x16x32_bf16 v[14:17], v[106:109], v[214:217], v[14:17]
	v_mfma_f32_16x16x32_bf16 v[10:13], v[130:133], v[214:217], v[10:13]
	v_mfma_f32_16x16x32_bf16 v[62:65], v[114:117], v[166:169], v[62:65]
	v_mfma_f32_16x16x32_bf16 v[58:61], v[142:145], v[166:169], v[58:61]
	v_mfma_f32_16x16x32_bf16 v[46:49], v[114:117], v[174:177], v[46:49]
	v_mfma_f32_16x16x32_bf16 v[42:45], v[142:145], v[174:177], v[42:45]
	v_mfma_f32_16x16x32_bf16 v[30:33], v[114:117], v[182:185], v[30:33]
	v_mfma_f32_16x16x32_bf16 v[26:29], v[142:145], v[182:185], v[26:29]
	v_mfma_f32_16x16x32_bf16 v[14:17], v[114:117], v[218:221], v[14:17]
	v_mfma_f32_16x16x32_bf16 v[10:13], v[142:145], v[218:221], v[10:13]
	v_mfma_f32_16x16x32_bf16 v[54:57], v[146:149], v[162:165], v[54:57]
	v_mfma_f32_16x16x32_bf16 v[50:53], v[154:157], v[162:165], v[50:53]
	v_mfma_f32_16x16x32_bf16 v[38:41], v[146:149], v[170:173], v[38:41]
	v_mfma_f32_16x16x32_bf16 v[34:37], v[154:157], v[170:173], v[34:37]
	v_mfma_f32_16x16x32_bf16 v[22:25], v[146:149], v[178:181], v[22:25]
	v_mfma_f32_16x16x32_bf16 v[18:21], v[154:157], v[178:181], v[18:21]
	v_mfma_f32_16x16x32_bf16 v[6:9], v[146:149], v[214:217], v[6:9]
	v_mfma_f32_16x16x32_bf16 v[2:5], v[154:157], v[214:217], v[2:5]
	v_mfma_f32_16x16x32_bf16 v[54:57], v[150:153], v[166:169], v[54:57]
	v_mfma_f32_16x16x32_bf16 v[50:53], v[158:161], v[166:169], v[50:53]
	v_mfma_f32_16x16x32_bf16 v[38:41], v[150:153], v[174:177], v[38:41]
	v_mfma_f32_16x16x32_bf16 v[34:37], v[158:161], v[174:177], v[34:37]
	v_mfma_f32_16x16x32_bf16 v[22:25], v[150:153], v[182:185], v[22:25]
	v_mfma_f32_16x16x32_bf16 v[18:21], v[158:161], v[182:185], v[18:21]
	v_mfma_f32_16x16x32_bf16 v[6:9], v[150:153], v[218:221], v[6:9]
	v_mfma_f32_16x16x32_bf16 v[2:5], v[158:161], v[218:221], v[2:5]
.Lcz_p10_1_j:
	s_barrier
	s_add_i32 s76, 0, 0x18000
	s_add_i32 s77, 0, 0x1c000
	v_add_u32_e32 v142, s76, v209
	v_add_u32_e32 v158, s77, v209
	ds_read_b128 v[106:109], v142
	ds_read_b128 v[114:117], v142 offset:1024
	ds_read_b128 v[130:133], v142 offset:2048
	ds_read_b128 v[142:145], v142 offset:3072
	ds_read_b128 v[146:149], v158
	ds_read_b128 v[150:153], v158 offset:1024
	ds_read_b128 v[154:157], v158 offset:2048
	ds_read_b128 v[158:161], v158 offset:3072
	s_add_u32 s34, s34, 0xb0000
	s_addc_u32 s35, s35, 0
	s_mov_b32 m0, s37
	v_lshl_add_u64 v[228:229], s[34:35], 0, v[186:187]
	ds_read_b128 v[162:165], v212 offset:32768
	ds_read_b128 v[166:169], v212 offset:33792
	ds_read_b128 v[170:173], v212 offset:34816
	ds_read_b128 v[174:177], v212 offset:35840
	ds_read_b128 v[178:181], v212 offset:36864
	ds_read_b128 v[182:185], v212 offset:37888
	ds_read_b128 v[214:217], v212 offset:38912
	ds_read_b128 v[218:221], v212 offset:39936
	global_load_lds_dwordx4 v[228:229], off
	v_lshl_add_u64 v[228:229], s[34:35], 0, v[190:191]
	s_mov_b32 m0, s38
	s_nop 0
	global_load_lds_dwordx4 v[228:229], off
	s_waitcnt vmcnt(8)
	s_waitcnt lgkmcnt(0)
	s_barrier
	s_waitcnt lgkmcnt(0)
	v_mfma_f32_16x16x32_bf16 v[138:141], v[106:109], v[162:165], v[138:141]
	v_mfma_f32_16x16x32_bf16 v[134:137], v[130:133], v[162:165], v[134:137]
	v_mfma_f32_16x16x32_bf16 v[118:121], v[106:109], v[170:173], v[118:121]
	v_mfma_f32_16x16x32_bf16 v[110:113], v[130:133], v[170:173], v[110:113]
	v_mfma_f32_16x16x32_bf16 v[94:97], v[106:109], v[178:181], v[94:97]
	v_mfma_f32_16x16x32_bf16 v[90:93], v[130:133], v[178:181], v[90:93]
	v_mfma_f32_16x16x32_bf16 v[78:81], v[106:109], v[214:217], v[78:81]
	v_mfma_f32_16x16x32_bf16 v[74:77], v[130:133], v[214:217], v[74:77]
	v_mfma_f32_16x16x32_bf16 v[138:141], v[114:117], v[166:169], v[138:141]
	v_mfma_f32_16x16x32_bf16 v[134:137], v[142:145], v[166:169], v[134:137]
	v_mfma_f32_16x16x32_bf16 v[118:121], v[114:117], v[174:177], v[118:121]
	v_mfma_f32_16x16x32_bf16 v[110:113], v[142:145], v[174:177], v[110:113]
	v_mfma_f32_16x16x32_bf16 v[94:97], v[114:117], v[182:185], v[94:97]
	v_mfma_f32_16x16x32_bf16 v[90:93], v[142:145], v[182:185], v[90:93]
	v_mfma_f32_16x16x32_bf16 v[78:81], v[114:117], v[218:221], v[78:81]
	v_mfma_f32_16x16x32_bf16 v[74:77], v[142:145], v[218:221], v[74:77]
	v_mfma_f32_16x16x32_bf16 v[126:129], v[146:149], v[162:165], v[126:129]
	v_mfma_f32_16x16x32_bf16 v[122:125], v[154:157], v[162:165], v[122:125]
	v_mfma_f32_16x16x32_bf16 v[102:105], v[146:149], v[170:173], v[102:105]
	v_mfma_f32_16x16x32_bf16 v[98:101], v[154:157], v[170:173], v[98:101]
	v_mfma_f32_16x16x32_bf16 v[86:89], v[146:149], v[178:181], v[86:89]
	v_mfma_f32_16x16x32_bf16 v[82:85], v[154:157], v[178:181], v[82:85]
	v_mfma_f32_16x16x32_bf16 v[70:73], v[146:149], v[214:217], v[70:73]
	v_mfma_f32_16x16x32_bf16 v[66:69], v[154:157], v[214:217], v[66:69]
	v_mfma_f32_16x16x32_bf16 v[126:129], v[150:153], v[166:169], v[126:129]
	v_mfma_f32_16x16x32_bf16 v[122:125], v[158:161], v[166:169], v[122:125]
	v_mfma_f32_16x16x32_bf16 v[102:105], v[150:153], v[174:177], v[102:105]
	v_mfma_f32_16x16x32_bf16 v[98:101], v[158:161], v[174:177], v[98:101]
	v_mfma_f32_16x16x32_bf16 v[86:89], v[150:153], v[182:185], v[86:89]
	v_mfma_f32_16x16x32_bf16 v[82:85], v[158:161], v[182:185], v[82:85]
	v_mfma_f32_16x16x32_bf16 v[70:73], v[150:153], v[218:221], v[70:73]
	v_mfma_f32_16x16x32_bf16 v[66:69], v[158:161], v[218:221], v[66:69]
	s_barrier
; #define PG8_STAGE(bufoff, gbase, voff) do { _Pragma("unroll") for (int _i = 0; _i < 2; ++_i) \
;         __builtin_amdgcn_global_load_lds((const unsigned*)((const char*)(gbase) + (voff)[_i]), (LAS unsigned*)(lds + (bufoff) + ldsw + _i * 8192), 16, 0, 0); } while (0)
; #define PG8_LDA(dst, b, h) do { _Pragma("unroll") for (int m = 0; m < 4; ++m) _Pragma("unroll") for (int k = 0; k < 2; ++k) dst[m][k] = *(const LAS bf16x8*)(lds + PG8_SA(b, h) + aoff + m * 2048 + k * 1024); } while (0)
; #define PG8_MMA(ai, bj, At, Bt) do { __builtin_amdgcn_s_setprio(1); _Pragma("unroll") for (int m = 0; m < 4; ++m) _Pragma("unroll") for (int n = 0; n < 2; ++n) _Pragma("unroll") for (int k = 0; k < 2; ++k) \
;         acc[ai][bj][m][n] = __builtin_amdgcn_mfma_f32_16x16x32_bf16(Bt[n][k], At[m][k], acc[ai][bj][m][n], 0, 0, 0); __builtin_amdgcn_s_setprio(0); } while (0)
; #define PG8_WAIT_V(n) asm volatile("s_waitcnt vmcnt(" #n ")" ::: "memory")
; #define PG8_WAIT_L(n) asm volatile("s_waitcnt lgkmcnt(" #n ")" ::: "memory")
; #define PG8_BAR __builtin_amdgcn_s_barrier()
; #define PG8_SCHED __builtin_amdgcn_sched_barrier(0)
; template <class Epi>
; __device__ __forceinline__ void gemm_phase(LAS unsigned char* lds, const Gemm g, const Sched& S, const Epi& E) {
;     ...
;             PG8_LDA(At, 1, 1); PG8_STAGE(PG8_SB(1, 0), b3, voffB); PG8_STAGE(PG8_SB(1, 1), b3 + hstepB, voffB); PG8_STAGE(PG8_SA(1, 0), a3, voffA);
;             PG8_WAIT_V(8); PG8_WAIT_L(0); PG8_BAR; PG8_MMA(1, 0, At, B0); PG8_MMA(1, 1, At, B1); PG8_BAR; PG8_SCHED;
;         }
	s_add_i32 s34, s76, s3
	v_lshl_add_u64 v[206:207], v[206:207], 0, s[22:23]
	s_mov_b32 m0, s34
	ds_read_b128 v[162:165], v212 offset:49152
	ds_read_b128 v[166:169], v212 offset:50176
	ds_read_b128 v[170:173], v212 offset:51200
	ds_read_b128 v[174:177], v212 offset:52224
	ds_read_b128 v[178:181], v212 offset:53248
	ds_read_b128 v[182:185], v212 offset:54272
	ds_read_b128 v[214:217], v212 offset:55296
	ds_read_b128 v[218:221], v212 offset:56320
	global_load_lds_dwordx4 v[206:207], off
	s_add_i32 m0, s34, 0x2000
	s_add_u32 s30, s30, 0xb0080
	v_lshl_add_u64 v[206:207], v[222:223], 0, s[22:23]
	s_addc_u32 s31, s31, 0
	s_add_i32 s34, s77, s3
	global_load_lds_dwordx4 v[206:207], off
	v_lshl_add_u64 v[206:207], s[30:31], 0, v[188:189]
	s_mov_b32 m0, s34
	s_nop 0
	global_load_lds_dwordx4 v[206:207], off
	v_lshl_add_u64 v[206:207], s[30:31], 0, v[192:193]
	s_add_i32 m0, s34, 0x2000
	s_nop 0
	global_load_lds_dwordx4 v[206:207], off
	v_lshl_add_u64 v[206:207], v[224:225], 0, s[22:23]
	s_mov_b32 m0, s43
	s_nop 0
	global_load_lds_dwordx4 v[206:207], off
	v_lshl_add_u64 v[206:207], v[226:227], 0, s[22:23]
	s_mov_b32 m0, s44
	s_nop 0
	global_load_lds_dwordx4 v[206:207], off
	s_waitcnt vmcnt(8)
	s_waitcnt lgkmcnt(0)
	s_barrier
	s_waitcnt lgkmcnt(0)
	v_mfma_f32_16x16x32_bf16 v[62:65], v[106:109], v[162:165], v[62:65]
	v_mfma_f32_16x16x32_bf16 v[58:61], v[130:133], v[162:165], v[58:61]
	v_mfma_f32_16x16x32_bf16 v[46:49], v[106:109], v[170:173], v[46:49]
	v_mfma_f32_16x16x32_bf16 v[42:45], v[130:133], v[170:173], v[42:45]
	v_mfma_f32_16x16x32_bf16 v[30:33], v[106:109], v[178:181], v[30:33]
	v_mfma_f32_16x16x32_bf16 v[26:29], v[130:133], v[178:181], v[26:29]
	v_mfma_f32_16x16x32_bf16 v[14:17], v[106:109], v[214:217], v[14:17]
	v_mfma_f32_16x16x32_bf16 v[10:13], v[130:133], v[214:217], v[10:13]
	v_mfma_f32_16x16x32_bf16 v[62:65], v[114:117], v[166:169], v[62:65]
	v_mfma_f32_16x16x32_bf16 v[58:61], v[142:145], v[166:169], v[58:61]
	v_mfma_f32_16x16x32_bf16 v[46:49], v[114:117], v[174:177], v[46:49]
	v_mfma_f32_16x16x32_bf16 v[42:45], v[142:145], v[174:177], v[42:45]
	v_mfma_f32_16x16x32_bf16 v[30:33], v[114:117], v[182:185], v[30:33]
	v_mfma_f32_16x16x32_bf16 v[26:29], v[142:145], v[182:185], v[26:29]
	v_mfma_f32_16x16x32_bf16 v[14:17], v[114:117], v[218:221], v[14:17]
	v_mfma_f32_16x16x32_bf16 v[10:13], v[142:145], v[218:221], v[10:13]
	v_mfma_f32_16x16x32_bf16 v[54:57], v[146:149], v[162:165], v[54:57]
	v_mfma_f32_16x16x32_bf16 v[50:53], v[154:157], v[162:165], v[50:53]
	v_mfma_f32_16x16x32_bf16 v[38:41], v[146:149], v[170:173], v[38:41]
	v_mfma_f32_16x16x32_bf16 v[34:37], v[154:157], v[170:173], v[34:37]
	v_mfma_f32_16x16x32_bf16 v[22:25], v[146:149], v[178:181], v[22:25]
	v_mfma_f32_16x16x32_bf16 v[18:21], v[154:157], v[178:181], v[18:21]
	v_mfma_f32_16x16x32_bf16 v[6:9], v[146:149], v[214:217], v[6:9]
	v_mfma_f32_16x16x32_bf16 v[2:5], v[154:157], v[214:217], v[2:5]
	v_mfma_f32_16x16x32_bf16 v[54:57], v[150:153], v[166:169], v[54:57]
	v_mfma_f32_16x16x32_bf16 v[50:53], v[158:161], v[166:169], v[50:53]
	v_mfma_f32_16x16x32_bf16 v[38:41], v[150:153], v[174:177], v[38:41]
	v_mfma_f32_16x16x32_bf16 v[34:37], v[158:161], v[174:177], v[34:37]
	v_mfma_f32_16x16x32_bf16 v[22:25], v[150:153], v[182:185], v[22:25]
	v_mfma_f32_16x16x32_bf16 v[18:21], v[158:161], v[182:185], v[18:21]
	v_mfma_f32_16x16x32_bf16 v[6:9], v[150:153], v[218:221], v[6:9]
	v_mfma_f32_16x16x32_bf16 v[2:5], v[158:161], v[218:221], v[2:5]
	s_barrier
	s_add_i32 s75, s75, 2
	s_add_u32 s8, s8, 0x100
	s_addc_u32 s9, s9, 0
	s_add_u32 s73, s73, 0x100
	s_addc_u32 s74, s74, 0
	s_cmp_gt_u32 s75, 41
	s_cbranch_scc0 .LBB0_1800
	s_and_b64 vcc, exec, s[24:25]
	s_cbranch_vccz .LBB0_1803
	s_barrier

; #define PG8_STAGE(bufoff, gbase, voff) do { _Pragma("unroll") for (int _i = 0; _i < 2; ++_i) \
;         __builtin_amdgcn_global_load_lds((const unsigned*)((const char*)(gbase) + (voff)[_i]), (LAS unsigned*)(lds + (bufoff) + ldsw + _i * 8192), 16, 0, 0); } while (0)
; #define PG8_LDA(dst, b, h) do { _Pragma("unroll") for (int m = 0; m < 4; ++m) _Pragma("unroll") for (int k = 0; k < 2; ++k) dst[m][k] = *(const LAS bf16x8*)(lds + PG8_SA(b, h) + aoff + m * 2048 + k * 1024); } while (0)
; #define PG8_LDB(dst, b, h) do { _Pragma("unroll") for (int n = 0; n < 2; ++n) _Pragma("unroll") for (int k = 0; k < 2; ++k) dst[n][k] = *(const LAS bf16x8*)(lds + PG8_SB(b, h) + boff + n * 2048 + k * 1024); } while (0)
; #define PG8_MMA(ai, bj, At, Bt) do { __builtin_amdgcn_s_setprio(1); _Pragma("unroll") for (int m = 0; m < 4; ++m) _Pragma("unroll") for (int n = 0; n < 2; ++n) _Pragma("unroll") for (int k = 0; k < 2; ++k) \
;         acc[ai][bj][m][n] = __builtin_amdgcn_mfma_f32_16x16x32_bf16(Bt[n][k], At[m][k], acc[ai][bj][m][n], 0, 0, 0); __builtin_amdgcn_s_setprio(0); } while (0)
; #define PG8_WAIT_V(n) asm volatile("s_waitcnt vmcnt(" #n ")" ::: "memory")
; #define PG8_WAIT_L(n) asm volatile("s_waitcnt lgkmcnt(" #n ")" ::: "memory")
; #define PG8_BAR __builtin_amdgcn_s_barrier()
; #define PG8_SCHED __builtin_amdgcn_sched_barrier(0)
; template <class Epi>
; __device__ __forceinline__ void gemm_phase(LAS unsigned char* lds, const Gemm g, const Sched& S, const Epi& E) {
;     ...
;             PG8_LDB(B0, 0, 0); PG8_LDB(B1, 0, 1); PG8_SCHED; PG8_LDA(At, 0, 0); PG8_STAGE(PG8_SA(1, 1), a1 + hstepA, voffA);
;             PG8_WAIT_V(8); PG8_WAIT_L(0); PG8_BAR; PG8_MMA(0, 0, At, B0); PG8_MMA(0, 1, At, B1); PG8_BAR; PG8_SCHED;
;             PG8_LDA(At, 0, 1); PG8_STAGE(PG8_SB(0, 0), b2, voffB); PG8_STAGE(PG8_SB(0, 1), b2 + hstepB, voffB); PG8_STAGE(PG8_SA(0, 0), a2, voffA);
;             PG8_WAIT_V(8); PG8_WAIT_L(0); PG8_BAR; PG8_MMA(1, 0, At, B0); PG8_MMA(1, 1, At, B1); PG8_BAR; PG8_SCHED;
.Lcz_p10_0:
	s_barrier
	s_waitcnt lgkmcnt(0)
	v_mfma_f32_16x16x32_bf16 v[138:141], v[106:109], v[162:165], 0
	v_mfma_f32_16x16x32_bf16 v[134:137], v[130:133], v[162:165], 0
	v_mfma_f32_16x16x32_bf16 v[118:121], v[106:109], v[170:173], 0
	v_mfma_f32_16x16x32_bf16 v[110:113], v[130:133], v[170:173], 0
	v_mfma_f32_16x16x32_bf16 v[94:97], v[106:109], v[178:181], 0
	v_mfma_f32_16x16x32_bf16 v[90:93], v[130:133], v[178:181], 0
	v_mfma_f32_16x16x32_bf16 v[78:81], v[106:109], v[214:217], 0
	v_mfma_f32_16x16x32_bf16 v[74:77], v[130:133], v[214:217], 0
	v_mfma_f32_16x16x32_bf16 v[138:141], v[114:117], v[166:169], v[138:141]
	v_mfma_f32_16x16x32_bf16 v[134:137], v[142:145], v[166:169], v[134:137]
	v_mfma_f32_16x16x32_bf16 v[118:121], v[114:117], v[174:177], v[118:121]
	v_mfma_f32_16x16x32_bf16 v[110:113], v[142:145], v[174:177], v[110:113]
	v_mfma_f32_16x16x32_bf16 v[94:97], v[114:117], v[182:185], v[94:97]
	v_mfma_f32_16x16x32_bf16 v[90:93], v[142:145], v[182:185], v[90:93]
	v_mfma_f32_16x16x32_bf16 v[78:81], v[114:117], v[218:221], v[78:81]
	v_mfma_f32_16x16x32_bf16 v[74:77], v[142:145], v[218:221], v[74:77]
	v_mfma_f32_16x16x32_bf16 v[126:129], v[146:149], v[162:165], 0
	v_mfma_f32_16x16x32_bf16 v[122:125], v[154:157], v[162:165], 0
	v_mfma_f32_16x16x32_bf16 v[102:105], v[146:149], v[170:173], 0
	v_mfma_f32_16x16x32_bf16 v[98:101], v[154:157], v[170:173], 0
	v_mfma_f32_16x16x32_bf16 v[86:89], v[146:149], v[178:181], 0
	v_mfma_f32_16x16x32_bf16 v[82:85], v[154:157], v[178:181], 0
	v_mfma_f32_16x16x32_bf16 v[70:73], v[146:149], v[214:217], 0
	v_mfma_f32_16x16x32_bf16 v[66:69], v[154:157], v[214:217], 0
	v_mfma_f32_16x16x32_bf16 v[126:129], v[150:153], v[166:169], v[126:129]
	v_mfma_f32_16x16x32_bf16 v[122:125], v[158:161], v[166:169], v[122:125]
	v_mfma_f32_16x16x32_bf16 v[102:105], v[150:153], v[174:177], v[102:105]
	v_mfma_f32_16x16x32_bf16 v[98:101], v[158:161], v[174:177], v[98:101]
	v_mfma_f32_16x16x32_bf16 v[86:89], v[150:153], v[182:185], v[86:89]
	v_mfma_f32_16x16x32_bf16 v[82:85], v[158:161], v[182:185], v[82:85]
	v_mfma_f32_16x16x32_bf16 v[70:73], v[150:153], v[218:221], v[70:73]
	v_mfma_f32_16x16x32_bf16 v[66:69], v[158:161], v[218:221], v[66:69]
	s_branch .Lcz_p10_0_j
.Lcz_p10_1:
	s_barrier
	s_waitcnt lgkmcnt(0)
	v_mfma_f32_16x16x32_bf16 v[62:65], v[106:109], v[162:165], 0
	v_mfma_f32_16x16x32_bf16 v[58:61], v[130:133], v[162:165], 0
	v_mfma_f32_16x16x32_bf16 v[46:49], v[106:109], v[170:173], 0
	v_mfma_f32_16x16x32_bf16 v[42:45], v[130:133], v[170:173], 0
	v_mfma_f32_16x16x32_bf16 v[30:33], v[106:109], v[178:181], 0
	v_mfma_f32_16x16x32_bf16 v[26:29], v[130:133], v[178:181], 0
	v_mfma_f32_16x16x32_bf16 v[14:17], v[106:109], v[214:217], 0
	v_mfma_f32_16x16x32_bf16 v[10:13], v[130:133], v[214:217], 0
	v_mfma_f32_16x16x32_bf16 v[62:65], v[114:117], v[166:169], v[62:65]
	v_mfma_f32_16x16x32_bf16 v[58:61], v[142:145], v[166:169], v[58:61]
	v_mfma_f32_16x16x32_bf16 v[46:49], v[114:117], v[174:177], v[46:49]
	v_mfma_f32_16x16x32_bf16 v[42:45], v[142:145], v[174:177], v[42:45]
	v_mfma_f32_16x16x32_bf16 v[30:33], v[114:117], v[182:185], v[30:33]
	v_mfma_f32_16x16x32_bf16 v[26:29], v[142:145], v[182:185], v[26:29]
	v_mfma_f32_16x16x32_bf16 v[14:17], v[114:117], v[218:221], v[14:17]
	v_mfma_f32_16x16x32_bf16 v[10:13], v[142:145], v[218:221], v[10:13]
	v_mfma_f32_16x16x32_bf16 v[54:57], v[146:149], v[162:165], 0
	v_mfma_f32_16x16x32_bf16 v[50:53], v[154:157], v[162:165], 0
	v_mfma_f32_16x16x32_bf16 v[38:41], v[146:149], v[170:173], 0
	v_mfma_f32_16x16x32_bf16 v[34:37], v[154:157], v[170:173], 0
	v_mfma_f32_16x16x32_bf16 v[22:25], v[146:149], v[178:181], 0
	v_mfma_f32_16x16x32_bf16 v[18:21], v[154:157], v[178:181], 0
	v_mfma_f32_16x16x32_bf16 v[6:9], v[146:149], v[214:217], 0
	v_mfma_f32_16x16x32_bf16 v[2:5], v[154:157], v[214:217], 0
	v_mfma_f32_16x16x32_bf16 v[54:57], v[150:153], v[166:169], v[54:57]
	v_mfma_f32_16x16x32_bf16 v[50:53], v[158:161], v[166:169], v[50:53]
	v_mfma_f32_16x16x32_bf16 v[38:41], v[150:153], v[174:177], v[38:41]
	v_mfma_f32_16x16x32_bf16 v[34:37], v[158:161], v[174:177], v[34:37]
	v_mfma_f32_16x16x32_bf16 v[22:25], v[150:153], v[182:185], v[22:25]
	v_mfma_f32_16x16x32_bf16 v[18:21], v[158:161], v[182:185], v[18:21]
	v_mfma_f32_16x16x32_bf16 v[6:9], v[150:153], v[218:221], v[6:9]
	v_mfma_f32_16x16x32_bf16 v[2:5], v[158:161], v[218:221], v[2:5]
	s_branch .Lcz_p10_1_j

; #define PG8_STAGE(bufoff, gbase, voff) do { _Pragma("unroll") for (int _i = 0; _i < 2; ++_i) \
;         __builtin_amdgcn_global_load_lds((const unsigned*)((const char*)(gbase) + (voff)[_i]), (LAS unsigned*)(lds + (bufoff) + ldsw + _i * 8192), 16, 0, 0); } while (0)
; #define PG8_LDA(dst, b, h) do { _Pragma("unroll") for (int m = 0; m < 4; ++m) _Pragma("unroll") for (int k = 0; k < 2; ++k) dst[m][k] = *(const LAS bf16x8*)(lds + PG8_SA(b, h) + aoff + m * 2048 + k * 1024); } while (0)
; #define PG8_LDB(dst, b, h) do { _Pragma("unroll") for (int n = 0; n < 2; ++n) _Pragma("unroll") for (int k = 0; k < 2; ++k) dst[n][k] = *(const LAS bf16x8*)(lds + PG8_SB(b, h) + boff + n * 2048 + k * 1024); } while (0)
; #define PG8_MMA(ai, bj, At, Bt) do { __builtin_amdgcn_s_setprio(1); _Pragma("unroll") for (int m = 0; m < 4; ++m) _Pragma("unroll") for (int n = 0; n < 2; ++n) _Pragma("unroll") for (int k = 0; k < 2; ++k) \
;         acc[ai][bj][m][n] = __builtin_amdgcn_mfma_f32_16x16x32_bf16(Bt[n][k], At[m][k], acc[ai][bj][m][n], 0, 0, 0); __builtin_amdgcn_s_setprio(0); } while (0)
; template <class Epi>
; __device__ __forceinline__ void gemm_phase(LAS unsigned char* lds, const Gemm g, const Sched& S, const Epi& E) {
;     ...
;         const bool has_next = S.next(ui + 1, nxt);
;         const char* nA = has_next ? (const char*)g.A + (size_t)nxt.pm * tstepA + (size_t)nxt.part * g.koff * 2 : cA; const char* nB = has_next ? (const char*)g.Bt + (size_t)nxt.pn * tstepB + (size_t)nxt.part * g.koff * 2 : cB;
;         for (int t = 0; t < nt; t += 2) {
;             const bool last = (t == nt - 2);
;             const char* a1 = cA + (size_t)(t + 1) * kstep;
;             const char* a2 = last ? nA : cA + (size_t)(t + 2) * kstep; const char* b2 = last ? nB : cB + (size_t)(t + 2) * kstep;
;             const char* a3 = a2 + kstep; const char* b3 = b2 + kstep;
;             PG8_LDB(B0, 0, 0); PG8_LDB(B1, 0, 1); PG8_SCHED; PG8_LDA(At, 0, 0); PG8_STAGE(PG8_SA(1, 1), a1 + hstepA, voffA);
;             PG8_WAIT_V(8); PG8_WAIT_L(0); PG8_BAR; PG8_MMA(0, 0, At, B0); PG8_MMA(0, 1, At, B1); PG8_BAR; PG8_SCHED;
;             PG8_LDA(At, 0, 1); PG8_STAGE(PG8_SB(0, 0), b2, voffB); PG8_STAGE(PG8_SB(0, 1), b2 + hstepB, voffB); PG8_STAGE(PG8_SA(0, 0), a2, voffA);
;             PG8_WAIT_V(8); PG8_WAIT_L(0); PG8_BAR; PG8_MMA(1, 0, At, B0); PG8_MMA(1, 1, At, B1); PG8_BAR; PG8_SCHED;
.LBB0_1884:
	s_add_u32 s27, s34, 0x100
	s_addc_u32 s56, s35, 0
	v_lshl_add_u64 v[150:151], s[30:31], 0, v[142:143]
	v_lshl_add_u64 v[152:153], s[30:31], 0, v[144:145]
	s_mov_b32 s57, -2
	s_mov_b64 s[34:35], 0
	v_readfirstlane_b32 s100, v0
	s_lshr_b32 s100, s100, 8
	s_cmp_eq_u32 s100, 0
	s_cbranch_scc0 .Lprio_7
	s_setprio 1
.Lprio_7:
.LBB0_1885:
	v_add_u32_e32 v164, s47, v133
	ds_read_b128 v[156:159], v164
	ds_read_b128 v[160:163], v164 offset:1024
	ds_read_b128 v[168:171], v164 offset:2048
	ds_read_b128 v[172:175], v164 offset:3072
	v_add_u32_e32 v164, s52, v133
	s_add_u32 s36, s30, s34
	ds_read_b128 v[176:179], v164
	ds_read_b128 v[180:183], v164 offset:1024
	ds_read_b128 v[184:187], v164 offset:2048
	ds_read_b128 v[188:191], v164 offset:3072
	s_addc_u32 s37, s31, s35
	s_add_u32 s36, s36, 0x100
	s_addc_u32 s37, s37, 0
	s_add_u32 s58, s27, s34
	s_addc_u32 s59, s56, s35
	s_cmpk_eq_i32 s34, 0x1500
	s_cselect_b32 s39, s9, s37
	s_cselect_b32 s38, s8, s36
	s_cselect_b32 s37, s29, s59
	s_cselect_b32 s36, s28, s58
	v_lshl_add_u64 v[164:165], v[150:151], 0, s[34:35]
	s_add_i32 m0, s33, 0xc000
	ds_read_b128 v[192:195], v155
	ds_read_b128 v[200:203], v155 offset:1024
	ds_read_b128 v[204:207], v155 offset:2048
	ds_read_b128 v[208:211], v155 offset:3072
	ds_read_b128 v[212:215], v155 offset:4096
	ds_read_b128 v[216:219], v155 offset:5120
	ds_read_b128 v[220:223], v155 offset:6144
	ds_read_b128 v[224:227], v155 offset:7168
	global_load_lds_dwordx4 v[164:165], off
	v_lshl_add_u64 v[164:165], v[152:153], 0, s[34:35]
	s_add_i32 m0, s33, 0xe000
	s_nop 0
	global_load_lds_dwordx4 v[164:165], off
	s_waitcnt vmcnt(8)
	s_waitcnt lgkmcnt(0)
	s_barrier
	s_waitcnt lgkmcnt(0)
	v_mfma_f32_16x16x32_bf16 v[126:129], v[156:159], v[192:195], v[126:129]
	v_mfma_f32_16x16x32_bf16 v[122:125], v[168:171], v[192:195], v[122:125]
	v_mfma_f32_16x16x32_bf16 v[110:113], v[156:159], v[204:207], v[110:113]
	v_mfma_f32_16x16x32_bf16 v[106:109], v[168:171], v[204:207], v[106:109]
	v_mfma_f32_16x16x32_bf16 v[94:97], v[156:159], v[212:215], v[94:97]
	v_mfma_f32_16x16x32_bf16 v[90:93], v[168:171], v[212:215], v[90:93]
	v_mfma_f32_16x16x32_bf16 v[78:81], v[156:159], v[220:223], v[78:81]
	v_mfma_f32_16x16x32_bf16 v[74:77], v[168:171], v[220:223], v[74:77]
	v_mfma_f32_16x16x32_bf16 v[126:129], v[160:163], v[200:203], v[126:129]
	v_mfma_f32_16x16x32_bf16 v[122:125], v[172:175], v[200:203], v[122:125]
	v_mfma_f32_16x16x32_bf16 v[110:113], v[160:163], v[208:211], v[110:113]
	v_mfma_f32_16x16x32_bf16 v[106:109], v[172:175], v[208:211], v[106:109]
	v_mfma_f32_16x16x32_bf16 v[94:97], v[160:163], v[216:219], v[94:97]
	v_mfma_f32_16x16x32_bf16 v[90:93], v[172:175], v[216:219], v[90:93]
	v_mfma_f32_16x16x32_bf16 v[78:81], v[160:163], v[224:227], v[78:81]
	v_mfma_f32_16x16x32_bf16 v[74:77], v[172:175], v[224:227], v[74:77]
	v_mfma_f32_16x16x32_bf16 v[118:121], v[176:179], v[192:195], v[118:121]
	v_mfma_f32_16x16x32_bf16 v[114:117], v[184:187], v[192:195], v[114:117]
	v_mfma_f32_16x16x32_bf16 v[102:105], v[176:179], v[204:207], v[102:105]
	v_mfma_f32_16x16x32_bf16 v[98:101], v[184:187], v[204:207], v[98:101]
	v_mfma_f32_16x16x32_bf16 v[86:89], v[176:179], v[212:215], v[86:89]
	v_mfma_f32_16x16x32_bf16 v[82:85], v[184:187], v[212:215], v[82:85]
	v_mfma_f32_16x16x32_bf16 v[70:73], v[176:179], v[220:223], v[70:73]
	v_mfma_f32_16x16x32_bf16 v[66:69], v[184:187], v[220:223], v[66:69]
	v_mfma_f32_16x16x32_bf16 v[118:121], v[180:183], v[200:203], v[118:121]
	v_mfma_f32_16x16x32_bf16 v[114:117], v[188:191], v[200:203], v[114:117]
	v_mfma_f32_16x16x32_bf16 v[102:105], v[180:183], v[208:211], v[102:105]
	v_mfma_f32_16x16x32_bf16 v[98:101], v[188:191], v[208:211], v[98:101]
	v_mfma_f32_16x16x32_bf16 v[86:89], v[180:183], v[216:219], v[86:89]
	v_mfma_f32_16x16x32_bf16 v[82:85], v[188:191], v[216:219], v[82:85]
	v_mfma_f32_16x16x32_bf16 v[70:73], v[180:183], v[224:227], v[70:73]
	v_mfma_f32_16x16x32_bf16 v[66:69], v[188:191], v[224:227], v[66:69]
	s_barrier
	s_add_i32 s58, s47, s13
	v_lshl_add_u64 v[164:165], s[36:37], 0, v[136:137]
	s_mov_b32 m0, s58
	ds_read_b128 v[192:195], v155 offset:16384
	ds_read_b128 v[200:203], v155 offset:17408
	ds_read_b128 v[204:207], v155 offset:18432
	ds_read_b128 v[208:211], v155 offset:19456
	ds_read_b128 v[212:215], v155 offset:20480
	ds_read_b128 v[216:219], v155 offset:21504
	ds_read_b128 v[220:223], v155 offset:22528
	ds_read_b128 v[224:227], v155 offset:23552
	global_load_lds_dwordx4 v[164:165], off
	s_add_i32 m0, s58, 0x2000
	s_add_u32 s58, s36, 0xb0000
	v_lshl_add_u64 v[196:197], s[36:37], 0, v[140:141]
	s_addc_u32 s59, s37, 0
	s_add_i32 s60, s52, s13
	global_load_lds_dwordx4 v[196:197], off
	v_lshl_add_u64 v[228:229], s[58:59], 0, v[136:137]
	s_mov_b32 m0, s60
	v_lshl_add_u64 v[230:231], s[38:39], 0, v[138:139]
	global_load_lds_dwordx4 v[228:229], off
	v_lshl_add_u64 v[228:229], s[58:59], 0, v[140:141]
	s_add_i32 m0, s60, 0x2000
	s_nop 0
	global_load_lds_dwordx4 v[228:229], off
	v_lshl_add_u64 v[228:229], s[38:39], 0, v[134:135]
	s_mov_b32 m0, s33
	s_nop 0
	global_load_lds_dwordx4 v[228:229], off
	s_mov_b32 m0, s42
	s_nop 0
	global_load_lds_dwordx4 v[230:231], off
	s_waitcnt vmcnt(8)
	s_waitcnt lgkmcnt(0)
	s_barrier
; #define PG8_STAGE(bufoff, gbase, voff) do { _Pragma("unroll") for (int _i = 0; _i < 2; ++_i) \
;         __builtin_amdgcn_global_load_lds((const unsigned*)((const char*)(gbase) + (voff)[_i]), (LAS unsigned*)(lds + (bufoff) + ldsw + _i * 8192), 16, 0, 0); } while (0)
; #define PG8_LDA(dst, b, h) do { _Pragma("unroll") for (int m = 0; m < 4; ++m) _Pragma("unroll") for (int k = 0; k < 2; ++k) dst[m][k] = *(const LAS bf16x8*)(lds + PG8_SA(b, h) + aoff + m * 2048 + k * 1024); } while (0)
; #define PG8_LDB(dst, b, h) do { _Pragma("unroll") for (int n = 0; n < 2; ++n) _Pragma("unroll") for (int k = 0; k < 2; ++k) dst[n][k] = *(const LAS bf16x8*)(lds + PG8_SB(b, h) + boff + n * 2048 + k * 1024); } while (0)
; #define PG8_MMA(ai, bj, At, Bt) do { __builtin_amdgcn_s_setprio(1); _Pragma("unroll") for (int m = 0; m < 4; ++m) _Pragma("unroll") for (int n = 0; n < 2; ++n) _Pragma("unroll") for (int k = 0; k < 2; ++k) \
;         acc[ai][bj][m][n] = __builtin_amdgcn_mfma_f32_16x16x32_bf16(Bt[n][k], At[m][k], acc[ai][bj][m][n], 0, 0, 0); __builtin_amdgcn_s_setprio(0); } while (0)
; #define PG8_WAIT_V(n) asm volatile("s_waitcnt vmcnt(" #n ")" ::: "memory")
; #define PG8_WAIT_L(n) asm volatile("s_waitcnt lgkmcnt(" #n ")" ::: "memory")
; #define PG8_BAR __builtin_amdgcn_s_barrier()
; #define PG8_SCHED __builtin_amdgcn_sched_barrier(0)
; template <class Epi>
; __device__ __forceinline__ void gemm_phase(LAS unsigned char* lds, const Gemm g, const Sched& S, const Epi& E) {
;     ...
;             PG8_WAIT_V(8); PG8_WAIT_L(0); PG8_BAR; PG8_MMA(1, 0, At, B0); PG8_MMA(1, 1, At, B1); PG8_BAR; PG8_SCHED;
;             PG8_LDB(B0, 1, 0); PG8_LDB(B1, 1, 1); PG8_SCHED; PG8_LDA(At, 1, 0); PG8_STAGE(PG8_SA(0, 1), a2 + hstepA, voffA);
;             PG8_WAIT_V(8); PG8_WAIT_L(0); PG8_BAR; PG8_MMA(0, 0, At, B0); PG8_MMA(0, 1, At, B1); PG8_BAR; PG8_SCHED;
;             PG8_LDA(At, 1, 1); PG8_STAGE(PG8_SB(1, 0), b3, voffB); PG8_STAGE(PG8_SB(1, 1), b3 + hstepB, voffB); PG8_STAGE(PG8_SA(1, 0), a3, voffA);
;             PG8_WAIT_V(8); PG8_WAIT_L(0); PG8_BAR; PG8_MMA(1, 0, At, B0); PG8_MMA(1, 1, At, B1); PG8_BAR; PG8_SCHED;
	s_waitcnt lgkmcnt(0)
	v_mfma_f32_16x16x32_bf16 v[62:65], v[156:159], v[192:195], v[62:65]
	v_mfma_f32_16x16x32_bf16 v[58:61], v[168:171], v[192:195], v[58:61]
	v_mfma_f32_16x16x32_bf16 v[46:49], v[156:159], v[204:207], v[46:49]
	v_mfma_f32_16x16x32_bf16 v[42:45], v[168:171], v[204:207], v[42:45]
	v_mfma_f32_16x16x32_bf16 v[30:33], v[156:159], v[212:215], v[30:33]
	v_mfma_f32_16x16x32_bf16 v[26:29], v[168:171], v[212:215], v[26:29]
	v_mfma_f32_16x16x32_bf16 v[14:17], v[156:159], v[220:223], v[14:17]
	v_mfma_f32_16x16x32_bf16 v[10:13], v[168:171], v[220:223], v[10:13]
	v_mfma_f32_16x16x32_bf16 v[62:65], v[160:163], v[200:203], v[62:65]
	v_mfma_f32_16x16x32_bf16 v[58:61], v[172:175], v[200:203], v[58:61]
	v_mfma_f32_16x16x32_bf16 v[46:49], v[160:163], v[208:211], v[46:49]
	v_mfma_f32_16x16x32_bf16 v[42:45], v[172:175], v[208:211], v[42:45]
	v_mfma_f32_16x16x32_bf16 v[30:33], v[160:163], v[216:219], v[30:33]
	v_mfma_f32_16x16x32_bf16 v[26:29], v[172:175], v[216:219], v[26:29]
	v_mfma_f32_16x16x32_bf16 v[14:17], v[160:163], v[224:227], v[14:17]
	v_mfma_f32_16x16x32_bf16 v[10:13], v[172:175], v[224:227], v[10:13]
	v_mfma_f32_16x16x32_bf16 v[54:57], v[176:179], v[192:195], v[54:57]
	v_mfma_f32_16x16x32_bf16 v[50:53], v[184:187], v[192:195], v[50:53]
	v_mfma_f32_16x16x32_bf16 v[38:41], v[176:179], v[204:207], v[38:41]
	v_mfma_f32_16x16x32_bf16 v[34:37], v[184:187], v[204:207], v[34:37]
	v_mfma_f32_16x16x32_bf16 v[22:25], v[176:179], v[212:215], v[22:25]
	v_mfma_f32_16x16x32_bf16 v[18:21], v[184:187], v[212:215], v[18:21]
	v_mfma_f32_16x16x32_bf16 v[6:9], v[176:179], v[220:223], v[6:9]
	v_mfma_f32_16x16x32_bf16 v[2:5], v[184:187], v[220:223], v[2:5]
	v_mfma_f32_16x16x32_bf16 v[54:57], v[180:183], v[200:203], v[54:57]
	v_mfma_f32_16x16x32_bf16 v[50:53], v[188:191], v[200:203], v[50:53]
	v_mfma_f32_16x16x32_bf16 v[38:41], v[180:183], v[208:211], v[38:41]
	v_mfma_f32_16x16x32_bf16 v[34:37], v[188:191], v[208:211], v[34:37]
	v_mfma_f32_16x16x32_bf16 v[22:25], v[180:183], v[216:219], v[22:25]
	v_mfma_f32_16x16x32_bf16 v[18:21], v[188:191], v[216:219], v[18:21]
	v_mfma_f32_16x16x32_bf16 v[6:9], v[180:183], v[224:227], v[6:9]
	v_mfma_f32_16x16x32_bf16 v[2:5], v[188:191], v[224:227], v[2:5]
	s_barrier
	s_add_i32 s58, 0, 0x18000
	s_add_i32 s59, 0, 0x1c000
	v_add_u32_e32 v172, s58, v133
	v_add_u32_e32 v188, s59, v133
	ds_read_b128 v[156:159], v172
	ds_read_b128 v[160:163], v172 offset:1024
	ds_read_b128 v[168:171], v172 offset:2048
	ds_read_b128 v[172:175], v172 offset:3072
	ds_read_b128 v[176:179], v188
	ds_read_b128 v[180:183], v188 offset:1024
	ds_read_b128 v[184:187], v188 offset:2048
	ds_read_b128 v[188:191], v188 offset:3072
	s_add_u32 s38, s38, 0xb0000
	s_addc_u32 s39, s39, 0
	s_mov_b32 m0, s43
	v_lshl_add_u64 v[232:233], s[38:39], 0, v[134:135]
	ds_read_b128 v[192:195], v155 offset:32768
	ds_read_b128 v[200:203], v155 offset:33792
	ds_read_b128 v[204:207], v155 offset:34816
	ds_read_b128 v[208:211], v155 offset:35840
	ds_read_b128 v[212:215], v155 offset:36864
	ds_read_b128 v[216:219], v155 offset:37888
	ds_read_b128 v[220:223], v155 offset:38912
	ds_read_b128 v[224:227], v155 offset:39936
	global_load_lds_dwordx4 v[232:233], off
	v_lshl_add_u64 v[232:233], s[38:39], 0, v[138:139]
	s_mov_b32 m0, s44
	s_nop 0
	global_load_lds_dwordx4 v[232:233], off
	s_waitcnt vmcnt(8)
	s_waitcnt lgkmcnt(0)
	s_barrier
	s_waitcnt lgkmcnt(0)
	v_mfma_f32_16x16x32_bf16 v[126:129], v[156:159], v[192:195], v[126:129]
	v_mfma_f32_16x16x32_bf16 v[122:125], v[168:171], v[192:195], v[122:125]
	v_mfma_f32_16x16x32_bf16 v[110:113], v[156:159], v[204:207], v[110:113]
	v_mfma_f32_16x16x32_bf16 v[106:109], v[168:171], v[204:207], v[106:109]
	v_mfma_f32_16x16x32_bf16 v[94:97], v[156:159], v[212:215], v[94:97]
	v_mfma_f32_16x16x32_bf16 v[90:93], v[168:171], v[212:215], v[90:93]
	v_mfma_f32_16x16x32_bf16 v[78:81], v[156:159], v[220:223], v[78:81]
	v_mfma_f32_16x16x32_bf16 v[74:77], v[168:171], v[220:223], v[74:77]
	v_mfma_f32_16x16x32_bf16 v[126:129], v[160:163], v[200:203], v[126:129]
	v_mfma_f32_16x16x32_bf16 v[122:125], v[172:175], v[200:203], v[122:125]
	v_mfma_f32_16x16x32_bf16 v[110:113], v[160:163], v[208:211], v[110:113]
	v_mfma_f32_16x16x32_bf16 v[106:109], v[172:175], v[208:211], v[106:109]
	v_mfma_f32_16x16x32_bf16 v[94:97], v[160:163], v[216:219], v[94:97]
	v_mfma_f32_16x16x32_bf16 v[90:93], v[172:175], v[216:219], v[90:93]
	v_mfma_f32_16x16x32_bf16 v[78:81], v[160:163], v[224:227], v[78:81]
	v_mfma_f32_16x16x32_bf16 v[74:77], v[172:175], v[224:227], v[74:77]
	v_mfma_f32_16x16x32_bf16 v[118:121], v[176:179], v[192:195], v[118:121]
	v_mfma_f32_16x16x32_bf16 v[114:117], v[184:187], v[192:195], v[114:117]
	v_mfma_f32_16x16x32_bf16 v[102:105], v[176:179], v[204:207], v[102:105]
	v_mfma_f32_16x16x32_bf16 v[98:101], v[184:187], v[204:207], v[98:101]
	v_mfma_f32_16x16x32_bf16 v[86:89], v[176:179], v[212:215], v[86:89]
	v_mfma_f32_16x16x32_bf16 v[82:85], v[184:187], v[212:215], v[82:85]
	v_mfma_f32_16x16x32_bf16 v[70:73], v[176:179], v[220:223], v[70:73]
	v_mfma_f32_16x16x32_bf16 v[66:69], v[184:187], v[220:223], v[66:69]
	v_mfma_f32_16x16x32_bf16 v[118:121], v[180:183], v[200:203], v[118:121]
	v_mfma_f32_16x16x32_bf16 v[114:117], v[188:191], v[200:203], v[114:117]
	v_mfma_f32_16x16x32_bf16 v[102:105], v[180:183], v[208:211], v[102:105]
	v_mfma_f32_16x16x32_bf16 v[98:101], v[188:191], v[208:211], v[98:101]
	v_mfma_f32_16x16x32_bf16 v[86:89], v[180:183], v[216:219], v[86:89]
	v_mfma_f32_16x16x32_bf16 v[82:85], v[188:191], v[216:219], v[82:85]
	v_mfma_f32_16x16x32_bf16 v[70:73], v[180:183], v[224:227], v[70:73]
	v_mfma_f32_16x16x32_bf16 v[66:69], v[188:191], v[224:227], v[66:69]
	s_barrier
; #define PG8_STAGE(bufoff, gbase, voff) do { _Pragma("unroll") for (int _i = 0; _i < 2; ++_i) \
;         __builtin_amdgcn_global_load_lds((const unsigned*)((const char*)(gbase) + (voff)[_i]), (LAS unsigned*)(lds + (bufoff) + ldsw + _i * 8192), 16, 0, 0); } while (0)
; #define PG8_LDA(dst, b, h) do { _Pragma("unroll") for (int m = 0; m < 4; ++m) _Pragma("unroll") for (int k = 0; k < 2; ++k) dst[m][k] = *(const LAS bf16x8*)(lds + PG8_SA(b, h) + aoff + m * 2048 + k * 1024); } while (0)
; #define PG8_MMA(ai, bj, At, Bt) do { __builtin_amdgcn_s_setprio(1); _Pragma("unroll") for (int m = 0; m < 4; ++m) _Pragma("unroll") for (int n = 0; n < 2; ++n) _Pragma("unroll") for (int k = 0; k < 2; ++k) \
;         acc[ai][bj][m][n] = __builtin_amdgcn_mfma_f32_16x16x32_bf16(Bt[n][k], At[m][k], acc[ai][bj][m][n], 0, 0, 0); __builtin_amdgcn_s_setprio(0); } while (0)
; #define PG8_WAIT_V(n) asm volatile("s_waitcnt vmcnt(" #n ")" ::: "memory")
; #define PG8_WAIT_L(n) asm volatile("s_waitcnt lgkmcnt(" #n ")" ::: "memory")
; #define PG8_BAR __builtin_amdgcn_s_barrier()
; #define PG8_SCHED __builtin_amdgcn_sched_barrier(0)
; template <class Epi>
; __device__ __forceinline__ void gemm_phase(LAS unsigned char* lds, const Gemm g, const Sched& S, const Epi& E) {
;     ...
;             PG8_LDA(At, 1, 1); PG8_STAGE(PG8_SB(1, 0), b3, voffB); PG8_STAGE(PG8_SB(1, 1), b3 + hstepB, voffB); PG8_STAGE(PG8_SA(1, 0), a3, voffA);
;             PG8_WAIT_V(8); PG8_WAIT_L(0); PG8_BAR; PG8_MMA(1, 0, At, B0); PG8_MMA(1, 1, At, B1); PG8_BAR; PG8_SCHED;
;         }
	s_add_i32 s38, s58, s13
	v_lshl_add_u64 v[164:165], v[164:165], 0, s[22:23]
	s_mov_b32 m0, s38
	ds_read_b128 v[192:195], v155 offset:49152
	ds_read_b128 v[200:203], v155 offset:50176
	ds_read_b128 v[204:207], v155 offset:51200
	ds_read_b128 v[208:211], v155 offset:52224
	ds_read_b128 v[212:215], v155 offset:53248
	ds_read_b128 v[216:219], v155 offset:54272
	ds_read_b128 v[220:223], v155 offset:55296
	ds_read_b128 v[224:227], v155 offset:56320
	global_load_lds_dwordx4 v[164:165], off
	s_add_i32 m0, s38, 0x2000
	s_add_u32 s36, s36, 0xb0080
	v_lshl_add_u64 v[164:165], v[196:197], 0, s[22:23]
	s_addc_u32 s37, s37, 0
	s_add_i32 s38, s59, s13
	global_load_lds_dwordx4 v[164:165], off
	v_lshl_add_u64 v[164:165], s[36:37], 0, v[136:137]
	s_mov_b32 m0, s38
	s_nop 0
	global_load_lds_dwordx4 v[164:165], off
	v_lshl_add_u64 v[164:165], s[36:37], 0, v[140:141]
	s_add_i32 m0, s38, 0x2000
	s_nop 0
	global_load_lds_dwordx4 v[164:165], off
	v_lshl_add_u64 v[164:165], v[228:229], 0, s[22:23]
	s_mov_b32 m0, s45
	s_nop 0
	global_load_lds_dwordx4 v[164:165], off
	v_lshl_add_u64 v[164:165], v[230:231], 0, s[22:23]
	s_mov_b32 m0, s46
	s_nop 0
	global_load_lds_dwordx4 v[164:165], off
	s_waitcnt vmcnt(8)
	s_waitcnt lgkmcnt(0)
	s_barrier
	s_waitcnt lgkmcnt(0)
	v_mfma_f32_16x16x32_bf16 v[62:65], v[156:159], v[192:195], v[62:65]
	v_mfma_f32_16x16x32_bf16 v[58:61], v[168:171], v[192:195], v[58:61]
	v_mfma_f32_16x16x32_bf16 v[46:49], v[156:159], v[204:207], v[46:49]
	v_mfma_f32_16x16x32_bf16 v[42:45], v[168:171], v[204:207], v[42:45]
	v_mfma_f32_16x16x32_bf16 v[30:33], v[156:159], v[212:215], v[30:33]
	v_mfma_f32_16x16x32_bf16 v[26:29], v[168:171], v[212:215], v[26:29]
	v_mfma_f32_16x16x32_bf16 v[14:17], v[156:159], v[220:223], v[14:17]
	v_mfma_f32_16x16x32_bf16 v[10:13], v[168:171], v[220:223], v[10:13]
	v_mfma_f32_16x16x32_bf16 v[62:65], v[160:163], v[200:203], v[62:65]
	v_mfma_f32_16x16x32_bf16 v[58:61], v[172:175], v[200:203], v[58:61]
	v_mfma_f32_16x16x32_bf16 v[46:49], v[160:163], v[208:211], v[46:49]
	v_mfma_f32_16x16x32_bf16 v[42:45], v[172:175], v[208:211], v[42:45]
	v_mfma_f32_16x16x32_bf16 v[30:33], v[160:163], v[216:219], v[30:33]
	v_mfma_f32_16x16x32_bf16 v[26:29], v[172:175], v[216:219], v[26:29]
	v_mfma_f32_16x16x32_bf16 v[14:17], v[160:163], v[224:227], v[14:17]
	v_mfma_f32_16x16x32_bf16 v[10:13], v[172:175], v[224:227], v[10:13]
	v_mfma_f32_16x16x32_bf16 v[54:57], v[176:179], v[192:195], v[54:57]
	v_mfma_f32_16x16x32_bf16 v[50:53], v[184:187], v[192:195], v[50:53]
	v_mfma_f32_16x16x32_bf16 v[38:41], v[176:179], v[204:207], v[38:41]
	v_mfma_f32_16x16x32_bf16 v[34:37], v[184:187], v[204:207], v[34:37]
	v_mfma_f32_16x16x32_bf16 v[22:25], v[176:179], v[212:215], v[22:25]
	v_mfma_f32_16x16x32_bf16 v[18:21], v[184:187], v[212:215], v[18:21]
	v_mfma_f32_16x16x32_bf16 v[6:9], v[176:179], v[220:223], v[6:9]
	v_mfma_f32_16x16x32_bf16 v[2:5], v[184:187], v[220:223], v[2:5]
	v_mfma_f32_16x16x32_bf16 v[54:57], v[180:183], v[200:203], v[54:57]
	v_mfma_f32_16x16x32_bf16 v[50:53], v[188:191], v[200:203], v[50:53]
	v_mfma_f32_16x16x32_bf16 v[38:41], v[180:183], v[208:211], v[38:41]
	v_mfma_f32_16x16x32_bf16 v[34:37], v[188:191], v[208:211], v[34:37]
	v_mfma_f32_16x16x32_bf16 v[22:25], v[180:183], v[216:219], v[22:25]
	v_mfma_f32_16x16x32_bf16 v[18:21], v[188:191], v[216:219], v[18:21]
	v_mfma_f32_16x16x32_bf16 v[6:9], v[180:183], v[224:227], v[6:9]
	v_mfma_f32_16x16x32_bf16 v[2:5], v[188:191], v[224:227], v[2:5]
	s_barrier
	s_add_i32 s57, s57, 2
	s_add_u32 s34, s34, 0x100
	s_addc_u32 s35, s35, 0
	s_cmp_gt_u32 s57, 41
	s_cbranch_scc0 .LBB0_1885
	s_and_b64 vcc, exec, s[24:25]
	s_cbranch_vccz .LBB0_1888
	s_barrier
